# sample-group SSD step hand-written (wave per head, no LDS or barriers, DPP row butterfly, packed f32, half-head state always in flight): 102 -> 69 us; the freed sample-path workgroups transpose 7168 w
# speedup vs baseline: 1.0185x; 1.0094x over previous
; #define LAS __attribute__((address_space(3)))
; __device__ __forceinline__ int ltid() { int t = threadIdx.x; asm volatile("" : "+v"(t)); return t; }
; __device__ __forceinline__ KArgs ka_get() { KArgs p = (KArgs)__builtin_amdgcn_kernarg_segment_ptr(); asm volatile("" : "+s"(p)); return p; }
; __device__ __forceinline__ int win_dest_row(int n0) {
;     if (n0 < 5120) return n0;
;     if (n0 < 5152) return CDT + (n0 - 5120);
;     if (n0 < 7200) { const int c = n0 - 5152; return CCF + 256 * (c >> 7) + (c & 127); }
;     { const int c = n0 - 7200; return CCF + 256 * (c >> 7) + 128 + (c & 127); }
; }
; __global__ void __launch_bounds__(512, 2) mk_fwd(Args args) {
;     ...
;     if (IN(0)) { const KArgs KA = ka_get(); const int tid = ltid(), lane = tid & 63, wave = __builtin_amdgcn_readfirstlane(tid >> 6); (void)lane; (void)wave;
;         LAS float* scr = (LAS float*)(lds + wave * 16384);
;         const int gw = bx * 8 + wave, NGW = G * 8;
;         constexpr int I_IN = (DM / 64) * (9248 / 32), I_OUT = (DMIX / 64) * (DM / 32), I_UP = (DM / 64) * (FF2 / 32), I_DN = (FF / 64) * (DM / 32);
;         constexpr int n_items0 = I_IN + I_OUT + I_UP + I_DN;
;         for (int it = gw; it < n_items0; it += NGW) {
;             int r = it;
;             if (r < I_IN) { const int nblk = 9248 / 32, kb = r / nblk, nb = r % nblk; p0_transpose_item(w_in, DM, 9248, WinT, 64 * kb, 32 * nb, win_dest_row(32 * nb), scr, lane); continue; } r -= I_IN;
.LBB0_18:
	s_cmp_lt_i32 s88, 1
	s_cselect_b64 s[0:1], -1, 0
	s_cmp_gt_i32 s89, 0
	s_cselect_b64 s[4:5], -1, 0
	s_and_b64 s[0:1], s[0:1], s[4:5]
	s_andn2_b64 vcc, exec, s[0:1]
	s_cbranch_vccnz .LBB0_61
	s_mov_b64 s[8:9], s[96:97]
	v_mov_b32_e32 v1, v212
	s_lshl_b32 s10, s94, 3
	v_readfirstlane_b32 s3, v1
	s_ashr_i32 s4, s3, 6
	s_lshl_b32 s3, s2, 3
	v_and_b32_e32 v3, 63, v1
	s_add_i32 s3, s4, s3
	s_cmpk_gt_i32 s3, 0x282f
	v_lshlrev_b32_e32 v0, 3, v3
	s_cbranch_scc1 .LBB0_54
	s_load_dwordx2 s[12:13], s[8:9], 0x38
	s_load_dwordx2 s[14:15], s[8:9], 0x90
	s_load_dwordx2 s[16:17], s[8:9], 0xa0
	s_load_dwordx2 s[18:19], s[8:9], 0xb8
	s_load_dwordx2 s[20:21], s[8:9], 0x98
	s_load_dwordx2 s[22:23], s[8:9], 0xd0
	v_lshrrev_b32_e32 v4, 3, v3
	v_and_b32_e32 v7, 7, v3
	v_lshlrev_b32_e32 v5, 4, v7
	v_lshlrev_b32_e32 v6, 5, v7
	s_lshl_b32 s24, s4, 14
	v_lshl_add_u32 v16, v4, 7, s24
	v_xor_b32_e32 v8, 0, v7
	v_lshl_add_u32 v8, v8, 4, v16
	v_xor_b32_e32 v9, 1, v7
	v_lshl_add_u32 v9, v9, 4, v16
	v_xor_b32_e32 v10, 2, v7
	v_lshl_add_u32 v10, v10, 4, v16
	v_xor_b32_e32 v11, 3, v7
	v_lshl_add_u32 v11, v11, 4, v16
	v_xor_b32_e32 v12, 4, v7
	v_lshl_add_u32 v12, v12, 4, v16
	v_xor_b32_e32 v13, 5, v7
	v_lshl_add_u32 v13, v13, 4, v16
	v_xor_b32_e32 v14, 6, v7
	v_lshl_add_u32 v14, v14, 4, v16
	v_xor_b32_e32 v15, 7, v7
	v_lshl_add_u32 v15, v15, 4, v16
	v_lshlrev_b32_e32 v20, 2, v7
	v_lshl_add_u32 v21, v7, 10, s24
	v_add_u32_e32 v16, 0, v4
	v_xor_b32_e32 v16, v16, v20
	v_lshl_add_u32 v16, v16, 2, v21
	v_add_u32_e32 v17, 8, v4
	v_xor_b32_e32 v17, v17, v20
	v_lshl_add_u32 v17, v17, 2, v21
	v_add_u32_e32 v18, 16, v4
	v_xor_b32_e32 v18, v18, v20
	v_lshl_add_u32 v18, v18, 2, v21
	v_add_u32_e32 v19, 24, v4
	v_xor_b32_e32 v19, v19, v20
	v_lshl_add_u32 v19, v19, 2, v21
	s_mov_b32 s11, s3
	s_waitcnt lgkmcnt(0)
	s_cmpk_lt_u32 s11, 9248
	s_cbranch_scc0 .Lp0t_pro_notin
	s_mul_hi_u32 s40, s11, 14861479
	s_mul_i32 s42, s40, 289
	s_sub_u32 s41, s11, s42
	s_mul_i32 s42, s40, 2367488
	s_lshl_b32 s43, s41, 7
	s_add_u32 s42, s42, s43
	s_add_u32 s26, s12, s42
	s_addc_u32 s27, s13, 0
	s_mov_b32 s28, 36992
	s_lshl_b32 s45, s41, 5
	s_mov_b32 s46, s45
	s_cmpk_lt_u32 s45, 5120
	s_cbranch_scc1 .Lp0t_pro_drow_done
	s_movk_i32 s46, 9216
	s_cmpk_lt_u32 s45, 5152
	s_cbranch_scc1 .Lp0t_pro_drow_done
	s_sub_u32 s47, s45, 5152
	s_movk_i32 s43, 5120
	s_cmpk_lt_u32 s45, 7200
	s_cbranch_scc1 .Lp0t_pro_drow_cf
	s_sub_u32 s47, s45, 7200
	s_movk_i32 s43, 5248

; __global__ void __launch_bounds__(512, 2) mk_fwd(Args args) {
;     ...
;         for (int it = gw; it < n_items0; it += NGW) {
;             int r = it;
;             if (r < I_IN) { const int nblk = 9248 / 32, kb = r / nblk, nb = r % nblk; p0_transpose_item(w_in, DM, 9248, WinT, 64 * kb, 32 * nb, win_dest_row(32 * nb), scr, lane); continue; } r -= I_IN;
.Lp0t_loop:
	s_cmpk_lt_u32 s11, 10288
	s_cbranch_scc0 .Lp0t_last
	s_cmpk_lt_u32 s11, 9248
	s_cbranch_scc0 .Lp0t_main_notin
	s_mul_hi_u32 s40, s11, 14861479
	s_mul_i32 s42, s40, 289
	s_sub_u32 s41, s11, s42
	s_mul_i32 s42, s40, 2367488
	s_lshl_b32 s43, s41, 7
	s_add_u32 s42, s42, s43
	s_add_u32 s26, s12, s42
	s_addc_u32 s27, s13, 0
	s_mov_b32 s28, 36992
	s_lshl_b32 s45, s41, 5
	s_mov_b32 s46, s45
	s_cmpk_lt_u32 s45, 5120
	s_cbranch_scc1 .Lp0t_main_drow_done
	s_movk_i32 s46, 9216
	s_cmpk_lt_u32 s45, 5152
	s_cbranch_scc1 .Lp0t_main_drow_done
	s_sub_u32 s47, s45, 5152
	s_movk_i32 s43, 5120
	s_cmpk_lt_u32 s45, 7200
	s_cbranch_scc1 .Lp0t_main_drow_cf
	s_sub_u32 s47, s45, 7200
	s_movk_i32 s43, 5248

; __device__ __forceinline__ void rms_row_to_bf16(const float* xrow, const float* w, bf16_t* orow, int lane) {
;     ...
;     for (int j = 0; j < 8; ++j) { v[j] = *(const f32x4*)(xrow + (j * 64 + lane) * 4); ww[j] = *(const f32x4*)(w + (j * 64 + lane) * 4); }
; __global__ void __launch_bounds__(512, 2) mk_fwd(Args args) {
;     ...
;         const int gr = (gw + NGW - (n_items0 % NGW)) % NGW;
;         for (int m = gr; m < MT; m += NGW) { const float* xr = (m < MP) ? x_prompt + (size_t)m * DM : x_sample + (size_t)(m - MP) * DM; rms_row_to_bf16(xr, norm_mix_w, XN + (size_t)m * DM, lane); }
.LBB0_54:
	s_abs_i32 s4, s10
	v_cvt_f32_u32_e32 v1, s4
	s_sub_i32 s5, 0, s4
	s_add_i32 s3, s3, s10
	v_rcp_iflag_f32_e32 v1, v1
	s_nop 0
	v_mul_f32_e32 v1, 0x4f7ffffe, v1
	v_cvt_u32_f32_e32 v1, v1
	s_nop 0
	v_readfirstlane_b32 s6, v1
	s_mul_i32 s5, s5, s6
	s_mul_hi_u32 s5, s6, s5
	s_add_i32 s6, s6, s5
	s_mul_hi_u32 s5, s6, 0x2830
	s_mul_i32 s5, s5, s4
	s_sub_i32 s5, 0x2830, s5
	s_sub_i32 s7, s5, s4
	s_cmp_ge_u32 s5, s4
	s_cselect_b32 s5, s7, s5
	s_sub_i32 s7, s5, s4
	s_cmp_ge_u32 s5, s4
	s_cselect_b32 s5, s7, s5
	s_sub_i32 s3, s3, s5
	s_ashr_i32 s5, s3, 31
	s_abs_i32 s3, s3
	s_mul_hi_u32 s6, s3, s6
	s_mul_i32 s6, s6, s4
	s_sub_i32 s3, s3, s6
	s_sub_i32 s6, s3, s4
	s_cmp_ge_u32 s3, s4
	s_cselect_b32 s3, s6, s3
	s_sub_i32 s6, s3, s4
	s_cmp_ge_u32 s3, s4
	s_cselect_b32 s3, s6, s3
	s_xor_b32 s3, s3, s5
	s_sub_i32 s4, s3, s5
	s_cmpk_gt_i32 s4, 0x21ff
	s_mov_b32 s7, 0
	s_cbranch_scc1 .LBB0_61
	s_load_dwordx2 s[12:13], s[8:9], 0x0
	s_load_dwordx2 s[14:15], s[8:9], 0x8
	s_load_dwordx2 s[16:17], s[8:9], 0x30
	s_load_dwordx2 s[18:19], s[8:9], 0xd0
	v_lshlrev_b32_e32 v4, 4, v3
	v_lshlrev_b32_e32 v5, 3, v3
	v_xor_b32_e32 v6, 1, v3
	v_lshlrev_b32_e32 v6, 2, v6
	v_xor_b32_e32 v7, 2, v3
	v_lshlrev_b32_e32 v7, 2, v7
	v_xor_b32_e32 v8, 4, v3
	v_lshlrev_b32_e32 v8, 2, v8
	v_xor_b32_e32 v9, 8, v3
	v_lshlrev_b32_e32 v9, 2, v9
	v_xor_b32_e32 v10, 16, v3
	v_lshlrev_b32_e32 v10, 2, v10
	v_xor_b32_e32 v11, 32, v3
	v_lshlrev_b32_e32 v11, 2, v11
	v_mov_b32_e32 v16, 0x3727c5ac
	s_waitcnt lgkmcnt(0)
	s_add_u32 s18, s18, 0x7580000
	s_addc_u32 s19, s19, 0
	global_load_dwordx4 v[40:43], v4, s[16:17] offset:0
	global_load_dwordx4 v[44:47], v4, s[16:17] offset:1024
	global_load_dwordx4 v[48:51], v4, s[16:17] offset:2048
	global_load_dwordx4 v[52:55], v4, s[16:17] offset:3072
	s_add_u32 s16, s16, 4096
	s_addc_u32 s17, s17, 0
	global_load_dwordx4 v[56:59], v4, s[16:17] offset:0
	global_load_dwordx4 v[60:63], v4, s[16:17] offset:1024
	global_load_dwordx4 v[64:67], v4, s[16:17] offset:2048
	global_load_dwordx4 v[68:71], v4, s[16:17] offset:3072
	s_cmpk_lt_u32 s4, 8192
	s_cselect_b32 s20, s12, s14
	s_cselect_b32 s21, s13, s15
	s_cselect_b32 s28, 0, 8192
	s_sub_u32 s28, s4, s28
	s_lshr_b32 s29, s28, 19
	s_lshl_b32 s28, s28, 13
	s_add_u32 s20, s20, s28
	s_addc_u32 s21, s21, s29
	global_load_dwordx4 v[72:75], v4, s[20:21] offset:0 nt
	global_load_dwordx4 v[76:79], v4, s[20:21] offset:1024 nt
	global_load_dwordx4 v[80:83], v4, s[20:21] offset:2048 nt
	global_load_dwordx4 v[84:87], v4, s[20:21] offset:3072 nt
	s_add_u32 s20, s20, 4096
	s_addc_u32 s21, s21, 0
	global_load_dwordx4 v[88:91], v4, s[20:21] offset:0 nt
	global_load_dwordx4 v[92:95], v4, s[20:21] offset:1024 nt
	global_load_dwordx4 v[96:99], v4, s[20:21] offset:2048 nt
	global_load_dwordx4 v[100:103], v4, s[20:21] offset:3072 nt
	s_mov_b32 s27, 0

; __device__ __forceinline__ float bf2f(unsigned h) { return __uint_as_float(h << 16); }
; __device__ __forceinline__ void ssd_sample_items(LAS unsigned char* lds, int it0, int itstride, int nitems, const bf16_t* XBC, const float* DT, const float* a_log,
;                                                  const float* state_in, bf16_t* MIX, float* s_ssm) {
;     ...
;     { const int b = it0 >> 2, g = it0 & 3, h = g * 8 + w; const float* sp = state_in + (size_t)(b * NH + h) * HP * NS;
; #pragma unroll
;       for (int k = 0; k < 16; ++k) nx[k] = *(const f32x4*)(sp + k * 256 + lane * 4); }
;     for (int it = it0; it < nitems; it += itstride) {
;         const int b = it >> 2, g = it & 3, h = g * 8 + w;
;         u32x2 Bp[4], Cp[4]; float dtv[4];
; #pragma unroll
;         for (int t = 0; t < 4; ++t) { const size_t row = (size_t)(MP + 4 * b + t);
;             Xs[t * 512 + tid] = bf2f(XBC[row * XBCW + g * 512 + tid]);
;             Bp[t] = *(const u32x2*)(XBC + row * XBCW + 2048 + g * 128 + 4 * nl); Cp[t] = *(const u32x2*)(XBC + row * XBCW + 2560 + g * 128 + 4 * nl);
;             dtv[t] = DT[row * NH + h]; }
;     ...
;                 if (hh == 0) { const float* sp = state_in + (size_t)(b * NH + h) * HP * NS + 4096;
; #pragma unroll
;                     for (int k = 0; k < 16; ++k) nx[k] = *(const f32x4*)(sp + k * 256 + lane * 4); }
;                 else if (itn < nitems) { const int bn = itn >> 2, gn = itn & 3; const float* sp = state_in + (size_t)(bn * NH + gn * 8 + w) * HP * NS;
; #pragma unroll
;                     for (int k = 0; k < 16; ++k) nx[k] = *(const f32x4*)(sp + k * 256 + lane * 4); }
.Lssds_begin:
	s_load_dwordx4 s[24:27], s[0:1], 0xc8
	s_load_dwordx2 s[14:15], s[0:1], 0x10
	s_load_dwordx2 s[16:17], s[0:1], 0x58
	s_mov_b32 s47, s4
	s_lshr_b32 s46, s6, 6
	v_readlane_b32 s21, v253, 20
	v_and_b32_e32 v213, 63, v212
	v_lshrrev_b32_e32 v133, 4, v213
	v_and_b32_e32 v134, 15, v213
	v_lshlrev_b32_e32 v132, 12, v133
	v_lshl_add_u32 v132, v134, 4, v132
	v_lshlrev_b32_e32 v133, 4, v133
	v_lshlrev_b32_e32 v134, 3, v134
	s_mov_b32 s38, 0x55555555
	s_mov_b32 s39, 0x55555555
	s_mov_b32 s68, 0xcccccccc
	s_mov_b32 s69, 0xcccccccc
	s_sub_u32 s33, s94, s21
	s_mov_b32 s48, 1
	s_waitcnt lgkmcnt(0)
	s_add_u32 s40, s26, 0x135d0000
	s_addc_u32 s41, s27, 0
	s_add_u32 s42, s26, 0x9780000
	s_addc_u32 s43, s27, 0
	s_add_u32 s44, s26, 0x1acd0000
	s_addc_u32 s45, s27, 0
	s_add_u32 s18, s24, 0x496a000
	s_addc_u32 s19, s25, 0
	s_lshr_b32 s20, s47, 2
	s_and_b32 s21, s47, 3
	s_lshl_b32 s22, s21, 3
	s_add_u32 s22, s22, s46
	s_lshl_b32 s23, s20, 5
	s_add_u32 s23, s23, s22
	s_lshr_b32 s51, s23, 17
	s_lshl_b32 s50, s23, 15
	s_add_u32 s52, s18, s50
	s_addc_u32 s53, s19, s51
	s_add_u32 s50, s14, s50
	s_addc_u32 s51, s15, s51
	s_add_u32 s54, s50, 0x4000
	s_addc_u32 s55, s51, 0
	s_add_u32 s56, s52, 0x4000
	s_addc_u32 s57, s53, 0
	s_lshl_b32 s20, s20, 2
	s_add_u32 s20, s20, 0x2000
	s_lshl_b32 s23, s22, 7
	s_mul_hi_u32 s59, s20, 0x1800
	s_mul_i32 s58, s20, 0x1800
	s_add_u32 s58, s58, s40
	s_addc_u32 s59, s59, s41
	s_add_u32 s58, s58, s23
	s_addc_u32 s59, s59, 0
	s_add_u32 s60, s58, 0x1800
	s_addc_u32 s61, s59, 0
	s_add_u32 s62, s60, 0x1800
	s_addc_u32 s63, s61, 0
	s_add_u32 s64, s62, 0x1800
	s_addc_u32 s65, s63, 0
	s_lshr_b32 s5, s20, 19
	s_lshl_b32 s4, s20, 13
	s_add_u32 s4, s4, s44
	s_addc_u32 s5, s5, s45
	s_add_u32 s4, s4, s23
	s_addc_u32 s5, s5, 0
	s_add_u32 s6, s4, 0x2000
	s_addc_u32 s7, s5, 0
	s_add_u32 s8, s6, 0x2000
	s_addc_u32 s9, s7, 0
	s_add_u32 s10, s8, 0x2000
	s_addc_u32 s11, s9, 0
	s_lshl_b32 s23, s22, 2
	s_lshr_b32 s21, s20, 25
	s_lshl_b32 s20, s20, 7
	s_add_u32 s20, s20, s42
	s_addc_u32 s21, s21, s43
	s_add_u32 s20, s20, s23
	s_addc_u32 s21, s21, 0
	s_load_dword s28, s[20:21], 0x0
	s_load_dword s29, s[20:21], 0x80
	s_load_dword s30, s[20:21], 0x100
	s_load_dword s31, s[20:21], 0x180
	s_add_u32 s20, s16, s23
	s_addc_u32 s21, s17, 0
	s_load_dword s36, s[20:21], 0x0
	global_load_dwordx4 v[0:3], v132, s[50:51] offset:0
	global_load_dwordx4 v[4:7], v132, s[50:51] offset:256
	global_load_dwordx4 v[8:11], v132, s[50:51] offset:512
	global_load_dwordx4 v[12:15], v132, s[50:51] offset:768
	global_load_dwordx4 v[16:19], v132, s[50:51] offset:1024
	global_load_dwordx4 v[20:23], v132, s[50:51] offset:1280
	global_load_dwordx4 v[24:27], v132, s[50:51] offset:1536
	global_load_dwordx4 v[28:31], v132, s[50:51] offset:1792
	global_load_dwordx4 v[32:35], v132, s[50:51] offset:2048
	global_load_dwordx4 v[36:39], v132, s[50:51] offset:2304
	global_load_dwordx4 v[40:43], v132, s[50:51] offset:2560
	global_load_dwordx4 v[44:47], v132, s[50:51] offset:2816
	global_load_dwordx4 v[48:51], v132, s[50:51] offset:3072
	global_load_dwordx4 v[52:55], v132, s[50:51] offset:3328
	global_load_dwordx4 v[56:59], v132, s[50:51] offset:3584
	global_load_dwordx4 v[60:63], v132, s[50:51] offset:3840
	s_and_b32 s20, s47, 3
	s_lshl_b32 s20, s20, 8
	s_lshl_b32 s21, s22, 7
	s_sub_u32 s20, s20, s21
	s_add_u32 s20, s20, 0x1000
	s_add_u32 s22, s58, s20
	s_addc_u32 s23, s59, 0
	global_load_dwordx2 v[136:137], v134, s[22:23]
	global_load_dwordx2 v[138:139], v134, s[22:23] offset:128
	global_load_dwordx2 v[152:153], v134, s[22:23] offset:1024
	global_load_dwordx2 v[154:155], v134, s[22:23] offset:1152
	s_add_u32 s22, s60, s20
	s_addc_u32 s23, s61, 0
	global_load_dwordx2 v[140:141], v134, s[22:23]
	global_load_dwordx2 v[142:143], v134, s[22:23] offset:128
	global_load_dwordx2 v[156:157], v134, s[22:23] offset:1024
	global_load_dwordx2 v[158:159], v134, s[22:23] offset:1152
	s_add_u32 s22, s62, s20
	s_addc_u32 s23, s63, 0
	global_load_dwordx2 v[144:145], v134, s[22:23]
	global_load_dwordx2 v[146:147], v134, s[22:23] offset:128
	global_load_dwordx2 v[160:161], v134, s[22:23] offset:1024
	global_load_dwordx2 v[162:163], v134, s[22:23] offset:1152
	s_add_u32 s22, s64, s20
	s_addc_u32 s23, s65, 0
	global_load_dwordx2 v[148:149], v134, s[22:23]
	global_load_dwordx2 v[150:151], v134, s[22:23] offset:128
	global_load_dwordx2 v[164:165], v134, s[22:23] offset:1024
	global_load_dwordx2 v[166:167], v134, s[22:23] offset:1152
	global_load_dwordx4 v[168:171], v133, s[58:59] offset:0
	global_load_dwordx4 v[184:187], v133, s[58:59] offset:64
	global_load_dwordx4 v[172:175], v133, s[60:61] offset:0
	global_load_dwordx4 v[188:191], v133, s[60:61] offset:64
	global_load_dwordx4 v[176:179], v133, s[62:63] offset:0
	global_load_dwordx4 v[192:195], v133, s[62:63] offset:64
	global_load_dwordx4 v[180:183], v133, s[64:65] offset:0
	global_load_dwordx4 v[196:199], v133, s[64:65] offset:64
.Lssds_unit:
	global_load_dwordx4 v[64:67], v132, s[54:55] offset:0
	global_load_dwordx4 v[68:71], v132, s[54:55] offset:256
	global_load_dwordx4 v[72:75], v132, s[54:55] offset:512
	global_load_dwordx4 v[76:79], v132, s[54:55] offset:768
	global_load_dwordx4 v[80:83], v132, s[54:55] offset:1024
	global_load_dwordx4 v[84:87], v132, s[54:55] offset:1280
	global_load_dwordx4 v[88:91], v132, s[54:55] offset:1536
	global_load_dwordx4 v[92:95], v132, s[54:55] offset:1792
	global_load_dwordx4 v[96:99], v132, s[54:55] offset:2048
	global_load_dwordx4 v[100:103], v132, s[54:55] offset:2304
	global_load_dwordx4 v[104:107], v132, s[54:55] offset:2560
	global_load_dwordx4 v[108:111], v132, s[54:55] offset:2816
	global_load_dwordx4 v[112:115], v132, s[54:55] offset:3072
	global_load_dwordx4 v[116:119], v132, s[54:55] offset:3328
	global_load_dwordx4 v[120:123], v132, s[54:55] offset:3584
	global_load_dwordx4 v[124:127], v132, s[54:55] offset:3840
	s_cmp_eq_u32 s48, 1
	s_cbranch_scc1 .Lssds_w16
	s_waitcnt vmcnt(32)
	s_branch .Lssds_wd

; __device__ __forceinline__ float bf2f(unsigned h) { return __uint_as_float(h << 16); }
; __device__ __forceinline__ void ssd_sample_items(LAS unsigned char* lds, int it0, int itstride, int nitems, const bf16_t* XBC, const float* DT, const float* a_log,
;                                                  const float* state_in, bf16_t* MIX, float* s_ssm) {
;     ...
;                 const float dt = dtv[t]; const float da = __expf(dt * A);
;                 const f32x4 Bt = (f32x4){bf2f(Bp[t].x & 0xffffu), bf2f(Bp[t].x >> 16), bf2f(Bp[t].y & 0xffffu), bf2f(Bp[t].y >> 16)} * dt;
;                 const f32x4 Ct = (f32x4){bf2f(Cp[t].x & 0xffffu), bf2f(Cp[t].x >> 16), bf2f(Cp[t].y & 0xffffu), bf2f(Cp[t].y >> 16)};
;                 float part[8];
;                 { const bool up8 = (nl & 8) != 0;
; #pragma unroll
;                   for (int i = 0; i < 8; ++i) {
;                     const float x0 = Xs[t * 512 + w * 64 + 32 * hh + 2 * i + half], x1 = Xs[t * 512 + w * 64 + 32 * hh + 2 * (i + 8) + half];
;                     st[i] = st[i] * da + Bt * x0; st[i + 8] = st[i + 8] * da + Bt * x1;
;                     const f32x4 q0 = Ct * st[i], q1 = Ct * st[i + 8];
;                     const float p0 = (q0.x + q0.y) + (q0.z + q0.w), p1 = (q1.x + q1.y) + (q1.z + q1.w);
;                     const float send = up8 ? p0 : p1, keep = up8 ? p1 : p0; part[i] = keep + __shfl_xor(send, 8); } }
.Lssds_wd:
	s_mov_b32 s48, 0
	s_waitcnt lgkmcnt(0)
	v_mov_b32_e32 v248, s36
	v_mul_f32_e32 v248, 0x3fb8aa3b, v248
	v_exp_f32_e32 v248, v248
	s_nop 0
	v_mov_b32_e32 v208, s28
	v_mul_f32_e32 v128, s28, v248
	v_mul_f32_e32 v128, 0xbfb8aa3b, v128
	v_exp_f32_e32 v128, v128
	v_mov_b32_e32 v209, s29
	v_mul_f32_e32 v129, s29, v248
	v_mul_f32_e32 v129, 0xbfb8aa3b, v129
	v_exp_f32_e32 v129, v129
	v_mov_b32_e32 v210, s30
	v_mul_f32_e32 v130, s30, v248
	v_mul_f32_e32 v130, 0xbfb8aa3b, v130
	v_exp_f32_e32 v130, v130
	v_mov_b32_e32 v211, s31
	v_mul_f32_e32 v131, s31, v248
	v_mul_f32_e32 v131, 0xbfb8aa3b, v131
	v_exp_f32_e32 v131, v131
	s_nop 0
	v_lshlrev_b32_e32 v224, 16, v168
	v_and_b32_e32 v225, 0xffff0000, v168
	v_lshlrev_b32_e32 v226, 16, v169
	v_and_b32_e32 v227, 0xffff0000, v169
	v_lshlrev_b32_e32 v228, 16, v170
	v_and_b32_e32 v229, 0xffff0000, v170
	v_lshlrev_b32_e32 v230, 16, v171
	v_and_b32_e32 v231, 0xffff0000, v171
	v_lshlrev_b32_e32 v200, 16, v136
	v_and_b32_e32 v201, 0xffff0000, v136
	v_lshlrev_b32_e32 v202, 16, v137
	v_and_b32_e32 v203, 0xffff0000, v137
	v_lshlrev_b32_e32 v204, 16, v138
	v_and_b32_e32 v205, 0xffff0000, v138
	v_lshlrev_b32_e32 v206, 16, v139
	v_and_b32_e32 v207, 0xffff0000, v139
	v_lshlrev_b32_e32 v216, 16, v152
	v_and_b32_e32 v217, 0xffff0000, v152
	v_lshlrev_b32_e32 v218, 16, v153
	v_and_b32_e32 v219, 0xffff0000, v153
	v_lshlrev_b32_e32 v220, 16, v154
	v_and_b32_e32 v221, 0xffff0000, v154
	v_lshlrev_b32_e32 v222, 16, v155
	v_and_b32_e32 v223, 0xffff0000, v155
	v_pk_mul_f32 v[200:201], v[200:201], v[208:209] op_sel:[0,0] op_sel_hi:[1,0]
	v_pk_mul_f32 v[202:203], v[202:203], v[208:209] op_sel:[0,0] op_sel_hi:[1,0]
	v_pk_mul_f32 v[204:205], v[204:205], v[208:209] op_sel:[0,0] op_sel_hi:[1,0]
	v_pk_mul_f32 v[206:207], v[206:207], v[208:209] op_sel:[0,0] op_sel_hi:[1,0]
	v_pk_mul_f32 v[0:1], v[0:1], v[128:129] op_sel:[0,0] op_sel_hi:[1,0]
	v_pk_mul_f32 v[2:3], v[2:3], v[128:129] op_sel:[0,0] op_sel_hi:[1,0]
	v_pk_fma_f32 v[0:1], v[200:201], v[224:225], v[0:1] op_sel:[0,0,0] op_sel_hi:[1,0,1]
	v_pk_fma_f32 v[2:3], v[202:203], v[224:225], v[2:3] op_sel:[0,0,0] op_sel_hi:[1,0,1]
	v_pk_mul_f32 v[4:5], v[4:5], v[128:129] op_sel:[0,0] op_sel_hi:[1,0]
	v_pk_mul_f32 v[6:7], v[6:7], v[128:129] op_sel:[0,0] op_sel_hi:[1,0]
	v_pk_fma_f32 v[4:5], v[204:205], v[224:225], v[4:5] op_sel:[0,0,0] op_sel_hi:[1,0,1]
	v_pk_fma_f32 v[6:7], v[206:207], v[224:225], v[6:7] op_sel:[0,0,0] op_sel_hi:[1,0,1]
	v_pk_mul_f32 v[240:241], v[216:217], v[0:1]
	v_pk_fma_f32 v[240:241], v[218:219], v[2:3], v[240:241]
	v_pk_fma_f32 v[240:241], v[220:221], v[4:5], v[240:241]
	v_pk_fma_f32 v[240:241], v[222:223], v[6:7], v[240:241]
	v_add_f32_e32 v232, v240, v241
	v_pk_mul_f32 v[8:9], v[8:9], v[128:129] op_sel:[0,0] op_sel_hi:[1,0]
	v_pk_mul_f32 v[10:11], v[10:11], v[128:129] op_sel:[0,0] op_sel_hi:[1,0]
	v_pk_fma_f32 v[8:9], v[200:201], v[224:225], v[8:9] op_sel:[0,1,0] op_sel_hi:[1,1,1]
	v_pk_fma_f32 v[10:11], v[202:203], v[224:225], v[10:11] op_sel:[0,1,0] op_sel_hi:[1,1,1]
	v_pk_mul_f32 v[12:13], v[12:13], v[128:129] op_sel:[0,0] op_sel_hi:[1,0]
	v_pk_mul_f32 v[14:15], v[14:15], v[128:129] op_sel:[0,0] op_sel_hi:[1,0]
	v_pk_fma_f32 v[12:13], v[204:205], v[224:225], v[12:13] op_sel:[0,1,0] op_sel_hi:[1,1,1]
	v_pk_fma_f32 v[14:15], v[206:207], v[224:225], v[14:15] op_sel:[0,1,0] op_sel_hi:[1,1,1]
	v_pk_mul_f32 v[242:243], v[216:217], v[8:9]
	v_pk_fma_f32 v[242:243], v[218:219], v[10:11], v[242:243]
	v_pk_fma_f32 v[242:243], v[220:221], v[12:13], v[242:243]
	v_pk_fma_f32 v[242:243], v[222:223], v[14:15], v[242:243]
	v_add_f32_e32 v233, v242, v243
	v_pk_mul_f32 v[16:17], v[16:17], v[128:129] op_sel:[0,0] op_sel_hi:[1,0]
	v_pk_mul_f32 v[18:19], v[18:19], v[128:129] op_sel:[0,0] op_sel_hi:[1,0]
	v_pk_fma_f32 v[16:17], v[200:201], v[226:227], v[16:17] op_sel:[0,0,0] op_sel_hi:[1,0,1]
	v_pk_fma_f32 v[18:19], v[202:203], v[226:227], v[18:19] op_sel:[0,0,0] op_sel_hi:[1,0,1]
	v_pk_mul_f32 v[20:21], v[20:21], v[128:129] op_sel:[0,0] op_sel_hi:[1,0]
	v_pk_mul_f32 v[22:23], v[22:23], v[128:129] op_sel:[0,0] op_sel_hi:[1,0]
	v_pk_fma_f32 v[20:21], v[204:205], v[226:227], v[20:21] op_sel:[0,0,0] op_sel_hi:[1,0,1]
	v_pk_fma_f32 v[22:23], v[206:207], v[226:227], v[22:23] op_sel:[0,0,0] op_sel_hi:[1,0,1]
	v_pk_mul_f32 v[244:245], v[216:217], v[16:17]
	v_pk_fma_f32 v[244:245], v[218:219], v[18:19], v[244:245]
	v_pk_fma_f32 v[244:245], v[220:221], v[20:21], v[244:245]
	v_pk_fma_f32 v[244:245], v[222:223], v[22:23], v[244:245]
	v_add_f32_e32 v234, v244, v245
	v_pk_mul_f32 v[24:25], v[24:25], v[128:129] op_sel:[0,0] op_sel_hi:[1,0]
	v_pk_mul_f32 v[26:27], v[26:27], v[128:129] op_sel:[0,0] op_sel_hi:[1,0]
	v_pk_fma_f32 v[24:25], v[200:201], v[226:227], v[24:25] op_sel:[0,1,0] op_sel_hi:[1,1,1]
	v_pk_fma_f32 v[26:27], v[202:203], v[226:227], v[26:27] op_sel:[0,1,0] op_sel_hi:[1,1,1]
	v_pk_mul_f32 v[28:29], v[28:29], v[128:129] op_sel:[0,0] op_sel_hi:[1,0]
	v_pk_mul_f32 v[30:31], v[30:31], v[128:129] op_sel:[0,0] op_sel_hi:[1,0]
	v_pk_fma_f32 v[28:29], v[204:205], v[226:227], v[28:29] op_sel:[0,1,0] op_sel_hi:[1,1,1]
	v_pk_fma_f32 v[30:31], v[206:207], v[226:227], v[30:31] op_sel:[0,1,0] op_sel_hi:[1,1,1]
	v_pk_mul_f32 v[246:247], v[216:217], v[24:25]
	v_pk_fma_f32 v[246:247], v[218:219], v[26:27], v[246:247]
	v_pk_fma_f32 v[246:247], v[220:221], v[28:29], v[246:247]
	v_pk_fma_f32 v[246:247], v[222:223], v[30:31], v[246:247]
	v_add_f32_e32 v235, v246, v247
	v_pk_mul_f32 v[32:33], v[32:33], v[128:129] op_sel:[0,0] op_sel_hi:[1,0]
	v_pk_mul_f32 v[34:35], v[34:35], v[128:129] op_sel:[0,0] op_sel_hi:[1,0]
	v_pk_fma_f32 v[32:33], v[200:201], v[228:229], v[32:33] op_sel:[0,0,0] op_sel_hi:[1,0,1]
; __device__ __forceinline__ unsigned f2bf(float f) { unsigned u = __float_as_uint(f); return (u + 0x7fffu + ((u >> 16) & 1u)) >> 16; }
; #define BFLY(o) do { const bool up = (nl & (o)) != 0; _Pragma("unroll") for (int i = 0; i < (o); ++i) { \
;                     const float send = up ? part[i] : part[i + (o)]; const float keep = up ? part[i + (o)] : part[i]; part[i] = keep + __shfl_xor(send, (o)); } } while (0)
; __device__ __forceinline__ void ssd_sample_items(LAS unsigned char* lds, int it0, int itstride, int nitems, const bf16_t* XBC, const float* DT, const float* a_log,
;                                                  const float* state_in, bf16_t* MIX, float* s_ssm) {
;     ...
;                 float part[8];
;                 { const bool up8 = (nl & 8) != 0;
; #pragma unroll
;                   for (int i = 0; i < 8; ++i) {
;                     const float x0 = Xs[t * 512 + w * 64 + 32 * hh + 2 * i + half], x1 = Xs[t * 512 + w * 64 + 32 * hh + 2 * (i + 8) + half];
;                     st[i] = st[i] * da + Bt * x0; st[i + 8] = st[i + 8] * da + Bt * x1;
;                     const f32x4 q0 = Ct * st[i], q1 = Ct * st[i + 8];
;                     const float p0 = (q0.x + q0.y) + (q0.z + q0.w), p1 = (q1.x + q1.y) + (q1.z + q1.w);
;                     const float send = up8 ? p0 : p1, keep = up8 ? p1 : p0; part[i] = keep + __shfl_xor(send, 8); } }
;     ...
;                 BFLY(4); BFLY(2); BFLY(1);
;     ...
;                 yv[t] = part[0] + __shfl_xor(part[0], 16);
;             }
;             const int pout = 32 * hh + 2 * (nl & 15) + half;
;             if ((nl & 16) == 0) {
; #pragma unroll
;                 for (int t = 0; t < 4; ++t) MIX[(size_t)(MP + 4 * b + t) * DMIX + h * 64 + pout] = (bf16_t)f2bf(yv[t]);
	v_pk_fma_f32 v[34:35], v[202:203], v[228:229], v[34:35] op_sel:[0,0,0] op_sel_hi:[1,0,1]
	v_pk_mul_f32 v[36:37], v[36:37], v[128:129] op_sel:[0,0] op_sel_hi:[1,0]
	v_pk_mul_f32 v[38:39], v[38:39], v[128:129] op_sel:[0,0] op_sel_hi:[1,0]
	v_pk_fma_f32 v[36:37], v[204:205], v[228:229], v[36:37] op_sel:[0,0,0] op_sel_hi:[1,0,1]
	v_pk_fma_f32 v[38:39], v[206:207], v[228:229], v[38:39] op_sel:[0,0,0] op_sel_hi:[1,0,1]
	v_pk_mul_f32 v[240:241], v[216:217], v[32:33]
	v_pk_fma_f32 v[240:241], v[218:219], v[34:35], v[240:241]
	v_pk_fma_f32 v[240:241], v[220:221], v[36:37], v[240:241]
	v_pk_fma_f32 v[240:241], v[222:223], v[38:39], v[240:241]
	v_add_f32_e32 v236, v240, v241
	v_pk_mul_f32 v[40:41], v[40:41], v[128:129] op_sel:[0,0] op_sel_hi:[1,0]
	v_pk_mul_f32 v[42:43], v[42:43], v[128:129] op_sel:[0,0] op_sel_hi:[1,0]
	v_pk_fma_f32 v[40:41], v[200:201], v[228:229], v[40:41] op_sel:[0,1,0] op_sel_hi:[1,1,1]
	v_pk_fma_f32 v[42:43], v[202:203], v[228:229], v[42:43] op_sel:[0,1,0] op_sel_hi:[1,1,1]
	v_pk_mul_f32 v[44:45], v[44:45], v[128:129] op_sel:[0,0] op_sel_hi:[1,0]
	v_pk_mul_f32 v[46:47], v[46:47], v[128:129] op_sel:[0,0] op_sel_hi:[1,0]
	v_pk_fma_f32 v[44:45], v[204:205], v[228:229], v[44:45] op_sel:[0,1,0] op_sel_hi:[1,1,1]
	v_pk_fma_f32 v[46:47], v[206:207], v[228:229], v[46:47] op_sel:[0,1,0] op_sel_hi:[1,1,1]
	v_pk_mul_f32 v[242:243], v[216:217], v[40:41]
	v_pk_fma_f32 v[242:243], v[218:219], v[42:43], v[242:243]
	v_pk_fma_f32 v[242:243], v[220:221], v[44:45], v[242:243]
	v_pk_fma_f32 v[242:243], v[222:223], v[46:47], v[242:243]
	v_add_f32_e32 v237, v242, v243
	v_pk_mul_f32 v[48:49], v[48:49], v[128:129] op_sel:[0,0] op_sel_hi:[1,0]
	v_pk_mul_f32 v[50:51], v[50:51], v[128:129] op_sel:[0,0] op_sel_hi:[1,0]
	v_pk_fma_f32 v[48:49], v[200:201], v[230:231], v[48:49] op_sel:[0,0,0] op_sel_hi:[1,0,1]
	v_pk_fma_f32 v[50:51], v[202:203], v[230:231], v[50:51] op_sel:[0,0,0] op_sel_hi:[1,0,1]
	v_pk_mul_f32 v[52:53], v[52:53], v[128:129] op_sel:[0,0] op_sel_hi:[1,0]
	v_pk_mul_f32 v[54:55], v[54:55], v[128:129] op_sel:[0,0] op_sel_hi:[1,0]
	v_pk_fma_f32 v[52:53], v[204:205], v[230:231], v[52:53] op_sel:[0,0,0] op_sel_hi:[1,0,1]
	v_pk_fma_f32 v[54:55], v[206:207], v[230:231], v[54:55] op_sel:[0,0,0] op_sel_hi:[1,0,1]
	v_pk_mul_f32 v[244:245], v[216:217], v[48:49]
	v_pk_fma_f32 v[244:245], v[218:219], v[50:51], v[244:245]
	v_pk_fma_f32 v[244:245], v[220:221], v[52:53], v[244:245]
	v_pk_fma_f32 v[244:245], v[222:223], v[54:55], v[244:245]
	v_add_f32_e32 v238, v244, v245
	v_pk_mul_f32 v[56:57], v[56:57], v[128:129] op_sel:[0,0] op_sel_hi:[1,0]
	v_pk_mul_f32 v[58:59], v[58:59], v[128:129] op_sel:[0,0] op_sel_hi:[1,0]
	v_pk_fma_f32 v[56:57], v[200:201], v[230:231], v[56:57] op_sel:[0,1,0] op_sel_hi:[1,1,1]
	v_pk_fma_f32 v[58:59], v[202:203], v[230:231], v[58:59] op_sel:[0,1,0] op_sel_hi:[1,1,1]
	v_pk_mul_f32 v[60:61], v[60:61], v[128:129] op_sel:[0,0] op_sel_hi:[1,0]
	v_pk_mul_f32 v[62:63], v[62:63], v[128:129] op_sel:[0,0] op_sel_hi:[1,0]
	v_pk_fma_f32 v[60:61], v[204:205], v[230:231], v[60:61] op_sel:[0,1,0] op_sel_hi:[1,1,1]
	v_pk_fma_f32 v[62:63], v[206:207], v[230:231], v[62:63] op_sel:[0,1,0] op_sel_hi:[1,1,1]
	v_pk_mul_f32 v[246:247], v[216:217], v[56:57]
	v_pk_fma_f32 v[246:247], v[218:219], v[58:59], v[246:247]
	v_pk_fma_f32 v[246:247], v[220:221], v[60:61], v[246:247]
	v_pk_fma_f32 v[246:247], v[222:223], v[62:63], v[246:247]
	v_add_f32_e32 v239, v246, v247
	v_add_f32_dpp v232, v232, v232 row_mirror row_mask:0xf bank_mask:0x3
	v_add_f32_dpp v232, v236, v236 row_mirror row_mask:0xf bank_mask:0xc
	v_add_f32_dpp v233, v233, v233 row_mirror row_mask:0xf bank_mask:0x3
	v_add_f32_dpp v233, v237, v237 row_mirror row_mask:0xf bank_mask:0xc
	v_add_f32_dpp v234, v234, v234 row_mirror row_mask:0xf bank_mask:0x3
	v_add_f32_dpp v234, v238, v238 row_mirror row_mask:0xf bank_mask:0xc
	v_add_f32_dpp v235, v235, v235 row_mirror row_mask:0xf bank_mask:0x3
	v_add_f32_dpp v235, v239, v239 row_mirror row_mask:0xf bank_mask:0xc
	v_add_f32_dpp v232, v232, v232 row_half_mirror row_mask:0xf bank_mask:0x5
	v_add_f32_dpp v232, v234, v234 row_half_mirror row_mask:0xf bank_mask:0xa
	v_add_f32_dpp v233, v233, v233 row_half_mirror row_mask:0xf bank_mask:0x5
	v_add_f32_dpp v233, v235, v235 row_half_mirror row_mask:0xf bank_mask:0xa
	v_add_f32_dpp v248, v232, v232 quad_perm:[2,3,0,1] row_mask:0xf bank_mask:0xf
	s_nop 0
	v_add_f32_dpp v249, v233, v233 quad_perm:[2,3,0,1] row_mask:0xf bank_mask:0xf
	v_cndmask_b32_e64 v232, v248, v249, s[68:69]
	s_nop 1
	v_add_f32_dpp v233, v232, v232 quad_perm:[1,0,3,2] row_mask:0xf bank_mask:0xf
	v_cvt_pk_bf16_f32 v214, v233, v233
	s_mov_b64 exec, s[38:39]
	global_store_short v213, v214, s[4:5] offset:0
	s_mov_b64 exec, -1
	v_lshlrev_b32_e32 v224, 16, v172
	v_and_b32_e32 v225, 0xffff0000, v172
	v_lshlrev_b32_e32 v226, 16, v173
	v_and_b32_e32 v227, 0xffff0000, v173
	v_lshlrev_b32_e32 v228, 16, v174
	v_and_b32_e32 v229, 0xffff0000, v174
	v_lshlrev_b32_e32 v230, 16, v175
	v_and_b32_e32 v231, 0xffff0000, v175
	v_lshlrev_b32_e32 v200, 16, v140
	v_and_b32_e32 v201, 0xffff0000, v140
	v_lshlrev_b32_e32 v202, 16, v141
	v_and_b32_e32 v203, 0xffff0000, v141
	v_lshlrev_b32_e32 v204, 16, v142
	v_and_b32_e32 v205, 0xffff0000, v142
	v_lshlrev_b32_e32 v206, 16, v143
	v_and_b32_e32 v207, 0xffff0000, v143
	v_lshlrev_b32_e32 v216, 16, v156
	v_and_b32_e32 v217, 0xffff0000, v156
	v_lshlrev_b32_e32 v218, 16, v157
	v_and_b32_e32 v219, 0xffff0000, v157
	v_lshlrev_b32_e32 v220, 16, v158
	v_and_b32_e32 v221, 0xffff0000, v158
	v_lshlrev_b32_e32 v222, 16, v159
	v_and_b32_e32 v223, 0xffff0000, v159
	v_pk_mul_f32 v[200:201], v[200:201], v[208:209] op_sel:[0,1] op_sel_hi:[1,1]
; __device__ __forceinline__ float bf2f(unsigned h) { return __uint_as_float(h << 16); }
; __device__ __forceinline__ void ssd_sample_items(LAS unsigned char* lds, int it0, int itstride, int nitems, const bf16_t* XBC, const float* DT, const float* a_log,
;                                                  const float* state_in, bf16_t* MIX, float* s_ssm) {
;     ...
;                 const float dt = dtv[t]; const float da = __expf(dt * A);
;                 const f32x4 Bt = (f32x4){bf2f(Bp[t].x & 0xffffu), bf2f(Bp[t].x >> 16), bf2f(Bp[t].y & 0xffffu), bf2f(Bp[t].y >> 16)} * dt;
;                 const f32x4 Ct = (f32x4){bf2f(Cp[t].x & 0xffffu), bf2f(Cp[t].x >> 16), bf2f(Cp[t].y & 0xffffu), bf2f(Cp[t].y >> 16)};
;                 float part[8];
;                 { const bool up8 = (nl & 8) != 0;
; #pragma unroll
;                   for (int i = 0; i < 8; ++i) {
;                     const float x0 = Xs[t * 512 + w * 64 + 32 * hh + 2 * i + half], x1 = Xs[t * 512 + w * 64 + 32 * hh + 2 * (i + 8) + half];
;                     st[i] = st[i] * da + Bt * x0; st[i + 8] = st[i + 8] * da + Bt * x1;
;                     const f32x4 q0 = Ct * st[i], q1 = Ct * st[i + 8];
;                     const float p0 = (q0.x + q0.y) + (q0.z + q0.w), p1 = (q1.x + q1.y) + (q1.z + q1.w);
;                     const float send = up8 ? p0 : p1, keep = up8 ? p1 : p0; part[i] = keep + __shfl_xor(send, 8); } }
	v_pk_mul_f32 v[202:203], v[202:203], v[208:209] op_sel:[0,1] op_sel_hi:[1,1]
	v_pk_mul_f32 v[204:205], v[204:205], v[208:209] op_sel:[0,1] op_sel_hi:[1,1]
	v_pk_mul_f32 v[206:207], v[206:207], v[208:209] op_sel:[0,1] op_sel_hi:[1,1]
	v_pk_mul_f32 v[0:1], v[0:1], v[128:129] op_sel:[0,1] op_sel_hi:[1,1]
	v_pk_mul_f32 v[2:3], v[2:3], v[128:129] op_sel:[0,1] op_sel_hi:[1,1]
	v_pk_fma_f32 v[0:1], v[200:201], v[224:225], v[0:1] op_sel:[0,0,0] op_sel_hi:[1,0,1]
	v_pk_fma_f32 v[2:3], v[202:203], v[224:225], v[2:3] op_sel:[0,0,0] op_sel_hi:[1,0,1]
	v_pk_mul_f32 v[4:5], v[4:5], v[128:129] op_sel:[0,1] op_sel_hi:[1,1]
	v_pk_mul_f32 v[6:7], v[6:7], v[128:129] op_sel:[0,1] op_sel_hi:[1,1]
	v_pk_fma_f32 v[4:5], v[204:205], v[224:225], v[4:5] op_sel:[0,0,0] op_sel_hi:[1,0,1]
	v_pk_fma_f32 v[6:7], v[206:207], v[224:225], v[6:7] op_sel:[0,0,0] op_sel_hi:[1,0,1]
	v_pk_mul_f32 v[240:241], v[216:217], v[0:1]
	v_pk_fma_f32 v[240:241], v[218:219], v[2:3], v[240:241]
	v_pk_fma_f32 v[240:241], v[220:221], v[4:5], v[240:241]
	v_pk_fma_f32 v[240:241], v[222:223], v[6:7], v[240:241]
	v_add_f32_e32 v232, v240, v241
	v_pk_mul_f32 v[8:9], v[8:9], v[128:129] op_sel:[0,1] op_sel_hi:[1,1]
	v_pk_mul_f32 v[10:11], v[10:11], v[128:129] op_sel:[0,1] op_sel_hi:[1,1]
	v_pk_fma_f32 v[8:9], v[200:201], v[224:225], v[8:9] op_sel:[0,1,0] op_sel_hi:[1,1,1]
	v_pk_fma_f32 v[10:11], v[202:203], v[224:225], v[10:11] op_sel:[0,1,0] op_sel_hi:[1,1,1]
	v_pk_mul_f32 v[12:13], v[12:13], v[128:129] op_sel:[0,1] op_sel_hi:[1,1]
	v_pk_mul_f32 v[14:15], v[14:15], v[128:129] op_sel:[0,1] op_sel_hi:[1,1]
	v_pk_fma_f32 v[12:13], v[204:205], v[224:225], v[12:13] op_sel:[0,1,0] op_sel_hi:[1,1,1]
	v_pk_fma_f32 v[14:15], v[206:207], v[224:225], v[14:15] op_sel:[0,1,0] op_sel_hi:[1,1,1]
	v_pk_mul_f32 v[242:243], v[216:217], v[8:9]
	v_pk_fma_f32 v[242:243], v[218:219], v[10:11], v[242:243]
	v_pk_fma_f32 v[242:243], v[220:221], v[12:13], v[242:243]
	v_pk_fma_f32 v[242:243], v[222:223], v[14:15], v[242:243]
	v_add_f32_e32 v233, v242, v243
	v_pk_mul_f32 v[16:17], v[16:17], v[128:129] op_sel:[0,1] op_sel_hi:[1,1]
	v_pk_mul_f32 v[18:19], v[18:19], v[128:129] op_sel:[0,1] op_sel_hi:[1,1]
	v_pk_fma_f32 v[16:17], v[200:201], v[226:227], v[16:17] op_sel:[0,0,0] op_sel_hi:[1,0,1]
	v_pk_fma_f32 v[18:19], v[202:203], v[226:227], v[18:19] op_sel:[0,0,0] op_sel_hi:[1,0,1]
	v_pk_mul_f32 v[20:21], v[20:21], v[128:129] op_sel:[0,1] op_sel_hi:[1,1]
	v_pk_mul_f32 v[22:23], v[22:23], v[128:129] op_sel:[0,1] op_sel_hi:[1,1]
	v_pk_fma_f32 v[20:21], v[204:205], v[226:227], v[20:21] op_sel:[0,0,0] op_sel_hi:[1,0,1]
	v_pk_fma_f32 v[22:23], v[206:207], v[226:227], v[22:23] op_sel:[0,0,0] op_sel_hi:[1,0,1]
	v_pk_mul_f32 v[244:245], v[216:217], v[16:17]
	v_pk_fma_f32 v[244:245], v[218:219], v[18:19], v[244:245]
	v_pk_fma_f32 v[244:245], v[220:221], v[20:21], v[244:245]
	v_pk_fma_f32 v[244:245], v[222:223], v[22:23], v[244:245]
	v_add_f32_e32 v234, v244, v245
	v_pk_mul_f32 v[24:25], v[24:25], v[128:129] op_sel:[0,1] op_sel_hi:[1,1]
	v_pk_mul_f32 v[26:27], v[26:27], v[128:129] op_sel:[0,1] op_sel_hi:[1,1]
	v_pk_fma_f32 v[24:25], v[200:201], v[226:227], v[24:25] op_sel:[0,1,0] op_sel_hi:[1,1,1]
	v_pk_fma_f32 v[26:27], v[202:203], v[226:227], v[26:27] op_sel:[0,1,0] op_sel_hi:[1,1,1]
	v_pk_mul_f32 v[28:29], v[28:29], v[128:129] op_sel:[0,1] op_sel_hi:[1,1]
	v_pk_mul_f32 v[30:31], v[30:31], v[128:129] op_sel:[0,1] op_sel_hi:[1,1]
	v_pk_fma_f32 v[28:29], v[204:205], v[226:227], v[28:29] op_sel:[0,1,0] op_sel_hi:[1,1,1]
	v_pk_fma_f32 v[30:31], v[206:207], v[226:227], v[30:31] op_sel:[0,1,0] op_sel_hi:[1,1,1]
	v_pk_mul_f32 v[246:247], v[216:217], v[24:25]
	v_pk_fma_f32 v[246:247], v[218:219], v[26:27], v[246:247]
	v_pk_fma_f32 v[246:247], v[220:221], v[28:29], v[246:247]
	v_pk_fma_f32 v[246:247], v[222:223], v[30:31], v[246:247]
	v_add_f32_e32 v235, v246, v247
	v_pk_mul_f32 v[32:33], v[32:33], v[128:129] op_sel:[0,1] op_sel_hi:[1,1]
	v_pk_mul_f32 v[34:35], v[34:35], v[128:129] op_sel:[0,1] op_sel_hi:[1,1]
	v_pk_fma_f32 v[32:33], v[200:201], v[228:229], v[32:33] op_sel:[0,0,0] op_sel_hi:[1,0,1]
	v_pk_fma_f32 v[34:35], v[202:203], v[228:229], v[34:35] op_sel:[0,0,0] op_sel_hi:[1,0,1]
	v_pk_mul_f32 v[36:37], v[36:37], v[128:129] op_sel:[0,1] op_sel_hi:[1,1]
	v_pk_mul_f32 v[38:39], v[38:39], v[128:129] op_sel:[0,1] op_sel_hi:[1,1]
	v_pk_fma_f32 v[36:37], v[204:205], v[228:229], v[36:37] op_sel:[0,0,0] op_sel_hi:[1,0,1]
	v_pk_fma_f32 v[38:39], v[206:207], v[228:229], v[38:39] op_sel:[0,0,0] op_sel_hi:[1,0,1]
	v_pk_mul_f32 v[240:241], v[216:217], v[32:33]
	v_pk_fma_f32 v[240:241], v[218:219], v[34:35], v[240:241]
	v_pk_fma_f32 v[240:241], v[220:221], v[36:37], v[240:241]
	v_pk_fma_f32 v[240:241], v[222:223], v[38:39], v[240:241]
	v_add_f32_e32 v236, v240, v241
	v_pk_mul_f32 v[40:41], v[40:41], v[128:129] op_sel:[0,1] op_sel_hi:[1,1]
	v_pk_mul_f32 v[42:43], v[42:43], v[128:129] op_sel:[0,1] op_sel_hi:[1,1]
	v_pk_fma_f32 v[40:41], v[200:201], v[228:229], v[40:41] op_sel:[0,1,0] op_sel_hi:[1,1,1]
	v_pk_fma_f32 v[42:43], v[202:203], v[228:229], v[42:43] op_sel:[0,1,0] op_sel_hi:[1,1,1]
	v_pk_mul_f32 v[44:45], v[44:45], v[128:129] op_sel:[0,1] op_sel_hi:[1,1]
	v_pk_mul_f32 v[46:47], v[46:47], v[128:129] op_sel:[0,1] op_sel_hi:[1,1]
	v_pk_fma_f32 v[44:45], v[204:205], v[228:229], v[44:45] op_sel:[0,1,0] op_sel_hi:[1,1,1]
	v_pk_fma_f32 v[46:47], v[206:207], v[228:229], v[46:47] op_sel:[0,1,0] op_sel_hi:[1,1,1]
	v_pk_mul_f32 v[242:243], v[216:217], v[40:41]
	v_pk_fma_f32 v[242:243], v[218:219], v[42:43], v[242:243]
	v_pk_fma_f32 v[242:243], v[220:221], v[44:45], v[242:243]
	v_pk_fma_f32 v[242:243], v[222:223], v[46:47], v[242:243]
; __device__ __forceinline__ unsigned f2bf(float f) { unsigned u = __float_as_uint(f); return (u + 0x7fffu + ((u >> 16) & 1u)) >> 16; }
; #define BFLY(o) do { const bool up = (nl & (o)) != 0; _Pragma("unroll") for (int i = 0; i < (o); ++i) { \
;                     const float send = up ? part[i] : part[i + (o)]; const float keep = up ? part[i + (o)] : part[i]; part[i] = keep + __shfl_xor(send, (o)); } } while (0)
; __device__ __forceinline__ void ssd_sample_items(LAS unsigned char* lds, int it0, int itstride, int nitems, const bf16_t* XBC, const float* DT, const float* a_log,
;                                                  const float* state_in, bf16_t* MIX, float* s_ssm) {
;     ...
;                 float part[8];
;                 { const bool up8 = (nl & 8) != 0;
; #pragma unroll
;                   for (int i = 0; i < 8; ++i) {
;                     const float x0 = Xs[t * 512 + w * 64 + 32 * hh + 2 * i + half], x1 = Xs[t * 512 + w * 64 + 32 * hh + 2 * (i + 8) + half];
;                     st[i] = st[i] * da + Bt * x0; st[i + 8] = st[i + 8] * da + Bt * x1;
;                     const f32x4 q0 = Ct * st[i], q1 = Ct * st[i + 8];
;                     const float p0 = (q0.x + q0.y) + (q0.z + q0.w), p1 = (q1.x + q1.y) + (q1.z + q1.w);
;                     const float send = up8 ? p0 : p1, keep = up8 ? p1 : p0; part[i] = keep + __shfl_xor(send, 8); } }
;     ...
;                 BFLY(4); BFLY(2); BFLY(1);
;     ...
;                 yv[t] = part[0] + __shfl_xor(part[0], 16);
;             }
;             const int pout = 32 * hh + 2 * (nl & 15) + half;
;             if ((nl & 16) == 0) {
; #pragma unroll
;                 for (int t = 0; t < 4; ++t) MIX[(size_t)(MP + 4 * b + t) * DMIX + h * 64 + pout] = (bf16_t)f2bf(yv[t]);
	v_add_f32_e32 v237, v242, v243
	v_pk_mul_f32 v[48:49], v[48:49], v[128:129] op_sel:[0,1] op_sel_hi:[1,1]
	v_pk_mul_f32 v[50:51], v[50:51], v[128:129] op_sel:[0,1] op_sel_hi:[1,1]
	v_pk_fma_f32 v[48:49], v[200:201], v[230:231], v[48:49] op_sel:[0,0,0] op_sel_hi:[1,0,1]
	v_pk_fma_f32 v[50:51], v[202:203], v[230:231], v[50:51] op_sel:[0,0,0] op_sel_hi:[1,0,1]
	v_pk_mul_f32 v[52:53], v[52:53], v[128:129] op_sel:[0,1] op_sel_hi:[1,1]
	v_pk_mul_f32 v[54:55], v[54:55], v[128:129] op_sel:[0,1] op_sel_hi:[1,1]
	v_pk_fma_f32 v[52:53], v[204:205], v[230:231], v[52:53] op_sel:[0,0,0] op_sel_hi:[1,0,1]
	v_pk_fma_f32 v[54:55], v[206:207], v[230:231], v[54:55] op_sel:[0,0,0] op_sel_hi:[1,0,1]
	v_pk_mul_f32 v[244:245], v[216:217], v[48:49]
	v_pk_fma_f32 v[244:245], v[218:219], v[50:51], v[244:245]
	v_pk_fma_f32 v[244:245], v[220:221], v[52:53], v[244:245]
	v_pk_fma_f32 v[244:245], v[222:223], v[54:55], v[244:245]
	v_add_f32_e32 v238, v244, v245
	v_pk_mul_f32 v[56:57], v[56:57], v[128:129] op_sel:[0,1] op_sel_hi:[1,1]
	v_pk_mul_f32 v[58:59], v[58:59], v[128:129] op_sel:[0,1] op_sel_hi:[1,1]
	v_pk_fma_f32 v[56:57], v[200:201], v[230:231], v[56:57] op_sel:[0,1,0] op_sel_hi:[1,1,1]
	v_pk_fma_f32 v[58:59], v[202:203], v[230:231], v[58:59] op_sel:[0,1,0] op_sel_hi:[1,1,1]
	v_pk_mul_f32 v[60:61], v[60:61], v[128:129] op_sel:[0,1] op_sel_hi:[1,1]
	v_pk_mul_f32 v[62:63], v[62:63], v[128:129] op_sel:[0,1] op_sel_hi:[1,1]
	v_pk_fma_f32 v[60:61], v[204:205], v[230:231], v[60:61] op_sel:[0,1,0] op_sel_hi:[1,1,1]
	v_pk_fma_f32 v[62:63], v[206:207], v[230:231], v[62:63] op_sel:[0,1,0] op_sel_hi:[1,1,1]
	v_pk_mul_f32 v[246:247], v[216:217], v[56:57]
	v_pk_fma_f32 v[246:247], v[218:219], v[58:59], v[246:247]
	v_pk_fma_f32 v[246:247], v[220:221], v[60:61], v[246:247]
	v_pk_fma_f32 v[246:247], v[222:223], v[62:63], v[246:247]
	v_add_f32_e32 v239, v246, v247
	v_add_f32_dpp v232, v232, v232 row_mirror row_mask:0xf bank_mask:0x3
	v_add_f32_dpp v232, v236, v236 row_mirror row_mask:0xf bank_mask:0xc
	v_add_f32_dpp v233, v233, v233 row_mirror row_mask:0xf bank_mask:0x3
	v_add_f32_dpp v233, v237, v237 row_mirror row_mask:0xf bank_mask:0xc
	v_add_f32_dpp v234, v234, v234 row_mirror row_mask:0xf bank_mask:0x3
	v_add_f32_dpp v234, v238, v238 row_mirror row_mask:0xf bank_mask:0xc
	v_add_f32_dpp v235, v235, v235 row_mirror row_mask:0xf bank_mask:0x3
	v_add_f32_dpp v235, v239, v239 row_mirror row_mask:0xf bank_mask:0xc
	v_add_f32_dpp v232, v232, v232 row_half_mirror row_mask:0xf bank_mask:0x5
	v_add_f32_dpp v232, v234, v234 row_half_mirror row_mask:0xf bank_mask:0xa
	v_add_f32_dpp v233, v233, v233 row_half_mirror row_mask:0xf bank_mask:0x5
	v_add_f32_dpp v233, v235, v235 row_half_mirror row_mask:0xf bank_mask:0xa
	v_add_f32_dpp v248, v232, v232 quad_perm:[2,3,0,1] row_mask:0xf bank_mask:0xf
	s_nop 0
	v_add_f32_dpp v249, v233, v233 quad_perm:[2,3,0,1] row_mask:0xf bank_mask:0xf
	v_cndmask_b32_e64 v232, v248, v249, s[68:69]
	s_nop 1
	v_add_f32_dpp v233, v232, v232 quad_perm:[1,0,3,2] row_mask:0xf bank_mask:0xf
	v_cvt_pk_bf16_f32 v214, v233, v233
	s_mov_b64 exec, s[38:39]
	global_store_short v213, v214, s[6:7] offset:0
	s_mov_b64 exec, -1
	v_lshlrev_b32_e32 v224, 16, v176
	v_and_b32_e32 v225, 0xffff0000, v176
	v_lshlrev_b32_e32 v226, 16, v177
	v_and_b32_e32 v227, 0xffff0000, v177
	v_lshlrev_b32_e32 v228, 16, v178
	v_and_b32_e32 v229, 0xffff0000, v178
	v_lshlrev_b32_e32 v230, 16, v179
	v_and_b32_e32 v231, 0xffff0000, v179
	v_lshlrev_b32_e32 v200, 16, v144
	v_and_b32_e32 v201, 0xffff0000, v144
	v_lshlrev_b32_e32 v202, 16, v145
	v_and_b32_e32 v203, 0xffff0000, v145
	v_lshlrev_b32_e32 v204, 16, v146
	v_and_b32_e32 v205, 0xffff0000, v146
	v_lshlrev_b32_e32 v206, 16, v147
	v_and_b32_e32 v207, 0xffff0000, v147
	v_lshlrev_b32_e32 v216, 16, v160
	v_and_b32_e32 v217, 0xffff0000, v160
	v_lshlrev_b32_e32 v218, 16, v161
	v_and_b32_e32 v219, 0xffff0000, v161
	v_lshlrev_b32_e32 v220, 16, v162
	v_and_b32_e32 v221, 0xffff0000, v162
	v_lshlrev_b32_e32 v222, 16, v163
	v_and_b32_e32 v223, 0xffff0000, v163
	v_pk_mul_f32 v[200:201], v[200:201], v[210:211] op_sel:[0,0] op_sel_hi:[1,0]
	v_pk_mul_f32 v[202:203], v[202:203], v[210:211] op_sel:[0,0] op_sel_hi:[1,0]
	v_pk_mul_f32 v[204:205], v[204:205], v[210:211] op_sel:[0,0] op_sel_hi:[1,0]
	v_pk_mul_f32 v[206:207], v[206:207], v[210:211] op_sel:[0,0] op_sel_hi:[1,0]
	v_pk_mul_f32 v[0:1], v[0:1], v[130:131] op_sel:[0,0] op_sel_hi:[1,0]
	v_pk_mul_f32 v[2:3], v[2:3], v[130:131] op_sel:[0,0] op_sel_hi:[1,0]
	v_pk_fma_f32 v[0:1], v[200:201], v[224:225], v[0:1] op_sel:[0,0,0] op_sel_hi:[1,0,1]
	v_pk_fma_f32 v[2:3], v[202:203], v[224:225], v[2:3] op_sel:[0,0,0] op_sel_hi:[1,0,1]
	v_pk_mul_f32 v[4:5], v[4:5], v[130:131] op_sel:[0,0] op_sel_hi:[1,0]
	v_pk_mul_f32 v[6:7], v[6:7], v[130:131] op_sel:[0,0] op_sel_hi:[1,0]
	v_pk_fma_f32 v[4:5], v[204:205], v[224:225], v[4:5] op_sel:[0,0,0] op_sel_hi:[1,0,1]
	v_pk_fma_f32 v[6:7], v[206:207], v[224:225], v[6:7] op_sel:[0,0,0] op_sel_hi:[1,0,1]
	v_pk_mul_f32 v[240:241], v[216:217], v[0:1]
	v_pk_fma_f32 v[240:241], v[218:219], v[2:3], v[240:241]
	v_pk_fma_f32 v[240:241], v[220:221], v[4:5], v[240:241]
	v_pk_fma_f32 v[240:241], v[222:223], v[6:7], v[240:241]
	v_add_f32_e32 v232, v240, v241
	v_pk_mul_f32 v[8:9], v[8:9], v[130:131] op_sel:[0,0] op_sel_hi:[1,0]
	v_pk_mul_f32 v[10:11], v[10:11], v[130:131] op_sel:[0,0] op_sel_hi:[1,0]
	v_pk_fma_f32 v[8:9], v[200:201], v[224:225], v[8:9] op_sel:[0,1,0] op_sel_hi:[1,1,1]
	v_pk_fma_f32 v[10:11], v[202:203], v[224:225], v[10:11] op_sel:[0,1,0] op_sel_hi:[1,1,1]
	v_pk_mul_f32 v[12:13], v[12:13], v[130:131] op_sel:[0,0] op_sel_hi:[1,0]
	v_pk_mul_f32 v[14:15], v[14:15], v[130:131] op_sel:[0,0] op_sel_hi:[1,0]
; __device__ __forceinline__ float bf2f(unsigned h) { return __uint_as_float(h << 16); }
; __device__ __forceinline__ void ssd_sample_items(LAS unsigned char* lds, int it0, int itstride, int nitems, const bf16_t* XBC, const float* DT, const float* a_log,
;                                                  const float* state_in, bf16_t* MIX, float* s_ssm) {
;     ...
;                 const float dt = dtv[t]; const float da = __expf(dt * A);
;                 const f32x4 Bt = (f32x4){bf2f(Bp[t].x & 0xffffu), bf2f(Bp[t].x >> 16), bf2f(Bp[t].y & 0xffffu), bf2f(Bp[t].y >> 16)} * dt;
;                 const f32x4 Ct = (f32x4){bf2f(Cp[t].x & 0xffffu), bf2f(Cp[t].x >> 16), bf2f(Cp[t].y & 0xffffu), bf2f(Cp[t].y >> 16)};
;                 float part[8];
;                 { const bool up8 = (nl & 8) != 0;
; #pragma unroll
;                   for (int i = 0; i < 8; ++i) {
;                     const float x0 = Xs[t * 512 + w * 64 + 32 * hh + 2 * i + half], x1 = Xs[t * 512 + w * 64 + 32 * hh + 2 * (i + 8) + half];
;                     st[i] = st[i] * da + Bt * x0; st[i + 8] = st[i + 8] * da + Bt * x1;
;                     const f32x4 q0 = Ct * st[i], q1 = Ct * st[i + 8];
;                     const float p0 = (q0.x + q0.y) + (q0.z + q0.w), p1 = (q1.x + q1.y) + (q1.z + q1.w);
;                     const float send = up8 ? p0 : p1, keep = up8 ? p1 : p0; part[i] = keep + __shfl_xor(send, 8); } }
	v_pk_fma_f32 v[12:13], v[204:205], v[224:225], v[12:13] op_sel:[0,1,0] op_sel_hi:[1,1,1]
	v_pk_fma_f32 v[14:15], v[206:207], v[224:225], v[14:15] op_sel:[0,1,0] op_sel_hi:[1,1,1]
	v_pk_mul_f32 v[242:243], v[216:217], v[8:9]
	v_pk_fma_f32 v[242:243], v[218:219], v[10:11], v[242:243]
	v_pk_fma_f32 v[242:243], v[220:221], v[12:13], v[242:243]
	v_pk_fma_f32 v[242:243], v[222:223], v[14:15], v[242:243]
	v_add_f32_e32 v233, v242, v243
	v_pk_mul_f32 v[16:17], v[16:17], v[130:131] op_sel:[0,0] op_sel_hi:[1,0]
	v_pk_mul_f32 v[18:19], v[18:19], v[130:131] op_sel:[0,0] op_sel_hi:[1,0]
	v_pk_fma_f32 v[16:17], v[200:201], v[226:227], v[16:17] op_sel:[0,0,0] op_sel_hi:[1,0,1]
	v_pk_fma_f32 v[18:19], v[202:203], v[226:227], v[18:19] op_sel:[0,0,0] op_sel_hi:[1,0,1]
	v_pk_mul_f32 v[20:21], v[20:21], v[130:131] op_sel:[0,0] op_sel_hi:[1,0]
	v_pk_mul_f32 v[22:23], v[22:23], v[130:131] op_sel:[0,0] op_sel_hi:[1,0]
	v_pk_fma_f32 v[20:21], v[204:205], v[226:227], v[20:21] op_sel:[0,0,0] op_sel_hi:[1,0,1]
	v_pk_fma_f32 v[22:23], v[206:207], v[226:227], v[22:23] op_sel:[0,0,0] op_sel_hi:[1,0,1]
	v_pk_mul_f32 v[244:245], v[216:217], v[16:17]
	v_pk_fma_f32 v[244:245], v[218:219], v[18:19], v[244:245]
	v_pk_fma_f32 v[244:245], v[220:221], v[20:21], v[244:245]
	v_pk_fma_f32 v[244:245], v[222:223], v[22:23], v[244:245]
	v_add_f32_e32 v234, v244, v245
	v_pk_mul_f32 v[24:25], v[24:25], v[130:131] op_sel:[0,0] op_sel_hi:[1,0]
	v_pk_mul_f32 v[26:27], v[26:27], v[130:131] op_sel:[0,0] op_sel_hi:[1,0]
	v_pk_fma_f32 v[24:25], v[200:201], v[226:227], v[24:25] op_sel:[0,1,0] op_sel_hi:[1,1,1]
	v_pk_fma_f32 v[26:27], v[202:203], v[226:227], v[26:27] op_sel:[0,1,0] op_sel_hi:[1,1,1]
	v_pk_mul_f32 v[28:29], v[28:29], v[130:131] op_sel:[0,0] op_sel_hi:[1,0]
	v_pk_mul_f32 v[30:31], v[30:31], v[130:131] op_sel:[0,0] op_sel_hi:[1,0]
	v_pk_fma_f32 v[28:29], v[204:205], v[226:227], v[28:29] op_sel:[0,1,0] op_sel_hi:[1,1,1]
	v_pk_fma_f32 v[30:31], v[206:207], v[226:227], v[30:31] op_sel:[0,1,0] op_sel_hi:[1,1,1]
	v_pk_mul_f32 v[246:247], v[216:217], v[24:25]
	v_pk_fma_f32 v[246:247], v[218:219], v[26:27], v[246:247]
	v_pk_fma_f32 v[246:247], v[220:221], v[28:29], v[246:247]
	v_pk_fma_f32 v[246:247], v[222:223], v[30:31], v[246:247]
	v_add_f32_e32 v235, v246, v247
	v_pk_mul_f32 v[32:33], v[32:33], v[130:131] op_sel:[0,0] op_sel_hi:[1,0]
	v_pk_mul_f32 v[34:35], v[34:35], v[130:131] op_sel:[0,0] op_sel_hi:[1,0]
	v_pk_fma_f32 v[32:33], v[200:201], v[228:229], v[32:33] op_sel:[0,0,0] op_sel_hi:[1,0,1]
	v_pk_fma_f32 v[34:35], v[202:203], v[228:229], v[34:35] op_sel:[0,0,0] op_sel_hi:[1,0,1]
	v_pk_mul_f32 v[36:37], v[36:37], v[130:131] op_sel:[0,0] op_sel_hi:[1,0]
	v_pk_mul_f32 v[38:39], v[38:39], v[130:131] op_sel:[0,0] op_sel_hi:[1,0]
	v_pk_fma_f32 v[36:37], v[204:205], v[228:229], v[36:37] op_sel:[0,0,0] op_sel_hi:[1,0,1]
	v_pk_fma_f32 v[38:39], v[206:207], v[228:229], v[38:39] op_sel:[0,0,0] op_sel_hi:[1,0,1]
	v_pk_mul_f32 v[240:241], v[216:217], v[32:33]
	v_pk_fma_f32 v[240:241], v[218:219], v[34:35], v[240:241]
	v_pk_fma_f32 v[240:241], v[220:221], v[36:37], v[240:241]
	v_pk_fma_f32 v[240:241], v[222:223], v[38:39], v[240:241]
	v_add_f32_e32 v236, v240, v241
	v_pk_mul_f32 v[40:41], v[40:41], v[130:131] op_sel:[0,0] op_sel_hi:[1,0]
	v_pk_mul_f32 v[42:43], v[42:43], v[130:131] op_sel:[0,0] op_sel_hi:[1,0]
	v_pk_fma_f32 v[40:41], v[200:201], v[228:229], v[40:41] op_sel:[0,1,0] op_sel_hi:[1,1,1]
	v_pk_fma_f32 v[42:43], v[202:203], v[228:229], v[42:43] op_sel:[0,1,0] op_sel_hi:[1,1,1]
	v_pk_mul_f32 v[44:45], v[44:45], v[130:131] op_sel:[0,0] op_sel_hi:[1,0]
	v_pk_mul_f32 v[46:47], v[46:47], v[130:131] op_sel:[0,0] op_sel_hi:[1,0]
	v_pk_fma_f32 v[44:45], v[204:205], v[228:229], v[44:45] op_sel:[0,1,0] op_sel_hi:[1,1,1]
	v_pk_fma_f32 v[46:47], v[206:207], v[228:229], v[46:47] op_sel:[0,1,0] op_sel_hi:[1,1,1]
	v_pk_mul_f32 v[242:243], v[216:217], v[40:41]
	v_pk_fma_f32 v[242:243], v[218:219], v[42:43], v[242:243]
	v_pk_fma_f32 v[242:243], v[220:221], v[44:45], v[242:243]
	v_pk_fma_f32 v[242:243], v[222:223], v[46:47], v[242:243]
	v_add_f32_e32 v237, v242, v243
	v_pk_mul_f32 v[48:49], v[48:49], v[130:131] op_sel:[0,0] op_sel_hi:[1,0]
	v_pk_mul_f32 v[50:51], v[50:51], v[130:131] op_sel:[0,0] op_sel_hi:[1,0]
	v_pk_fma_f32 v[48:49], v[200:201], v[230:231], v[48:49] op_sel:[0,0,0] op_sel_hi:[1,0,1]
	v_pk_fma_f32 v[50:51], v[202:203], v[230:231], v[50:51] op_sel:[0,0,0] op_sel_hi:[1,0,1]
	v_pk_mul_f32 v[52:53], v[52:53], v[130:131] op_sel:[0,0] op_sel_hi:[1,0]
	v_pk_mul_f32 v[54:55], v[54:55], v[130:131] op_sel:[0,0] op_sel_hi:[1,0]
	v_pk_fma_f32 v[52:53], v[204:205], v[230:231], v[52:53] op_sel:[0,0,0] op_sel_hi:[1,0,1]
	v_pk_fma_f32 v[54:55], v[206:207], v[230:231], v[54:55] op_sel:[0,0,0] op_sel_hi:[1,0,1]
	v_pk_mul_f32 v[244:245], v[216:217], v[48:49]
	v_pk_fma_f32 v[244:245], v[218:219], v[50:51], v[244:245]
	v_pk_fma_f32 v[244:245], v[220:221], v[52:53], v[244:245]
	v_pk_fma_f32 v[244:245], v[222:223], v[54:55], v[244:245]
	v_add_f32_e32 v238, v244, v245
	v_pk_mul_f32 v[56:57], v[56:57], v[130:131] op_sel:[0,0] op_sel_hi:[1,0]
	v_pk_mul_f32 v[58:59], v[58:59], v[130:131] op_sel:[0,0] op_sel_hi:[1,0]
	v_pk_fma_f32 v[56:57], v[200:201], v[230:231], v[56:57] op_sel:[0,1,0] op_sel_hi:[1,1,1]
	v_pk_fma_f32 v[58:59], v[202:203], v[230:231], v[58:59] op_sel:[0,1,0] op_sel_hi:[1,1,1]
	v_pk_mul_f32 v[60:61], v[60:61], v[130:131] op_sel:[0,0] op_sel_hi:[1,0]
	v_pk_mul_f32 v[62:63], v[62:63], v[130:131] op_sel:[0,0] op_sel_hi:[1,0]
	v_pk_fma_f32 v[60:61], v[204:205], v[230:231], v[60:61] op_sel:[0,1,0] op_sel_hi:[1,1,1]
	v_pk_fma_f32 v[62:63], v[206:207], v[230:231], v[62:63] op_sel:[0,1,0] op_sel_hi:[1,1,1]
; __device__ __forceinline__ unsigned f2bf(float f) { unsigned u = __float_as_uint(f); return (u + 0x7fffu + ((u >> 16) & 1u)) >> 16; }
; #define BFLY(o) do { const bool up = (nl & (o)) != 0; _Pragma("unroll") for (int i = 0; i < (o); ++i) { \
;                     const float send = up ? part[i] : part[i + (o)]; const float keep = up ? part[i + (o)] : part[i]; part[i] = keep + __shfl_xor(send, (o)); } } while (0)
; __device__ __forceinline__ void ssd_sample_items(LAS unsigned char* lds, int it0, int itstride, int nitems, const bf16_t* XBC, const float* DT, const float* a_log,
;                                                  const float* state_in, bf16_t* MIX, float* s_ssm) {
;     ...
;                 float part[8];
;                 { const bool up8 = (nl & 8) != 0;
; #pragma unroll
;                   for (int i = 0; i < 8; ++i) {
;                     const float x0 = Xs[t * 512 + w * 64 + 32 * hh + 2 * i + half], x1 = Xs[t * 512 + w * 64 + 32 * hh + 2 * (i + 8) + half];
;                     st[i] = st[i] * da + Bt * x0; st[i + 8] = st[i + 8] * da + Bt * x1;
;                     const f32x4 q0 = Ct * st[i], q1 = Ct * st[i + 8];
;                     const float p0 = (q0.x + q0.y) + (q0.z + q0.w), p1 = (q1.x + q1.y) + (q1.z + q1.w);
;                     const float send = up8 ? p0 : p1, keep = up8 ? p1 : p0; part[i] = keep + __shfl_xor(send, 8); } }
;     ...
;                 BFLY(4); BFLY(2); BFLY(1);
;     ...
;                 yv[t] = part[0] + __shfl_xor(part[0], 16);
;             }
;             const int pout = 32 * hh + 2 * (nl & 15) + half;
;             if ((nl & 16) == 0) {
; #pragma unroll
;                 for (int t = 0; t < 4; ++t) MIX[(size_t)(MP + 4 * b + t) * DMIX + h * 64 + pout] = (bf16_t)f2bf(yv[t]);
	v_pk_mul_f32 v[246:247], v[216:217], v[56:57]
	v_pk_fma_f32 v[246:247], v[218:219], v[58:59], v[246:247]
	v_pk_fma_f32 v[246:247], v[220:221], v[60:61], v[246:247]
	v_pk_fma_f32 v[246:247], v[222:223], v[62:63], v[246:247]
	v_add_f32_e32 v239, v246, v247
	v_add_f32_dpp v232, v232, v232 row_mirror row_mask:0xf bank_mask:0x3
	v_add_f32_dpp v232, v236, v236 row_mirror row_mask:0xf bank_mask:0xc
	v_add_f32_dpp v233, v233, v233 row_mirror row_mask:0xf bank_mask:0x3
	v_add_f32_dpp v233, v237, v237 row_mirror row_mask:0xf bank_mask:0xc
	v_add_f32_dpp v234, v234, v234 row_mirror row_mask:0xf bank_mask:0x3
	v_add_f32_dpp v234, v238, v238 row_mirror row_mask:0xf bank_mask:0xc
	v_add_f32_dpp v235, v235, v235 row_mirror row_mask:0xf bank_mask:0x3
	v_add_f32_dpp v235, v239, v239 row_mirror row_mask:0xf bank_mask:0xc
	v_add_f32_dpp v232, v232, v232 row_half_mirror row_mask:0xf bank_mask:0x5
	v_add_f32_dpp v232, v234, v234 row_half_mirror row_mask:0xf bank_mask:0xa
	v_add_f32_dpp v233, v233, v233 row_half_mirror row_mask:0xf bank_mask:0x5
	v_add_f32_dpp v233, v235, v235 row_half_mirror row_mask:0xf bank_mask:0xa
	v_add_f32_dpp v248, v232, v232 quad_perm:[2,3,0,1] row_mask:0xf bank_mask:0xf
	s_nop 0
	v_add_f32_dpp v249, v233, v233 quad_perm:[2,3,0,1] row_mask:0xf bank_mask:0xf
	v_cndmask_b32_e64 v232, v248, v249, s[68:69]
	s_nop 1
	v_add_f32_dpp v233, v232, v232 quad_perm:[1,0,3,2] row_mask:0xf bank_mask:0xf
	v_cvt_pk_bf16_f32 v214, v233, v233
	s_mov_b64 exec, s[38:39]
	global_store_short v213, v214, s[8:9] offset:0
	s_mov_b64 exec, -1
	v_lshlrev_b32_e32 v224, 16, v180
	v_and_b32_e32 v225, 0xffff0000, v180
	v_lshlrev_b32_e32 v226, 16, v181
	v_and_b32_e32 v227, 0xffff0000, v181
	v_lshlrev_b32_e32 v228, 16, v182
	v_and_b32_e32 v229, 0xffff0000, v182
	v_lshlrev_b32_e32 v230, 16, v183
	v_and_b32_e32 v231, 0xffff0000, v183
	v_lshlrev_b32_e32 v200, 16, v148
	v_and_b32_e32 v201, 0xffff0000, v148
	v_lshlrev_b32_e32 v202, 16, v149
	v_and_b32_e32 v203, 0xffff0000, v149
	v_lshlrev_b32_e32 v204, 16, v150
	v_and_b32_e32 v205, 0xffff0000, v150
	v_lshlrev_b32_e32 v206, 16, v151
	v_and_b32_e32 v207, 0xffff0000, v151
	v_lshlrev_b32_e32 v216, 16, v164
	v_and_b32_e32 v217, 0xffff0000, v164
	v_lshlrev_b32_e32 v218, 16, v165
	v_and_b32_e32 v219, 0xffff0000, v165
	v_lshlrev_b32_e32 v220, 16, v166
	v_and_b32_e32 v221, 0xffff0000, v166
	v_lshlrev_b32_e32 v222, 16, v167
	v_and_b32_e32 v223, 0xffff0000, v167
	v_pk_mul_f32 v[200:201], v[200:201], v[210:211] op_sel:[0,1] op_sel_hi:[1,1]
	v_pk_mul_f32 v[202:203], v[202:203], v[210:211] op_sel:[0,1] op_sel_hi:[1,1]
	v_pk_mul_f32 v[204:205], v[204:205], v[210:211] op_sel:[0,1] op_sel_hi:[1,1]
	v_pk_mul_f32 v[206:207], v[206:207], v[210:211] op_sel:[0,1] op_sel_hi:[1,1]
	v_pk_mul_f32 v[0:1], v[0:1], v[130:131] op_sel:[0,1] op_sel_hi:[1,1]
	v_pk_mul_f32 v[2:3], v[2:3], v[130:131] op_sel:[0,1] op_sel_hi:[1,1]
	v_pk_fma_f32 v[0:1], v[200:201], v[224:225], v[0:1] op_sel:[0,0,0] op_sel_hi:[1,0,1]
	v_pk_fma_f32 v[2:3], v[202:203], v[224:225], v[2:3] op_sel:[0,0,0] op_sel_hi:[1,0,1]
	v_pk_mul_f32 v[4:5], v[4:5], v[130:131] op_sel:[0,1] op_sel_hi:[1,1]
	v_pk_mul_f32 v[6:7], v[6:7], v[130:131] op_sel:[0,1] op_sel_hi:[1,1]
	v_pk_fma_f32 v[4:5], v[204:205], v[224:225], v[4:5] op_sel:[0,0,0] op_sel_hi:[1,0,1]
	v_pk_fma_f32 v[6:7], v[206:207], v[224:225], v[6:7] op_sel:[0,0,0] op_sel_hi:[1,0,1]
	v_pk_mul_f32 v[240:241], v[216:217], v[0:1]
	v_pk_fma_f32 v[240:241], v[218:219], v[2:3], v[240:241]
	v_pk_fma_f32 v[240:241], v[220:221], v[4:5], v[240:241]
	v_pk_fma_f32 v[240:241], v[222:223], v[6:7], v[240:241]
	v_add_f32_e32 v232, v240, v241
	v_pk_mul_f32 v[8:9], v[8:9], v[130:131] op_sel:[0,1] op_sel_hi:[1,1]
	v_pk_mul_f32 v[10:11], v[10:11], v[130:131] op_sel:[0,1] op_sel_hi:[1,1]
	v_pk_fma_f32 v[8:9], v[200:201], v[224:225], v[8:9] op_sel:[0,1,0] op_sel_hi:[1,1,1]
	v_pk_fma_f32 v[10:11], v[202:203], v[224:225], v[10:11] op_sel:[0,1,0] op_sel_hi:[1,1,1]
	v_pk_mul_f32 v[12:13], v[12:13], v[130:131] op_sel:[0,1] op_sel_hi:[1,1]
	v_pk_mul_f32 v[14:15], v[14:15], v[130:131] op_sel:[0,1] op_sel_hi:[1,1]
	v_pk_fma_f32 v[12:13], v[204:205], v[224:225], v[12:13] op_sel:[0,1,0] op_sel_hi:[1,1,1]
	v_pk_fma_f32 v[14:15], v[206:207], v[224:225], v[14:15] op_sel:[0,1,0] op_sel_hi:[1,1,1]
	v_pk_mul_f32 v[242:243], v[216:217], v[8:9]
	v_pk_fma_f32 v[242:243], v[218:219], v[10:11], v[242:243]
	v_pk_fma_f32 v[242:243], v[220:221], v[12:13], v[242:243]
	v_pk_fma_f32 v[242:243], v[222:223], v[14:15], v[242:243]
	v_add_f32_e32 v233, v242, v243
	v_pk_mul_f32 v[16:17], v[16:17], v[130:131] op_sel:[0,1] op_sel_hi:[1,1]
	v_pk_mul_f32 v[18:19], v[18:19], v[130:131] op_sel:[0,1] op_sel_hi:[1,1]
	v_pk_fma_f32 v[16:17], v[200:201], v[226:227], v[16:17] op_sel:[0,0,0] op_sel_hi:[1,0,1]
	v_pk_fma_f32 v[18:19], v[202:203], v[226:227], v[18:19] op_sel:[0,0,0] op_sel_hi:[1,0,1]
	v_pk_mul_f32 v[20:21], v[20:21], v[130:131] op_sel:[0,1] op_sel_hi:[1,1]
	v_pk_mul_f32 v[22:23], v[22:23], v[130:131] op_sel:[0,1] op_sel_hi:[1,1]
	v_pk_fma_f32 v[20:21], v[204:205], v[226:227], v[20:21] op_sel:[0,0,0] op_sel_hi:[1,0,1]
	v_pk_fma_f32 v[22:23], v[206:207], v[226:227], v[22:23] op_sel:[0,0,0] op_sel_hi:[1,0,1]
	v_pk_mul_f32 v[244:245], v[216:217], v[16:17]
	v_pk_fma_f32 v[244:245], v[218:219], v[18:19], v[244:245]
	v_pk_fma_f32 v[244:245], v[220:221], v[20:21], v[244:245]
	v_pk_fma_f32 v[244:245], v[222:223], v[22:23], v[244:245]
	v_add_f32_e32 v234, v244, v245
	v_pk_mul_f32 v[24:25], v[24:25], v[130:131] op_sel:[0,1] op_sel_hi:[1,1]
	v_pk_mul_f32 v[26:27], v[26:27], v[130:131] op_sel:[0,1] op_sel_hi:[1,1]
	v_pk_fma_f32 v[24:25], v[200:201], v[226:227], v[24:25] op_sel:[0,1,0] op_sel_hi:[1,1,1]
; __device__ __forceinline__ unsigned f2bf(float f) { unsigned u = __float_as_uint(f); return (u + 0x7fffu + ((u >> 16) & 1u)) >> 16; }
; #define BFLY(o) do { const bool up = (nl & (o)) != 0; _Pragma("unroll") for (int i = 0; i < (o); ++i) { \
;                     const float send = up ? part[i] : part[i + (o)]; const float keep = up ? part[i + (o)] : part[i]; part[i] = keep + __shfl_xor(send, (o)); } } while (0)
; __device__ __forceinline__ void ssd_sample_items(LAS unsigned char* lds, int it0, int itstride, int nitems, const bf16_t* XBC, const float* DT, const float* a_log,
;                                                  const float* state_in, bf16_t* MIX, float* s_ssm) {
;     ...
;                 float part[8];
;                 { const bool up8 = (nl & 8) != 0;
; #pragma unroll
;                   for (int i = 0; i < 8; ++i) {
;                     const float x0 = Xs[t * 512 + w * 64 + 32 * hh + 2 * i + half], x1 = Xs[t * 512 + w * 64 + 32 * hh + 2 * (i + 8) + half];
;                     st[i] = st[i] * da + Bt * x0; st[i + 8] = st[i + 8] * da + Bt * x1;
;                     const f32x4 q0 = Ct * st[i], q1 = Ct * st[i + 8];
;                     const float p0 = (q0.x + q0.y) + (q0.z + q0.w), p1 = (q1.x + q1.y) + (q1.z + q1.w);
;                     const float send = up8 ? p0 : p1, keep = up8 ? p1 : p0; part[i] = keep + __shfl_xor(send, 8); } }
;     ...
;                 BFLY(4); BFLY(2); BFLY(1);
;     ...
;                 yv[t] = part[0] + __shfl_xor(part[0], 16);
;             }
;             const int pout = 32 * hh + 2 * (nl & 15) + half;
;             if ((nl & 16) == 0) {
; #pragma unroll
;                 for (int t = 0; t < 4; ++t) MIX[(size_t)(MP + 4 * b + t) * DMIX + h * 64 + pout] = (bf16_t)f2bf(yv[t]);
;             }
;             float* op = s_ssm + (size_t)(b * NH + h) * HP * NS + hh * 4096;
; #pragma unroll
;             for (int k = 0; k < 16; ++k) *(f32x4*)(op + k * 256 + lane * 4) = st[k];
	v_pk_fma_f32 v[26:27], v[202:203], v[226:227], v[26:27] op_sel:[0,1,0] op_sel_hi:[1,1,1]
	v_pk_mul_f32 v[28:29], v[28:29], v[130:131] op_sel:[0,1] op_sel_hi:[1,1]
	v_pk_mul_f32 v[30:31], v[30:31], v[130:131] op_sel:[0,1] op_sel_hi:[1,1]
	v_pk_fma_f32 v[28:29], v[204:205], v[226:227], v[28:29] op_sel:[0,1,0] op_sel_hi:[1,1,1]
	v_pk_fma_f32 v[30:31], v[206:207], v[226:227], v[30:31] op_sel:[0,1,0] op_sel_hi:[1,1,1]
	v_pk_mul_f32 v[246:247], v[216:217], v[24:25]
	v_pk_fma_f32 v[246:247], v[218:219], v[26:27], v[246:247]
	v_pk_fma_f32 v[246:247], v[220:221], v[28:29], v[246:247]
	v_pk_fma_f32 v[246:247], v[222:223], v[30:31], v[246:247]
	v_add_f32_e32 v235, v246, v247
	v_pk_mul_f32 v[32:33], v[32:33], v[130:131] op_sel:[0,1] op_sel_hi:[1,1]
	v_pk_mul_f32 v[34:35], v[34:35], v[130:131] op_sel:[0,1] op_sel_hi:[1,1]
	v_pk_fma_f32 v[32:33], v[200:201], v[228:229], v[32:33] op_sel:[0,0,0] op_sel_hi:[1,0,1]
	v_pk_fma_f32 v[34:35], v[202:203], v[228:229], v[34:35] op_sel:[0,0,0] op_sel_hi:[1,0,1]
	v_pk_mul_f32 v[36:37], v[36:37], v[130:131] op_sel:[0,1] op_sel_hi:[1,1]
	v_pk_mul_f32 v[38:39], v[38:39], v[130:131] op_sel:[0,1] op_sel_hi:[1,1]
	v_pk_fma_f32 v[36:37], v[204:205], v[228:229], v[36:37] op_sel:[0,0,0] op_sel_hi:[1,0,1]
	v_pk_fma_f32 v[38:39], v[206:207], v[228:229], v[38:39] op_sel:[0,0,0] op_sel_hi:[1,0,1]
	v_pk_mul_f32 v[240:241], v[216:217], v[32:33]
	v_pk_fma_f32 v[240:241], v[218:219], v[34:35], v[240:241]
	v_pk_fma_f32 v[240:241], v[220:221], v[36:37], v[240:241]
	v_pk_fma_f32 v[240:241], v[222:223], v[38:39], v[240:241]
	v_add_f32_e32 v236, v240, v241
	v_pk_mul_f32 v[40:41], v[40:41], v[130:131] op_sel:[0,1] op_sel_hi:[1,1]
	v_pk_mul_f32 v[42:43], v[42:43], v[130:131] op_sel:[0,1] op_sel_hi:[1,1]
	v_pk_fma_f32 v[40:41], v[200:201], v[228:229], v[40:41] op_sel:[0,1,0] op_sel_hi:[1,1,1]
	v_pk_fma_f32 v[42:43], v[202:203], v[228:229], v[42:43] op_sel:[0,1,0] op_sel_hi:[1,1,1]
	v_pk_mul_f32 v[44:45], v[44:45], v[130:131] op_sel:[0,1] op_sel_hi:[1,1]
	v_pk_mul_f32 v[46:47], v[46:47], v[130:131] op_sel:[0,1] op_sel_hi:[1,1]
	v_pk_fma_f32 v[44:45], v[204:205], v[228:229], v[44:45] op_sel:[0,1,0] op_sel_hi:[1,1,1]
	v_pk_fma_f32 v[46:47], v[206:207], v[228:229], v[46:47] op_sel:[0,1,0] op_sel_hi:[1,1,1]
	v_pk_mul_f32 v[242:243], v[216:217], v[40:41]
	v_pk_fma_f32 v[242:243], v[218:219], v[42:43], v[242:243]
	v_pk_fma_f32 v[242:243], v[220:221], v[44:45], v[242:243]
	v_pk_fma_f32 v[242:243], v[222:223], v[46:47], v[242:243]
	v_add_f32_e32 v237, v242, v243
	v_pk_mul_f32 v[48:49], v[48:49], v[130:131] op_sel:[0,1] op_sel_hi:[1,1]
	v_pk_mul_f32 v[50:51], v[50:51], v[130:131] op_sel:[0,1] op_sel_hi:[1,1]
	v_pk_fma_f32 v[48:49], v[200:201], v[230:231], v[48:49] op_sel:[0,0,0] op_sel_hi:[1,0,1]
	v_pk_fma_f32 v[50:51], v[202:203], v[230:231], v[50:51] op_sel:[0,0,0] op_sel_hi:[1,0,1]
	v_pk_mul_f32 v[52:53], v[52:53], v[130:131] op_sel:[0,1] op_sel_hi:[1,1]
	v_pk_mul_f32 v[54:55], v[54:55], v[130:131] op_sel:[0,1] op_sel_hi:[1,1]
	v_pk_fma_f32 v[52:53], v[204:205], v[230:231], v[52:53] op_sel:[0,0,0] op_sel_hi:[1,0,1]
	v_pk_fma_f32 v[54:55], v[206:207], v[230:231], v[54:55] op_sel:[0,0,0] op_sel_hi:[1,0,1]
	v_pk_mul_f32 v[244:245], v[216:217], v[48:49]
	v_pk_fma_f32 v[244:245], v[218:219], v[50:51], v[244:245]
	v_pk_fma_f32 v[244:245], v[220:221], v[52:53], v[244:245]
	v_pk_fma_f32 v[244:245], v[222:223], v[54:55], v[244:245]
	v_add_f32_e32 v238, v244, v245
	v_pk_mul_f32 v[56:57], v[56:57], v[130:131] op_sel:[0,1] op_sel_hi:[1,1]
	v_pk_mul_f32 v[58:59], v[58:59], v[130:131] op_sel:[0,1] op_sel_hi:[1,1]
	v_pk_fma_f32 v[56:57], v[200:201], v[230:231], v[56:57] op_sel:[0,1,0] op_sel_hi:[1,1,1]
	v_pk_fma_f32 v[58:59], v[202:203], v[230:231], v[58:59] op_sel:[0,1,0] op_sel_hi:[1,1,1]
	v_pk_mul_f32 v[60:61], v[60:61], v[130:131] op_sel:[0,1] op_sel_hi:[1,1]
	v_pk_mul_f32 v[62:63], v[62:63], v[130:131] op_sel:[0,1] op_sel_hi:[1,1]
	v_pk_fma_f32 v[60:61], v[204:205], v[230:231], v[60:61] op_sel:[0,1,0] op_sel_hi:[1,1,1]
	v_pk_fma_f32 v[62:63], v[206:207], v[230:231], v[62:63] op_sel:[0,1,0] op_sel_hi:[1,1,1]
	v_pk_mul_f32 v[246:247], v[216:217], v[56:57]
	v_pk_fma_f32 v[246:247], v[218:219], v[58:59], v[246:247]
	v_pk_fma_f32 v[246:247], v[220:221], v[60:61], v[246:247]
	v_pk_fma_f32 v[246:247], v[222:223], v[62:63], v[246:247]
	v_add_f32_e32 v239, v246, v247
	v_add_f32_dpp v232, v232, v232 row_mirror row_mask:0xf bank_mask:0x3
	v_add_f32_dpp v232, v236, v236 row_mirror row_mask:0xf bank_mask:0xc
	v_add_f32_dpp v233, v233, v233 row_mirror row_mask:0xf bank_mask:0x3
	v_add_f32_dpp v233, v237, v237 row_mirror row_mask:0xf bank_mask:0xc
	v_add_f32_dpp v234, v234, v234 row_mirror row_mask:0xf bank_mask:0x3
	v_add_f32_dpp v234, v238, v238 row_mirror row_mask:0xf bank_mask:0xc
	v_add_f32_dpp v235, v235, v235 row_mirror row_mask:0xf bank_mask:0x3
	v_add_f32_dpp v235, v239, v239 row_mirror row_mask:0xf bank_mask:0xc
	v_add_f32_dpp v232, v232, v232 row_half_mirror row_mask:0xf bank_mask:0x5
	v_add_f32_dpp v232, v234, v234 row_half_mirror row_mask:0xf bank_mask:0xa
	v_add_f32_dpp v233, v233, v233 row_half_mirror row_mask:0xf bank_mask:0x5
	v_add_f32_dpp v233, v235, v235 row_half_mirror row_mask:0xf bank_mask:0xa
	v_add_f32_dpp v248, v232, v232 quad_perm:[2,3,0,1] row_mask:0xf bank_mask:0xf
	s_nop 0
	v_add_f32_dpp v249, v233, v233 quad_perm:[2,3,0,1] row_mask:0xf bank_mask:0xf
	v_cndmask_b32_e64 v232, v248, v249, s[68:69]
	s_nop 1
	v_add_f32_dpp v233, v232, v232 quad_perm:[1,0,3,2] row_mask:0xf bank_mask:0xf
	v_cvt_pk_bf16_f32 v214, v233, v233
	s_mov_b64 exec, s[38:39]
	global_store_short v213, v214, s[10:11] offset:0
	s_mov_b64 exec, -1
	global_store_dwordx4 v132, v[0:3], s[52:53] offset:0
	global_store_dwordx4 v132, v[4:7], s[52:53] offset:256
	global_store_dwordx4 v132, v[8:11], s[52:53] offset:512
	global_store_dwordx4 v132, v[12:15], s[52:53] offset:768
	global_store_dwordx4 v132, v[16:19], s[52:53] offset:1024
	global_store_dwordx4 v132, v[20:23], s[52:53] offset:1280
	global_store_dwordx4 v132, v[24:27], s[52:53] offset:1536
	global_store_dwordx4 v132, v[28:31], s[52:53] offset:1792
	global_store_dwordx4 v132, v[32:35], s[52:53] offset:2048
	global_store_dwordx4 v132, v[36:39], s[52:53] offset:2304
	global_store_dwordx4 v132, v[40:43], s[52:53] offset:2560
	global_store_dwordx4 v132, v[44:47], s[52:53] offset:2816
	global_store_dwordx4 v132, v[48:51], s[52:53] offset:3072
	global_store_dwordx4 v132, v[52:55], s[52:53] offset:3328
	global_store_dwordx4 v132, v[56:59], s[52:53] offset:3584
	global_store_dwordx4 v132, v[60:63], s[52:53] offset:3840
	s_waitcnt vmcnt(20)
	s_add_u32 s20, s47, s33
	s_cmpk_lt_u32 s20, 512
	s_cbranch_scc0 .Lssds_nopf
; __device__ __forceinline__ float bf2f(unsigned h) { return __uint_as_float(h << 16); }
; __device__ __forceinline__ void ssd_sample_items(LAS unsigned char* lds, int it0, int itstride, int nitems, const bf16_t* XBC, const float* DT, const float* a_log,
;                                                  const float* state_in, bf16_t* MIX, float* s_ssm) {
;     ...
;                 else if (itn < nitems) { const int bn = itn >> 2, gn = itn & 3; const float* sp = state_in + (size_t)(bn * NH + gn * 8 + w) * HP * NS;
; #pragma unroll
;                     for (int k = 0; k < 16; ++k) nx[k] = *(const f32x4*)(sp + k * 256 + lane * 4); }
;     ...
;                 const float dt = dtv[t]; const float da = __expf(dt * A);
;                 const f32x4 Bt = (f32x4){bf2f(Bp[t].x & 0xffffu), bf2f(Bp[t].x >> 16), bf2f(Bp[t].y & 0xffffu), bf2f(Bp[t].y >> 16)} * dt;
;                 const f32x4 Ct = (f32x4){bf2f(Cp[t].x & 0xffffu), bf2f(Cp[t].x >> 16), bf2f(Cp[t].y & 0xffffu), bf2f(Cp[t].y >> 16)};
;                 float part[8];
;                 { const bool up8 = (nl & 8) != 0;
; #pragma unroll
;                   for (int i = 0; i < 8; ++i) {
;                     const float x0 = Xs[t * 512 + w * 64 + 32 * hh + 2 * i + half], x1 = Xs[t * 512 + w * 64 + 32 * hh + 2 * (i + 8) + half];
;                     st[i] = st[i] * da + Bt * x0; st[i + 8] = st[i + 8] * da + Bt * x1;
;                     const f32x4 q0 = Ct * st[i], q1 = Ct * st[i + 8];
;                     const float p0 = (q0.x + q0.y) + (q0.z + q0.w), p1 = (q1.x + q1.y) + (q1.z + q1.w);
;                     const float send = up8 ? p0 : p1, keep = up8 ? p1 : p0; part[i] = keep + __shfl_xor(send, 8); } }
	s_lshr_b32 s21, s20, 2
	s_and_b32 s22, s20, 3
	s_lshl_b32 s22, s22, 3
	s_add_u32 s22, s22, s46
	s_lshl_b32 s21, s21, 5
	s_add_u32 s21, s21, s22
	s_lshr_b32 s71, s21, 17
	s_lshl_b32 s70, s21, 15
	s_add_u32 s70, s14, s70
	s_addc_u32 s71, s15, s71
	global_load_dwordx4 v[0:3], v132, s[70:71] offset:0
	global_load_dwordx4 v[4:7], v132, s[70:71] offset:256
	global_load_dwordx4 v[8:11], v132, s[70:71] offset:512
	global_load_dwordx4 v[12:15], v132, s[70:71] offset:768
	global_load_dwordx4 v[16:19], v132, s[70:71] offset:1024
	global_load_dwordx4 v[20:23], v132, s[70:71] offset:1280
	global_load_dwordx4 v[24:27], v132, s[70:71] offset:1536
	global_load_dwordx4 v[28:31], v132, s[70:71] offset:1792
	global_load_dwordx4 v[32:35], v132, s[70:71] offset:2048
	global_load_dwordx4 v[36:39], v132, s[70:71] offset:2304
	global_load_dwordx4 v[40:43], v132, s[70:71] offset:2560
	global_load_dwordx4 v[44:47], v132, s[70:71] offset:2816
	global_load_dwordx4 v[48:51], v132, s[70:71] offset:3072
	global_load_dwordx4 v[52:55], v132, s[70:71] offset:3328
	global_load_dwordx4 v[56:59], v132, s[70:71] offset:3584
	global_load_dwordx4 v[60:63], v132, s[70:71] offset:3840
.Lssds_nopf:
	v_lshlrev_b32_e32 v224, 16, v184
	v_and_b32_e32 v225, 0xffff0000, v184
	v_lshlrev_b32_e32 v226, 16, v185
	v_and_b32_e32 v227, 0xffff0000, v185
	v_lshlrev_b32_e32 v228, 16, v186
	v_and_b32_e32 v229, 0xffff0000, v186
	v_lshlrev_b32_e32 v230, 16, v187
	v_and_b32_e32 v231, 0xffff0000, v187
	v_lshlrev_b32_e32 v200, 16, v136
	v_and_b32_e32 v201, 0xffff0000, v136
	v_lshlrev_b32_e32 v202, 16, v137
	v_and_b32_e32 v203, 0xffff0000, v137
	v_lshlrev_b32_e32 v204, 16, v138
	v_and_b32_e32 v205, 0xffff0000, v138
	v_lshlrev_b32_e32 v206, 16, v139
	v_and_b32_e32 v207, 0xffff0000, v139
	v_lshlrev_b32_e32 v216, 16, v152
	v_and_b32_e32 v217, 0xffff0000, v152
	v_lshlrev_b32_e32 v218, 16, v153
	v_and_b32_e32 v219, 0xffff0000, v153
	v_lshlrev_b32_e32 v220, 16, v154
	v_and_b32_e32 v221, 0xffff0000, v154
	v_lshlrev_b32_e32 v222, 16, v155
	v_and_b32_e32 v223, 0xffff0000, v155
	v_pk_mul_f32 v[200:201], v[200:201], v[208:209] op_sel:[0,0] op_sel_hi:[1,0]
	v_pk_mul_f32 v[202:203], v[202:203], v[208:209] op_sel:[0,0] op_sel_hi:[1,0]
	v_pk_mul_f32 v[204:205], v[204:205], v[208:209] op_sel:[0,0] op_sel_hi:[1,0]
	v_pk_mul_f32 v[206:207], v[206:207], v[208:209] op_sel:[0,0] op_sel_hi:[1,0]
	v_pk_mul_f32 v[64:65], v[64:65], v[128:129] op_sel:[0,0] op_sel_hi:[1,0]
	v_pk_mul_f32 v[66:67], v[66:67], v[128:129] op_sel:[0,0] op_sel_hi:[1,0]
	v_pk_fma_f32 v[64:65], v[200:201], v[224:225], v[64:65] op_sel:[0,0,0] op_sel_hi:[1,0,1]
	v_pk_fma_f32 v[66:67], v[202:203], v[224:225], v[66:67] op_sel:[0,0,0] op_sel_hi:[1,0,1]
	v_pk_mul_f32 v[68:69], v[68:69], v[128:129] op_sel:[0,0] op_sel_hi:[1,0]
	v_pk_mul_f32 v[70:71], v[70:71], v[128:129] op_sel:[0,0] op_sel_hi:[1,0]
	v_pk_fma_f32 v[68:69], v[204:205], v[224:225], v[68:69] op_sel:[0,0,0] op_sel_hi:[1,0,1]
	v_pk_fma_f32 v[70:71], v[206:207], v[224:225], v[70:71] op_sel:[0,0,0] op_sel_hi:[1,0,1]
	v_pk_mul_f32 v[240:241], v[216:217], v[64:65]
	v_pk_fma_f32 v[240:241], v[218:219], v[66:67], v[240:241]
	v_pk_fma_f32 v[240:241], v[220:221], v[68:69], v[240:241]
	v_pk_fma_f32 v[240:241], v[222:223], v[70:71], v[240:241]
	v_add_f32_e32 v232, v240, v241
	v_pk_mul_f32 v[72:73], v[72:73], v[128:129] op_sel:[0,0] op_sel_hi:[1,0]
	v_pk_mul_f32 v[74:75], v[74:75], v[128:129] op_sel:[0,0] op_sel_hi:[1,0]
	v_pk_fma_f32 v[72:73], v[200:201], v[224:225], v[72:73] op_sel:[0,1,0] op_sel_hi:[1,1,1]
	v_pk_fma_f32 v[74:75], v[202:203], v[224:225], v[74:75] op_sel:[0,1,0] op_sel_hi:[1,1,1]
	v_pk_mul_f32 v[76:77], v[76:77], v[128:129] op_sel:[0,0] op_sel_hi:[1,0]
	v_pk_mul_f32 v[78:79], v[78:79], v[128:129] op_sel:[0,0] op_sel_hi:[1,0]
	v_pk_fma_f32 v[76:77], v[204:205], v[224:225], v[76:77] op_sel:[0,1,0] op_sel_hi:[1,1,1]
	v_pk_fma_f32 v[78:79], v[206:207], v[224:225], v[78:79] op_sel:[0,1,0] op_sel_hi:[1,1,1]
	v_pk_mul_f32 v[242:243], v[216:217], v[72:73]
	v_pk_fma_f32 v[242:243], v[218:219], v[74:75], v[242:243]
	v_pk_fma_f32 v[242:243], v[220:221], v[76:77], v[242:243]
	v_pk_fma_f32 v[242:243], v[222:223], v[78:79], v[242:243]
	v_add_f32_e32 v233, v242, v243
	v_pk_mul_f32 v[80:81], v[80:81], v[128:129] op_sel:[0,0] op_sel_hi:[1,0]
	v_pk_mul_f32 v[82:83], v[82:83], v[128:129] op_sel:[0,0] op_sel_hi:[1,0]
	v_pk_fma_f32 v[80:81], v[200:201], v[226:227], v[80:81] op_sel:[0,0,0] op_sel_hi:[1,0,1]
	v_pk_fma_f32 v[82:83], v[202:203], v[226:227], v[82:83] op_sel:[0,0,0] op_sel_hi:[1,0,1]
	v_pk_mul_f32 v[84:85], v[84:85], v[128:129] op_sel:[0,0] op_sel_hi:[1,0]
	v_pk_mul_f32 v[86:87], v[86:87], v[128:129] op_sel:[0,0] op_sel_hi:[1,0]
	v_pk_fma_f32 v[84:85], v[204:205], v[226:227], v[84:85] op_sel:[0,0,0] op_sel_hi:[1,0,1]
	v_pk_fma_f32 v[86:87], v[206:207], v[226:227], v[86:87] op_sel:[0,0,0] op_sel_hi:[1,0,1]
	v_pk_mul_f32 v[244:245], v[216:217], v[80:81]
	v_pk_fma_f32 v[244:245], v[218:219], v[82:83], v[244:245]
	v_pk_fma_f32 v[244:245], v[220:221], v[84:85], v[244:245]
	v_pk_fma_f32 v[244:245], v[222:223], v[86:87], v[244:245]
	v_add_f32_e32 v234, v244, v245
	v_pk_mul_f32 v[88:89], v[88:89], v[128:129] op_sel:[0,0] op_sel_hi:[1,0]
	v_pk_mul_f32 v[90:91], v[90:91], v[128:129] op_sel:[0,0] op_sel_hi:[1,0]
	v_pk_fma_f32 v[88:89], v[200:201], v[226:227], v[88:89] op_sel:[0,1,0] op_sel_hi:[1,1,1]
	v_pk_fma_f32 v[90:91], v[202:203], v[226:227], v[90:91] op_sel:[0,1,0] op_sel_hi:[1,1,1]
	v_pk_mul_f32 v[92:93], v[92:93], v[128:129] op_sel:[0,0] op_sel_hi:[1,0]
	v_pk_mul_f32 v[94:95], v[94:95], v[128:129] op_sel:[0,0] op_sel_hi:[1,0]
	v_pk_fma_f32 v[92:93], v[204:205], v[226:227], v[92:93] op_sel:[0,1,0] op_sel_hi:[1,1,1]
; __device__ __forceinline__ float bf2f(unsigned h) { return __uint_as_float(h << 16); }
; __device__ __forceinline__ unsigned f2bf(float f) { unsigned u = __float_as_uint(f); return (u + 0x7fffu + ((u >> 16) & 1u)) >> 16; }
; #define BFLY(o) do { const bool up = (nl & (o)) != 0; _Pragma("unroll") for (int i = 0; i < (o); ++i) { \
;                     const float send = up ? part[i] : part[i + (o)]; const float keep = up ? part[i + (o)] : part[i]; part[i] = keep + __shfl_xor(send, (o)); } } while (0)
; __device__ __forceinline__ void ssd_sample_items(LAS unsigned char* lds, int it0, int itstride, int nitems, const bf16_t* XBC, const float* DT, const float* a_log,
;                                                  const float* state_in, bf16_t* MIX, float* s_ssm) {
;     ...
;             for (int t = 0; t < 4; ++t) {
;                 const float dt = dtv[t]; const float da = __expf(dt * A);
;                 const f32x4 Bt = (f32x4){bf2f(Bp[t].x & 0xffffu), bf2f(Bp[t].x >> 16), bf2f(Bp[t].y & 0xffffu), bf2f(Bp[t].y >> 16)} * dt;
;                 const f32x4 Ct = (f32x4){bf2f(Cp[t].x & 0xffffu), bf2f(Cp[t].x >> 16), bf2f(Cp[t].y & 0xffffu), bf2f(Cp[t].y >> 16)};
;                 float part[8];
;                 { const bool up8 = (nl & 8) != 0;
; #pragma unroll
;                   for (int i = 0; i < 8; ++i) {
;                     const float x0 = Xs[t * 512 + w * 64 + 32 * hh + 2 * i + half], x1 = Xs[t * 512 + w * 64 + 32 * hh + 2 * (i + 8) + half];
;                     st[i] = st[i] * da + Bt * x0; st[i + 8] = st[i + 8] * da + Bt * x1;
;                     const f32x4 q0 = Ct * st[i], q1 = Ct * st[i + 8];
;                     const float p0 = (q0.x + q0.y) + (q0.z + q0.w), p1 = (q1.x + q1.y) + (q1.z + q1.w);
;                     const float send = up8 ? p0 : p1, keep = up8 ? p1 : p0; part[i] = keep + __shfl_xor(send, 8); } }
;     ...
;                 BFLY(4); BFLY(2); BFLY(1);
;     ...
;                 yv[t] = part[0] + __shfl_xor(part[0], 16);
;             }
;             const int pout = 32 * hh + 2 * (nl & 15) + half;
;             if ((nl & 16) == 0) {
; #pragma unroll
;                 for (int t = 0; t < 4; ++t) MIX[(size_t)(MP + 4 * b + t) * DMIX + h * 64 + pout] = (bf16_t)f2bf(yv[t]);
;             }
	v_pk_fma_f32 v[94:95], v[206:207], v[226:227], v[94:95] op_sel:[0,1,0] op_sel_hi:[1,1,1]
	v_pk_mul_f32 v[246:247], v[216:217], v[88:89]
	v_pk_fma_f32 v[246:247], v[218:219], v[90:91], v[246:247]
	v_pk_fma_f32 v[246:247], v[220:221], v[92:93], v[246:247]
	v_pk_fma_f32 v[246:247], v[222:223], v[94:95], v[246:247]
	v_add_f32_e32 v235, v246, v247
	v_pk_mul_f32 v[96:97], v[96:97], v[128:129] op_sel:[0,0] op_sel_hi:[1,0]
	v_pk_mul_f32 v[98:99], v[98:99], v[128:129] op_sel:[0,0] op_sel_hi:[1,0]
	v_pk_fma_f32 v[96:97], v[200:201], v[228:229], v[96:97] op_sel:[0,0,0] op_sel_hi:[1,0,1]
	v_pk_fma_f32 v[98:99], v[202:203], v[228:229], v[98:99] op_sel:[0,0,0] op_sel_hi:[1,0,1]
	v_pk_mul_f32 v[100:101], v[100:101], v[128:129] op_sel:[0,0] op_sel_hi:[1,0]
	v_pk_mul_f32 v[102:103], v[102:103], v[128:129] op_sel:[0,0] op_sel_hi:[1,0]
	v_pk_fma_f32 v[100:101], v[204:205], v[228:229], v[100:101] op_sel:[0,0,0] op_sel_hi:[1,0,1]
	v_pk_fma_f32 v[102:103], v[206:207], v[228:229], v[102:103] op_sel:[0,0,0] op_sel_hi:[1,0,1]
	v_pk_mul_f32 v[240:241], v[216:217], v[96:97]
	v_pk_fma_f32 v[240:241], v[218:219], v[98:99], v[240:241]
	v_pk_fma_f32 v[240:241], v[220:221], v[100:101], v[240:241]
	v_pk_fma_f32 v[240:241], v[222:223], v[102:103], v[240:241]
	v_add_f32_e32 v236, v240, v241
	v_pk_mul_f32 v[104:105], v[104:105], v[128:129] op_sel:[0,0] op_sel_hi:[1,0]
	v_pk_mul_f32 v[106:107], v[106:107], v[128:129] op_sel:[0,0] op_sel_hi:[1,0]
	v_pk_fma_f32 v[104:105], v[200:201], v[228:229], v[104:105] op_sel:[0,1,0] op_sel_hi:[1,1,1]
	v_pk_fma_f32 v[106:107], v[202:203], v[228:229], v[106:107] op_sel:[0,1,0] op_sel_hi:[1,1,1]
	v_pk_mul_f32 v[108:109], v[108:109], v[128:129] op_sel:[0,0] op_sel_hi:[1,0]
	v_pk_mul_f32 v[110:111], v[110:111], v[128:129] op_sel:[0,0] op_sel_hi:[1,0]
	v_pk_fma_f32 v[108:109], v[204:205], v[228:229], v[108:109] op_sel:[0,1,0] op_sel_hi:[1,1,1]
	v_pk_fma_f32 v[110:111], v[206:207], v[228:229], v[110:111] op_sel:[0,1,0] op_sel_hi:[1,1,1]
	v_pk_mul_f32 v[242:243], v[216:217], v[104:105]
	v_pk_fma_f32 v[242:243], v[218:219], v[106:107], v[242:243]
	v_pk_fma_f32 v[242:243], v[220:221], v[108:109], v[242:243]
	v_pk_fma_f32 v[242:243], v[222:223], v[110:111], v[242:243]
	v_add_f32_e32 v237, v242, v243
	v_pk_mul_f32 v[112:113], v[112:113], v[128:129] op_sel:[0,0] op_sel_hi:[1,0]
	v_pk_mul_f32 v[114:115], v[114:115], v[128:129] op_sel:[0,0] op_sel_hi:[1,0]
	v_pk_fma_f32 v[112:113], v[200:201], v[230:231], v[112:113] op_sel:[0,0,0] op_sel_hi:[1,0,1]
	v_pk_fma_f32 v[114:115], v[202:203], v[230:231], v[114:115] op_sel:[0,0,0] op_sel_hi:[1,0,1]
	v_pk_mul_f32 v[116:117], v[116:117], v[128:129] op_sel:[0,0] op_sel_hi:[1,0]
	v_pk_mul_f32 v[118:119], v[118:119], v[128:129] op_sel:[0,0] op_sel_hi:[1,0]
	v_pk_fma_f32 v[116:117], v[204:205], v[230:231], v[116:117] op_sel:[0,0,0] op_sel_hi:[1,0,1]
	v_pk_fma_f32 v[118:119], v[206:207], v[230:231], v[118:119] op_sel:[0,0,0] op_sel_hi:[1,0,1]
	v_pk_mul_f32 v[244:245], v[216:217], v[112:113]
	v_pk_fma_f32 v[244:245], v[218:219], v[114:115], v[244:245]
	v_pk_fma_f32 v[244:245], v[220:221], v[116:117], v[244:245]
	v_pk_fma_f32 v[244:245], v[222:223], v[118:119], v[244:245]
	v_add_f32_e32 v238, v244, v245
	v_pk_mul_f32 v[120:121], v[120:121], v[128:129] op_sel:[0,0] op_sel_hi:[1,0]
	v_pk_mul_f32 v[122:123], v[122:123], v[128:129] op_sel:[0,0] op_sel_hi:[1,0]
	v_pk_fma_f32 v[120:121], v[200:201], v[230:231], v[120:121] op_sel:[0,1,0] op_sel_hi:[1,1,1]
	v_pk_fma_f32 v[122:123], v[202:203], v[230:231], v[122:123] op_sel:[0,1,0] op_sel_hi:[1,1,1]
	v_pk_mul_f32 v[124:125], v[124:125], v[128:129] op_sel:[0,0] op_sel_hi:[1,0]
	v_pk_mul_f32 v[126:127], v[126:127], v[128:129] op_sel:[0,0] op_sel_hi:[1,0]
	v_pk_fma_f32 v[124:125], v[204:205], v[230:231], v[124:125] op_sel:[0,1,0] op_sel_hi:[1,1,1]
	v_pk_fma_f32 v[126:127], v[206:207], v[230:231], v[126:127] op_sel:[0,1,0] op_sel_hi:[1,1,1]
	v_pk_mul_f32 v[246:247], v[216:217], v[120:121]
	v_pk_fma_f32 v[246:247], v[218:219], v[122:123], v[246:247]
	v_pk_fma_f32 v[246:247], v[220:221], v[124:125], v[246:247]
	v_pk_fma_f32 v[246:247], v[222:223], v[126:127], v[246:247]
	v_add_f32_e32 v239, v246, v247
	v_add_f32_dpp v232, v232, v232 row_mirror row_mask:0xf bank_mask:0x3
	v_add_f32_dpp v232, v236, v236 row_mirror row_mask:0xf bank_mask:0xc
	v_add_f32_dpp v233, v233, v233 row_mirror row_mask:0xf bank_mask:0x3
	v_add_f32_dpp v233, v237, v237 row_mirror row_mask:0xf bank_mask:0xc
	v_add_f32_dpp v234, v234, v234 row_mirror row_mask:0xf bank_mask:0x3
	v_add_f32_dpp v234, v238, v238 row_mirror row_mask:0xf bank_mask:0xc
	v_add_f32_dpp v235, v235, v235 row_mirror row_mask:0xf bank_mask:0x3
	v_add_f32_dpp v235, v239, v239 row_mirror row_mask:0xf bank_mask:0xc
	v_add_f32_dpp v232, v232, v232 row_half_mirror row_mask:0xf bank_mask:0x5
	v_add_f32_dpp v232, v234, v234 row_half_mirror row_mask:0xf bank_mask:0xa
	v_add_f32_dpp v233, v233, v233 row_half_mirror row_mask:0xf bank_mask:0x5
	v_add_f32_dpp v233, v235, v235 row_half_mirror row_mask:0xf bank_mask:0xa
	v_add_f32_dpp v248, v232, v232 quad_perm:[2,3,0,1] row_mask:0xf bank_mask:0xf
	s_nop 0
	v_add_f32_dpp v249, v233, v233 quad_perm:[2,3,0,1] row_mask:0xf bank_mask:0xf
	v_cndmask_b32_e64 v232, v248, v249, s[68:69]
	s_nop 1
	v_add_f32_dpp v233, v232, v232 quad_perm:[1,0,3,2] row_mask:0xf bank_mask:0xf
	v_cvt_pk_bf16_f32 v214, v233, v233
	s_mov_b64 exec, s[38:39]
	global_store_short v213, v214, s[4:5] offset:64
	s_mov_b64 exec, -1
	v_lshlrev_b32_e32 v224, 16, v188
	v_and_b32_e32 v225, 0xffff0000, v188
	v_lshlrev_b32_e32 v226, 16, v189
	v_and_b32_e32 v227, 0xffff0000, v189
	v_lshlrev_b32_e32 v228, 16, v190
	v_and_b32_e32 v229, 0xffff0000, v190
; __device__ __forceinline__ float bf2f(unsigned h) { return __uint_as_float(h << 16); }
; #define BFLY(o) do { const bool up = (nl & (o)) != 0; _Pragma("unroll") for (int i = 0; i < (o); ++i) { \
;                     const float send = up ? part[i] : part[i + (o)]; const float keep = up ? part[i + (o)] : part[i]; part[i] = keep + __shfl_xor(send, (o)); } } while (0)
; __device__ __forceinline__ void ssd_sample_items(LAS unsigned char* lds, int it0, int itstride, int nitems, const bf16_t* XBC, const float* DT, const float* a_log,
;                                                  const float* state_in, bf16_t* MIX, float* s_ssm) {
;     ...
;             for (int t = 0; t < 4; ++t) {
;                 const float dt = dtv[t]; const float da = __expf(dt * A);
;                 const f32x4 Bt = (f32x4){bf2f(Bp[t].x & 0xffffu), bf2f(Bp[t].x >> 16), bf2f(Bp[t].y & 0xffffu), bf2f(Bp[t].y >> 16)} * dt;
;                 const f32x4 Ct = (f32x4){bf2f(Cp[t].x & 0xffffu), bf2f(Cp[t].x >> 16), bf2f(Cp[t].y & 0xffffu), bf2f(Cp[t].y >> 16)};
;                 float part[8];
;                 { const bool up8 = (nl & 8) != 0;
; #pragma unroll
;                   for (int i = 0; i < 8; ++i) {
;                     const float x0 = Xs[t * 512 + w * 64 + 32 * hh + 2 * i + half], x1 = Xs[t * 512 + w * 64 + 32 * hh + 2 * (i + 8) + half];
;                     st[i] = st[i] * da + Bt * x0; st[i + 8] = st[i + 8] * da + Bt * x1;
;                     const f32x4 q0 = Ct * st[i], q1 = Ct * st[i + 8];
;                     const float p0 = (q0.x + q0.y) + (q0.z + q0.w), p1 = (q1.x + q1.y) + (q1.z + q1.w);
;                     const float send = up8 ? p0 : p1, keep = up8 ? p1 : p0; part[i] = keep + __shfl_xor(send, 8); } }
;     ...
;                 BFLY(4); BFLY(2); BFLY(1);
;     ...
;                 yv[t] = part[0] + __shfl_xor(part[0], 16);
	v_lshlrev_b32_e32 v230, 16, v191
	v_and_b32_e32 v231, 0xffff0000, v191
	v_lshlrev_b32_e32 v200, 16, v140
	v_and_b32_e32 v201, 0xffff0000, v140
	v_lshlrev_b32_e32 v202, 16, v141
	v_and_b32_e32 v203, 0xffff0000, v141
	v_lshlrev_b32_e32 v204, 16, v142
	v_and_b32_e32 v205, 0xffff0000, v142
	v_lshlrev_b32_e32 v206, 16, v143
	v_and_b32_e32 v207, 0xffff0000, v143
	v_lshlrev_b32_e32 v216, 16, v156
	v_and_b32_e32 v217, 0xffff0000, v156
	v_lshlrev_b32_e32 v218, 16, v157
	v_and_b32_e32 v219, 0xffff0000, v157
	v_lshlrev_b32_e32 v220, 16, v158
	v_and_b32_e32 v221, 0xffff0000, v158
	v_lshlrev_b32_e32 v222, 16, v159
	v_and_b32_e32 v223, 0xffff0000, v159
	v_pk_mul_f32 v[200:201], v[200:201], v[208:209] op_sel:[0,1] op_sel_hi:[1,1]
	v_pk_mul_f32 v[202:203], v[202:203], v[208:209] op_sel:[0,1] op_sel_hi:[1,1]
	v_pk_mul_f32 v[204:205], v[204:205], v[208:209] op_sel:[0,1] op_sel_hi:[1,1]
	v_pk_mul_f32 v[206:207], v[206:207], v[208:209] op_sel:[0,1] op_sel_hi:[1,1]
	v_pk_mul_f32 v[64:65], v[64:65], v[128:129] op_sel:[0,1] op_sel_hi:[1,1]
	v_pk_mul_f32 v[66:67], v[66:67], v[128:129] op_sel:[0,1] op_sel_hi:[1,1]
	v_pk_fma_f32 v[64:65], v[200:201], v[224:225], v[64:65] op_sel:[0,0,0] op_sel_hi:[1,0,1]
	v_pk_fma_f32 v[66:67], v[202:203], v[224:225], v[66:67] op_sel:[0,0,0] op_sel_hi:[1,0,1]
	v_pk_mul_f32 v[68:69], v[68:69], v[128:129] op_sel:[0,1] op_sel_hi:[1,1]
	v_pk_mul_f32 v[70:71], v[70:71], v[128:129] op_sel:[0,1] op_sel_hi:[1,1]
	v_pk_fma_f32 v[68:69], v[204:205], v[224:225], v[68:69] op_sel:[0,0,0] op_sel_hi:[1,0,1]
	v_pk_fma_f32 v[70:71], v[206:207], v[224:225], v[70:71] op_sel:[0,0,0] op_sel_hi:[1,0,1]
	v_pk_mul_f32 v[240:241], v[216:217], v[64:65]
	v_pk_fma_f32 v[240:241], v[218:219], v[66:67], v[240:241]
	v_pk_fma_f32 v[240:241], v[220:221], v[68:69], v[240:241]
	v_pk_fma_f32 v[240:241], v[222:223], v[70:71], v[240:241]
	v_add_f32_e32 v232, v240, v241
	v_pk_mul_f32 v[72:73], v[72:73], v[128:129] op_sel:[0,1] op_sel_hi:[1,1]
	v_pk_mul_f32 v[74:75], v[74:75], v[128:129] op_sel:[0,1] op_sel_hi:[1,1]
	v_pk_fma_f32 v[72:73], v[200:201], v[224:225], v[72:73] op_sel:[0,1,0] op_sel_hi:[1,1,1]
	v_pk_fma_f32 v[74:75], v[202:203], v[224:225], v[74:75] op_sel:[0,1,0] op_sel_hi:[1,1,1]
	v_pk_mul_f32 v[76:77], v[76:77], v[128:129] op_sel:[0,1] op_sel_hi:[1,1]
	v_pk_mul_f32 v[78:79], v[78:79], v[128:129] op_sel:[0,1] op_sel_hi:[1,1]
	v_pk_fma_f32 v[76:77], v[204:205], v[224:225], v[76:77] op_sel:[0,1,0] op_sel_hi:[1,1,1]
	v_pk_fma_f32 v[78:79], v[206:207], v[224:225], v[78:79] op_sel:[0,1,0] op_sel_hi:[1,1,1]
	v_pk_mul_f32 v[242:243], v[216:217], v[72:73]
	v_pk_fma_f32 v[242:243], v[218:219], v[74:75], v[242:243]
	v_pk_fma_f32 v[242:243], v[220:221], v[76:77], v[242:243]
	v_pk_fma_f32 v[242:243], v[222:223], v[78:79], v[242:243]
	v_add_f32_e32 v233, v242, v243
	v_pk_mul_f32 v[80:81], v[80:81], v[128:129] op_sel:[0,1] op_sel_hi:[1,1]
	v_pk_mul_f32 v[82:83], v[82:83], v[128:129] op_sel:[0,1] op_sel_hi:[1,1]
	v_pk_fma_f32 v[80:81], v[200:201], v[226:227], v[80:81] op_sel:[0,0,0] op_sel_hi:[1,0,1]
	v_pk_fma_f32 v[82:83], v[202:203], v[226:227], v[82:83] op_sel:[0,0,0] op_sel_hi:[1,0,1]
	v_pk_mul_f32 v[84:85], v[84:85], v[128:129] op_sel:[0,1] op_sel_hi:[1,1]
	v_pk_mul_f32 v[86:87], v[86:87], v[128:129] op_sel:[0,1] op_sel_hi:[1,1]
	v_pk_fma_f32 v[84:85], v[204:205], v[226:227], v[84:85] op_sel:[0,0,0] op_sel_hi:[1,0,1]
	v_pk_fma_f32 v[86:87], v[206:207], v[226:227], v[86:87] op_sel:[0,0,0] op_sel_hi:[1,0,1]
	v_pk_mul_f32 v[244:245], v[216:217], v[80:81]
	v_pk_fma_f32 v[244:245], v[218:219], v[82:83], v[244:245]
	v_pk_fma_f32 v[244:245], v[220:221], v[84:85], v[244:245]
	v_pk_fma_f32 v[244:245], v[222:223], v[86:87], v[244:245]
	v_add_f32_e32 v234, v244, v245
	v_pk_mul_f32 v[88:89], v[88:89], v[128:129] op_sel:[0,1] op_sel_hi:[1,1]
	v_pk_mul_f32 v[90:91], v[90:91], v[128:129] op_sel:[0,1] op_sel_hi:[1,1]
	v_pk_fma_f32 v[88:89], v[200:201], v[226:227], v[88:89] op_sel:[0,1,0] op_sel_hi:[1,1,1]
	v_pk_fma_f32 v[90:91], v[202:203], v[226:227], v[90:91] op_sel:[0,1,0] op_sel_hi:[1,1,1]
	v_pk_mul_f32 v[92:93], v[92:93], v[128:129] op_sel:[0,1] op_sel_hi:[1,1]
	v_pk_mul_f32 v[94:95], v[94:95], v[128:129] op_sel:[0,1] op_sel_hi:[1,1]
	v_pk_fma_f32 v[92:93], v[204:205], v[226:227], v[92:93] op_sel:[0,1,0] op_sel_hi:[1,1,1]
	v_pk_fma_f32 v[94:95], v[206:207], v[226:227], v[94:95] op_sel:[0,1,0] op_sel_hi:[1,1,1]
	v_pk_mul_f32 v[246:247], v[216:217], v[88:89]
	v_pk_fma_f32 v[246:247], v[218:219], v[90:91], v[246:247]
	v_pk_fma_f32 v[246:247], v[220:221], v[92:93], v[246:247]
	v_pk_fma_f32 v[246:247], v[222:223], v[94:95], v[246:247]
	v_add_f32_e32 v235, v246, v247
	v_pk_mul_f32 v[96:97], v[96:97], v[128:129] op_sel:[0,1] op_sel_hi:[1,1]
	v_pk_mul_f32 v[98:99], v[98:99], v[128:129] op_sel:[0,1] op_sel_hi:[1,1]
	v_pk_fma_f32 v[96:97], v[200:201], v[228:229], v[96:97] op_sel:[0,0,0] op_sel_hi:[1,0,1]
	v_pk_fma_f32 v[98:99], v[202:203], v[228:229], v[98:99] op_sel:[0,0,0] op_sel_hi:[1,0,1]
	v_pk_mul_f32 v[100:101], v[100:101], v[128:129] op_sel:[0,1] op_sel_hi:[1,1]
	v_pk_mul_f32 v[102:103], v[102:103], v[128:129] op_sel:[0,1] op_sel_hi:[1,1]
	v_pk_fma_f32 v[100:101], v[204:205], v[228:229], v[100:101] op_sel:[0,0,0] op_sel_hi:[1,0,1]
	v_pk_fma_f32 v[102:103], v[206:207], v[228:229], v[102:103] op_sel:[0,0,0] op_sel_hi:[1,0,1]
	v_pk_mul_f32 v[240:241], v[216:217], v[96:97]
	v_pk_fma_f32 v[240:241], v[218:219], v[98:99], v[240:241]
	v_pk_fma_f32 v[240:241], v[220:221], v[100:101], v[240:241]
	v_pk_fma_f32 v[240:241], v[222:223], v[102:103], v[240:241]
	v_add_f32_e32 v236, v240, v241
	v_pk_mul_f32 v[104:105], v[104:105], v[128:129] op_sel:[0,1] op_sel_hi:[1,1]
; __device__ __forceinline__ float bf2f(unsigned h) { return __uint_as_float(h << 16); }
; __device__ __forceinline__ unsigned f2bf(float f) { unsigned u = __float_as_uint(f); return (u + 0x7fffu + ((u >> 16) & 1u)) >> 16; }
; #define BFLY(o) do { const bool up = (nl & (o)) != 0; _Pragma("unroll") for (int i = 0; i < (o); ++i) { \
;                     const float send = up ? part[i] : part[i + (o)]; const float keep = up ? part[i + (o)] : part[i]; part[i] = keep + __shfl_xor(send, (o)); } } while (0)
; __device__ __forceinline__ void ssd_sample_items(LAS unsigned char* lds, int it0, int itstride, int nitems, const bf16_t* XBC, const float* DT, const float* a_log,
;                                                  const float* state_in, bf16_t* MIX, float* s_ssm) {
;     ...
;             for (int t = 0; t < 4; ++t) {
;                 const float dt = dtv[t]; const float da = __expf(dt * A);
;                 const f32x4 Bt = (f32x4){bf2f(Bp[t].x & 0xffffu), bf2f(Bp[t].x >> 16), bf2f(Bp[t].y & 0xffffu), bf2f(Bp[t].y >> 16)} * dt;
;                 const f32x4 Ct = (f32x4){bf2f(Cp[t].x & 0xffffu), bf2f(Cp[t].x >> 16), bf2f(Cp[t].y & 0xffffu), bf2f(Cp[t].y >> 16)};
;                 float part[8];
;                 { const bool up8 = (nl & 8) != 0;
; #pragma unroll
;                   for (int i = 0; i < 8; ++i) {
;                     const float x0 = Xs[t * 512 + w * 64 + 32 * hh + 2 * i + half], x1 = Xs[t * 512 + w * 64 + 32 * hh + 2 * (i + 8) + half];
;                     st[i] = st[i] * da + Bt * x0; st[i + 8] = st[i + 8] * da + Bt * x1;
;                     const f32x4 q0 = Ct * st[i], q1 = Ct * st[i + 8];
;                     const float p0 = (q0.x + q0.y) + (q0.z + q0.w), p1 = (q1.x + q1.y) + (q1.z + q1.w);
;                     const float send = up8 ? p0 : p1, keep = up8 ? p1 : p0; part[i] = keep + __shfl_xor(send, 8); } }
;     ...
;                 BFLY(4); BFLY(2); BFLY(1);
;     ...
;                 yv[t] = part[0] + __shfl_xor(part[0], 16);
;             }
;             const int pout = 32 * hh + 2 * (nl & 15) + half;
;             if ((nl & 16) == 0) {
; #pragma unroll
;                 for (int t = 0; t < 4; ++t) MIX[(size_t)(MP + 4 * b + t) * DMIX + h * 64 + pout] = (bf16_t)f2bf(yv[t]);
;             }
	v_pk_mul_f32 v[106:107], v[106:107], v[128:129] op_sel:[0,1] op_sel_hi:[1,1]
	v_pk_fma_f32 v[104:105], v[200:201], v[228:229], v[104:105] op_sel:[0,1,0] op_sel_hi:[1,1,1]
	v_pk_fma_f32 v[106:107], v[202:203], v[228:229], v[106:107] op_sel:[0,1,0] op_sel_hi:[1,1,1]
	v_pk_mul_f32 v[108:109], v[108:109], v[128:129] op_sel:[0,1] op_sel_hi:[1,1]
	v_pk_mul_f32 v[110:111], v[110:111], v[128:129] op_sel:[0,1] op_sel_hi:[1,1]
	v_pk_fma_f32 v[108:109], v[204:205], v[228:229], v[108:109] op_sel:[0,1,0] op_sel_hi:[1,1,1]
	v_pk_fma_f32 v[110:111], v[206:207], v[228:229], v[110:111] op_sel:[0,1,0] op_sel_hi:[1,1,1]
	v_pk_mul_f32 v[242:243], v[216:217], v[104:105]
	v_pk_fma_f32 v[242:243], v[218:219], v[106:107], v[242:243]
	v_pk_fma_f32 v[242:243], v[220:221], v[108:109], v[242:243]
	v_pk_fma_f32 v[242:243], v[222:223], v[110:111], v[242:243]
	v_add_f32_e32 v237, v242, v243
	v_pk_mul_f32 v[112:113], v[112:113], v[128:129] op_sel:[0,1] op_sel_hi:[1,1]
	v_pk_mul_f32 v[114:115], v[114:115], v[128:129] op_sel:[0,1] op_sel_hi:[1,1]
	v_pk_fma_f32 v[112:113], v[200:201], v[230:231], v[112:113] op_sel:[0,0,0] op_sel_hi:[1,0,1]
	v_pk_fma_f32 v[114:115], v[202:203], v[230:231], v[114:115] op_sel:[0,0,0] op_sel_hi:[1,0,1]
	v_pk_mul_f32 v[116:117], v[116:117], v[128:129] op_sel:[0,1] op_sel_hi:[1,1]
	v_pk_mul_f32 v[118:119], v[118:119], v[128:129] op_sel:[0,1] op_sel_hi:[1,1]
	v_pk_fma_f32 v[116:117], v[204:205], v[230:231], v[116:117] op_sel:[0,0,0] op_sel_hi:[1,0,1]
	v_pk_fma_f32 v[118:119], v[206:207], v[230:231], v[118:119] op_sel:[0,0,0] op_sel_hi:[1,0,1]
	v_pk_mul_f32 v[244:245], v[216:217], v[112:113]
	v_pk_fma_f32 v[244:245], v[218:219], v[114:115], v[244:245]
	v_pk_fma_f32 v[244:245], v[220:221], v[116:117], v[244:245]
	v_pk_fma_f32 v[244:245], v[222:223], v[118:119], v[244:245]
	v_add_f32_e32 v238, v244, v245
	v_pk_mul_f32 v[120:121], v[120:121], v[128:129] op_sel:[0,1] op_sel_hi:[1,1]
	v_pk_mul_f32 v[122:123], v[122:123], v[128:129] op_sel:[0,1] op_sel_hi:[1,1]
	v_pk_fma_f32 v[120:121], v[200:201], v[230:231], v[120:121] op_sel:[0,1,0] op_sel_hi:[1,1,1]
	v_pk_fma_f32 v[122:123], v[202:203], v[230:231], v[122:123] op_sel:[0,1,0] op_sel_hi:[1,1,1]
	v_pk_mul_f32 v[124:125], v[124:125], v[128:129] op_sel:[0,1] op_sel_hi:[1,1]
	v_pk_mul_f32 v[126:127], v[126:127], v[128:129] op_sel:[0,1] op_sel_hi:[1,1]
	v_pk_fma_f32 v[124:125], v[204:205], v[230:231], v[124:125] op_sel:[0,1,0] op_sel_hi:[1,1,1]
	v_pk_fma_f32 v[126:127], v[206:207], v[230:231], v[126:127] op_sel:[0,1,0] op_sel_hi:[1,1,1]
	v_pk_mul_f32 v[246:247], v[216:217], v[120:121]
	v_pk_fma_f32 v[246:247], v[218:219], v[122:123], v[246:247]
	v_pk_fma_f32 v[246:247], v[220:221], v[124:125], v[246:247]
	v_pk_fma_f32 v[246:247], v[222:223], v[126:127], v[246:247]
	v_add_f32_e32 v239, v246, v247
	v_add_f32_dpp v232, v232, v232 row_mirror row_mask:0xf bank_mask:0x3
	v_add_f32_dpp v232, v236, v236 row_mirror row_mask:0xf bank_mask:0xc
	v_add_f32_dpp v233, v233, v233 row_mirror row_mask:0xf bank_mask:0x3
	v_add_f32_dpp v233, v237, v237 row_mirror row_mask:0xf bank_mask:0xc
	v_add_f32_dpp v234, v234, v234 row_mirror row_mask:0xf bank_mask:0x3
	v_add_f32_dpp v234, v238, v238 row_mirror row_mask:0xf bank_mask:0xc
	v_add_f32_dpp v235, v235, v235 row_mirror row_mask:0xf bank_mask:0x3
	v_add_f32_dpp v235, v239, v239 row_mirror row_mask:0xf bank_mask:0xc
	v_add_f32_dpp v232, v232, v232 row_half_mirror row_mask:0xf bank_mask:0x5
	v_add_f32_dpp v232, v234, v234 row_half_mirror row_mask:0xf bank_mask:0xa
	v_add_f32_dpp v233, v233, v233 row_half_mirror row_mask:0xf bank_mask:0x5
	v_add_f32_dpp v233, v235, v235 row_half_mirror row_mask:0xf bank_mask:0xa
	v_add_f32_dpp v248, v232, v232 quad_perm:[2,3,0,1] row_mask:0xf bank_mask:0xf
	s_nop 0
	v_add_f32_dpp v249, v233, v233 quad_perm:[2,3,0,1] row_mask:0xf bank_mask:0xf
	v_cndmask_b32_e64 v232, v248, v249, s[68:69]
	s_nop 1
	v_add_f32_dpp v233, v232, v232 quad_perm:[1,0,3,2] row_mask:0xf bank_mask:0xf
	v_cvt_pk_bf16_f32 v214, v233, v233
	s_mov_b64 exec, s[38:39]
	global_store_short v213, v214, s[6:7] offset:64
	s_mov_b64 exec, -1
	v_lshlrev_b32_e32 v224, 16, v192
	v_and_b32_e32 v225, 0xffff0000, v192
	v_lshlrev_b32_e32 v226, 16, v193
	v_and_b32_e32 v227, 0xffff0000, v193
	v_lshlrev_b32_e32 v228, 16, v194
	v_and_b32_e32 v229, 0xffff0000, v194
	v_lshlrev_b32_e32 v230, 16, v195
	v_and_b32_e32 v231, 0xffff0000, v195
	v_lshlrev_b32_e32 v200, 16, v144
	v_and_b32_e32 v201, 0xffff0000, v144
	v_lshlrev_b32_e32 v202, 16, v145
	v_and_b32_e32 v203, 0xffff0000, v145
	v_lshlrev_b32_e32 v204, 16, v146
	v_and_b32_e32 v205, 0xffff0000, v146
	v_lshlrev_b32_e32 v206, 16, v147
	v_and_b32_e32 v207, 0xffff0000, v147
	v_lshlrev_b32_e32 v216, 16, v160
	v_and_b32_e32 v217, 0xffff0000, v160
	v_lshlrev_b32_e32 v218, 16, v161
	v_and_b32_e32 v219, 0xffff0000, v161
	v_lshlrev_b32_e32 v220, 16, v162
	v_and_b32_e32 v221, 0xffff0000, v162
	v_lshlrev_b32_e32 v222, 16, v163
	v_and_b32_e32 v223, 0xffff0000, v163
	v_pk_mul_f32 v[200:201], v[200:201], v[210:211] op_sel:[0,0] op_sel_hi:[1,0]
	v_pk_mul_f32 v[202:203], v[202:203], v[210:211] op_sel:[0,0] op_sel_hi:[1,0]
	v_pk_mul_f32 v[204:205], v[204:205], v[210:211] op_sel:[0,0] op_sel_hi:[1,0]
	v_pk_mul_f32 v[206:207], v[206:207], v[210:211] op_sel:[0,0] op_sel_hi:[1,0]
	v_pk_mul_f32 v[64:65], v[64:65], v[130:131] op_sel:[0,0] op_sel_hi:[1,0]
	v_pk_mul_f32 v[66:67], v[66:67], v[130:131] op_sel:[0,0] op_sel_hi:[1,0]
	v_pk_fma_f32 v[64:65], v[200:201], v[224:225], v[64:65] op_sel:[0,0,0] op_sel_hi:[1,0,1]
	v_pk_fma_f32 v[66:67], v[202:203], v[224:225], v[66:67] op_sel:[0,0,0] op_sel_hi:[1,0,1]
	v_pk_mul_f32 v[68:69], v[68:69], v[130:131] op_sel:[0,0] op_sel_hi:[1,0]
; __device__ __forceinline__ float bf2f(unsigned h) { return __uint_as_float(h << 16); }
; __device__ __forceinline__ void ssd_sample_items(LAS unsigned char* lds, int it0, int itstride, int nitems, const bf16_t* XBC, const float* DT, const float* a_log,
;                                                  const float* state_in, bf16_t* MIX, float* s_ssm) {
;     ...
;             for (int t = 0; t < 4; ++t) {
;                 const float dt = dtv[t]; const float da = __expf(dt * A);
;                 const f32x4 Bt = (f32x4){bf2f(Bp[t].x & 0xffffu), bf2f(Bp[t].x >> 16), bf2f(Bp[t].y & 0xffffu), bf2f(Bp[t].y >> 16)} * dt;
;                 const f32x4 Ct = (f32x4){bf2f(Cp[t].x & 0xffffu), bf2f(Cp[t].x >> 16), bf2f(Cp[t].y & 0xffffu), bf2f(Cp[t].y >> 16)};
;                 float part[8];
;                 { const bool up8 = (nl & 8) != 0;
; #pragma unroll
;                   for (int i = 0; i < 8; ++i) {
;                     const float x0 = Xs[t * 512 + w * 64 + 32 * hh + 2 * i + half], x1 = Xs[t * 512 + w * 64 + 32 * hh + 2 * (i + 8) + half];
;                     st[i] = st[i] * da + Bt * x0; st[i + 8] = st[i + 8] * da + Bt * x1;
;                     const f32x4 q0 = Ct * st[i], q1 = Ct * st[i + 8];
;                     const float p0 = (q0.x + q0.y) + (q0.z + q0.w), p1 = (q1.x + q1.y) + (q1.z + q1.w);
;                     const float send = up8 ? p0 : p1, keep = up8 ? p1 : p0; part[i] = keep + __shfl_xor(send, 8); } }
	v_pk_mul_f32 v[70:71], v[70:71], v[130:131] op_sel:[0,0] op_sel_hi:[1,0]
	v_pk_fma_f32 v[68:69], v[204:205], v[224:225], v[68:69] op_sel:[0,0,0] op_sel_hi:[1,0,1]
	v_pk_fma_f32 v[70:71], v[206:207], v[224:225], v[70:71] op_sel:[0,0,0] op_sel_hi:[1,0,1]
	v_pk_mul_f32 v[240:241], v[216:217], v[64:65]
	v_pk_fma_f32 v[240:241], v[218:219], v[66:67], v[240:241]
	v_pk_fma_f32 v[240:241], v[220:221], v[68:69], v[240:241]
	v_pk_fma_f32 v[240:241], v[222:223], v[70:71], v[240:241]
	v_add_f32_e32 v232, v240, v241
	v_pk_mul_f32 v[72:73], v[72:73], v[130:131] op_sel:[0,0] op_sel_hi:[1,0]
	v_pk_mul_f32 v[74:75], v[74:75], v[130:131] op_sel:[0,0] op_sel_hi:[1,0]
	v_pk_fma_f32 v[72:73], v[200:201], v[224:225], v[72:73] op_sel:[0,1,0] op_sel_hi:[1,1,1]
	v_pk_fma_f32 v[74:75], v[202:203], v[224:225], v[74:75] op_sel:[0,1,0] op_sel_hi:[1,1,1]
	v_pk_mul_f32 v[76:77], v[76:77], v[130:131] op_sel:[0,0] op_sel_hi:[1,0]
	v_pk_mul_f32 v[78:79], v[78:79], v[130:131] op_sel:[0,0] op_sel_hi:[1,0]
	v_pk_fma_f32 v[76:77], v[204:205], v[224:225], v[76:77] op_sel:[0,1,0] op_sel_hi:[1,1,1]
	v_pk_fma_f32 v[78:79], v[206:207], v[224:225], v[78:79] op_sel:[0,1,0] op_sel_hi:[1,1,1]
	v_pk_mul_f32 v[242:243], v[216:217], v[72:73]
	v_pk_fma_f32 v[242:243], v[218:219], v[74:75], v[242:243]
	v_pk_fma_f32 v[242:243], v[220:221], v[76:77], v[242:243]
	v_pk_fma_f32 v[242:243], v[222:223], v[78:79], v[242:243]
	v_add_f32_e32 v233, v242, v243
	v_pk_mul_f32 v[80:81], v[80:81], v[130:131] op_sel:[0,0] op_sel_hi:[1,0]
	v_pk_mul_f32 v[82:83], v[82:83], v[130:131] op_sel:[0,0] op_sel_hi:[1,0]
	v_pk_fma_f32 v[80:81], v[200:201], v[226:227], v[80:81] op_sel:[0,0,0] op_sel_hi:[1,0,1]
	v_pk_fma_f32 v[82:83], v[202:203], v[226:227], v[82:83] op_sel:[0,0,0] op_sel_hi:[1,0,1]
	v_pk_mul_f32 v[84:85], v[84:85], v[130:131] op_sel:[0,0] op_sel_hi:[1,0]
	v_pk_mul_f32 v[86:87], v[86:87], v[130:131] op_sel:[0,0] op_sel_hi:[1,0]
	v_pk_fma_f32 v[84:85], v[204:205], v[226:227], v[84:85] op_sel:[0,0,0] op_sel_hi:[1,0,1]
	v_pk_fma_f32 v[86:87], v[206:207], v[226:227], v[86:87] op_sel:[0,0,0] op_sel_hi:[1,0,1]
	v_pk_mul_f32 v[244:245], v[216:217], v[80:81]
	v_pk_fma_f32 v[244:245], v[218:219], v[82:83], v[244:245]
	v_pk_fma_f32 v[244:245], v[220:221], v[84:85], v[244:245]
	v_pk_fma_f32 v[244:245], v[222:223], v[86:87], v[244:245]
	v_add_f32_e32 v234, v244, v245
	v_pk_mul_f32 v[88:89], v[88:89], v[130:131] op_sel:[0,0] op_sel_hi:[1,0]
	v_pk_mul_f32 v[90:91], v[90:91], v[130:131] op_sel:[0,0] op_sel_hi:[1,0]
	v_pk_fma_f32 v[88:89], v[200:201], v[226:227], v[88:89] op_sel:[0,1,0] op_sel_hi:[1,1,1]
	v_pk_fma_f32 v[90:91], v[202:203], v[226:227], v[90:91] op_sel:[0,1,0] op_sel_hi:[1,1,1]
	v_pk_mul_f32 v[92:93], v[92:93], v[130:131] op_sel:[0,0] op_sel_hi:[1,0]
	v_pk_mul_f32 v[94:95], v[94:95], v[130:131] op_sel:[0,0] op_sel_hi:[1,0]
	v_pk_fma_f32 v[92:93], v[204:205], v[226:227], v[92:93] op_sel:[0,1,0] op_sel_hi:[1,1,1]
	v_pk_fma_f32 v[94:95], v[206:207], v[226:227], v[94:95] op_sel:[0,1,0] op_sel_hi:[1,1,1]
	v_pk_mul_f32 v[246:247], v[216:217], v[88:89]
	v_pk_fma_f32 v[246:247], v[218:219], v[90:91], v[246:247]
	v_pk_fma_f32 v[246:247], v[220:221], v[92:93], v[246:247]
	v_pk_fma_f32 v[246:247], v[222:223], v[94:95], v[246:247]
	v_add_f32_e32 v235, v246, v247
	v_pk_mul_f32 v[96:97], v[96:97], v[130:131] op_sel:[0,0] op_sel_hi:[1,0]
	v_pk_mul_f32 v[98:99], v[98:99], v[130:131] op_sel:[0,0] op_sel_hi:[1,0]
	v_pk_fma_f32 v[96:97], v[200:201], v[228:229], v[96:97] op_sel:[0,0,0] op_sel_hi:[1,0,1]
	v_pk_fma_f32 v[98:99], v[202:203], v[228:229], v[98:99] op_sel:[0,0,0] op_sel_hi:[1,0,1]
	v_pk_mul_f32 v[100:101], v[100:101], v[130:131] op_sel:[0,0] op_sel_hi:[1,0]
	v_pk_mul_f32 v[102:103], v[102:103], v[130:131] op_sel:[0,0] op_sel_hi:[1,0]
	v_pk_fma_f32 v[100:101], v[204:205], v[228:229], v[100:101] op_sel:[0,0,0] op_sel_hi:[1,0,1]
	v_pk_fma_f32 v[102:103], v[206:207], v[228:229], v[102:103] op_sel:[0,0,0] op_sel_hi:[1,0,1]
	v_pk_mul_f32 v[240:241], v[216:217], v[96:97]
	v_pk_fma_f32 v[240:241], v[218:219], v[98:99], v[240:241]
	v_pk_fma_f32 v[240:241], v[220:221], v[100:101], v[240:241]
	v_pk_fma_f32 v[240:241], v[222:223], v[102:103], v[240:241]
	v_add_f32_e32 v236, v240, v241
	v_pk_mul_f32 v[104:105], v[104:105], v[130:131] op_sel:[0,0] op_sel_hi:[1,0]
	v_pk_mul_f32 v[106:107], v[106:107], v[130:131] op_sel:[0,0] op_sel_hi:[1,0]
	v_pk_fma_f32 v[104:105], v[200:201], v[228:229], v[104:105] op_sel:[0,1,0] op_sel_hi:[1,1,1]
	v_pk_fma_f32 v[106:107], v[202:203], v[228:229], v[106:107] op_sel:[0,1,0] op_sel_hi:[1,1,1]
	v_pk_mul_f32 v[108:109], v[108:109], v[130:131] op_sel:[0,0] op_sel_hi:[1,0]
	v_pk_mul_f32 v[110:111], v[110:111], v[130:131] op_sel:[0,0] op_sel_hi:[1,0]
	v_pk_fma_f32 v[108:109], v[204:205], v[228:229], v[108:109] op_sel:[0,1,0] op_sel_hi:[1,1,1]
	v_pk_fma_f32 v[110:111], v[206:207], v[228:229], v[110:111] op_sel:[0,1,0] op_sel_hi:[1,1,1]
	v_pk_mul_f32 v[242:243], v[216:217], v[104:105]
	v_pk_fma_f32 v[242:243], v[218:219], v[106:107], v[242:243]
	v_pk_fma_f32 v[242:243], v[220:221], v[108:109], v[242:243]
	v_pk_fma_f32 v[242:243], v[222:223], v[110:111], v[242:243]
	v_add_f32_e32 v237, v242, v243
	v_pk_mul_f32 v[112:113], v[112:113], v[130:131] op_sel:[0,0] op_sel_hi:[1,0]
	v_pk_mul_f32 v[114:115], v[114:115], v[130:131] op_sel:[0,0] op_sel_hi:[1,0]
	v_pk_fma_f32 v[112:113], v[200:201], v[230:231], v[112:113] op_sel:[0,0,0] op_sel_hi:[1,0,1]
	v_pk_fma_f32 v[114:115], v[202:203], v[230:231], v[114:115] op_sel:[0,0,0] op_sel_hi:[1,0,1]
	v_pk_mul_f32 v[116:117], v[116:117], v[130:131] op_sel:[0,0] op_sel_hi:[1,0]
	v_pk_mul_f32 v[118:119], v[118:119], v[130:131] op_sel:[0,0] op_sel_hi:[1,0]
; __device__ __forceinline__ float bf2f(unsigned h) { return __uint_as_float(h << 16); }
; __device__ __forceinline__ unsigned f2bf(float f) { unsigned u = __float_as_uint(f); return (u + 0x7fffu + ((u >> 16) & 1u)) >> 16; }
; #define BFLY(o) do { const bool up = (nl & (o)) != 0; _Pragma("unroll") for (int i = 0; i < (o); ++i) { \
;                     const float send = up ? part[i] : part[i + (o)]; const float keep = up ? part[i + (o)] : part[i]; part[i] = keep + __shfl_xor(send, (o)); } } while (0)
; __device__ __forceinline__ void ssd_sample_items(LAS unsigned char* lds, int it0, int itstride, int nitems, const bf16_t* XBC, const float* DT, const float* a_log,
;                                                  const float* state_in, bf16_t* MIX, float* s_ssm) {
;     ...
;             for (int t = 0; t < 4; ++t) {
;                 const float dt = dtv[t]; const float da = __expf(dt * A);
;                 const f32x4 Bt = (f32x4){bf2f(Bp[t].x & 0xffffu), bf2f(Bp[t].x >> 16), bf2f(Bp[t].y & 0xffffu), bf2f(Bp[t].y >> 16)} * dt;
;                 const f32x4 Ct = (f32x4){bf2f(Cp[t].x & 0xffffu), bf2f(Cp[t].x >> 16), bf2f(Cp[t].y & 0xffffu), bf2f(Cp[t].y >> 16)};
;                 float part[8];
;                 { const bool up8 = (nl & 8) != 0;
; #pragma unroll
;                   for (int i = 0; i < 8; ++i) {
;                     const float x0 = Xs[t * 512 + w * 64 + 32 * hh + 2 * i + half], x1 = Xs[t * 512 + w * 64 + 32 * hh + 2 * (i + 8) + half];
;                     st[i] = st[i] * da + Bt * x0; st[i + 8] = st[i + 8] * da + Bt * x1;
;                     const f32x4 q0 = Ct * st[i], q1 = Ct * st[i + 8];
;                     const float p0 = (q0.x + q0.y) + (q0.z + q0.w), p1 = (q1.x + q1.y) + (q1.z + q1.w);
;                     const float send = up8 ? p0 : p1, keep = up8 ? p1 : p0; part[i] = keep + __shfl_xor(send, 8); } }
;     ...
;                 BFLY(4); BFLY(2); BFLY(1);
;     ...
;                 yv[t] = part[0] + __shfl_xor(part[0], 16);
;             }
;             const int pout = 32 * hh + 2 * (nl & 15) + half;
;             if ((nl & 16) == 0) {
; #pragma unroll
;                 for (int t = 0; t < 4; ++t) MIX[(size_t)(MP + 4 * b + t) * DMIX + h * 64 + pout] = (bf16_t)f2bf(yv[t]);
;             }
	v_pk_fma_f32 v[116:117], v[204:205], v[230:231], v[116:117] op_sel:[0,0,0] op_sel_hi:[1,0,1]
	v_pk_fma_f32 v[118:119], v[206:207], v[230:231], v[118:119] op_sel:[0,0,0] op_sel_hi:[1,0,1]
	v_pk_mul_f32 v[244:245], v[216:217], v[112:113]
	v_pk_fma_f32 v[244:245], v[218:219], v[114:115], v[244:245]
	v_pk_fma_f32 v[244:245], v[220:221], v[116:117], v[244:245]
	v_pk_fma_f32 v[244:245], v[222:223], v[118:119], v[244:245]
	v_add_f32_e32 v238, v244, v245
	v_pk_mul_f32 v[120:121], v[120:121], v[130:131] op_sel:[0,0] op_sel_hi:[1,0]
	v_pk_mul_f32 v[122:123], v[122:123], v[130:131] op_sel:[0,0] op_sel_hi:[1,0]
	v_pk_fma_f32 v[120:121], v[200:201], v[230:231], v[120:121] op_sel:[0,1,0] op_sel_hi:[1,1,1]
	v_pk_fma_f32 v[122:123], v[202:203], v[230:231], v[122:123] op_sel:[0,1,0] op_sel_hi:[1,1,1]
	v_pk_mul_f32 v[124:125], v[124:125], v[130:131] op_sel:[0,0] op_sel_hi:[1,0]
	v_pk_mul_f32 v[126:127], v[126:127], v[130:131] op_sel:[0,0] op_sel_hi:[1,0]
	v_pk_fma_f32 v[124:125], v[204:205], v[230:231], v[124:125] op_sel:[0,1,0] op_sel_hi:[1,1,1]
	v_pk_fma_f32 v[126:127], v[206:207], v[230:231], v[126:127] op_sel:[0,1,0] op_sel_hi:[1,1,1]
	v_pk_mul_f32 v[246:247], v[216:217], v[120:121]
	v_pk_fma_f32 v[246:247], v[218:219], v[122:123], v[246:247]
	v_pk_fma_f32 v[246:247], v[220:221], v[124:125], v[246:247]
	v_pk_fma_f32 v[246:247], v[222:223], v[126:127], v[246:247]
	v_add_f32_e32 v239, v246, v247
	v_add_f32_dpp v232, v232, v232 row_mirror row_mask:0xf bank_mask:0x3
	v_add_f32_dpp v232, v236, v236 row_mirror row_mask:0xf bank_mask:0xc
	v_add_f32_dpp v233, v233, v233 row_mirror row_mask:0xf bank_mask:0x3
	v_add_f32_dpp v233, v237, v237 row_mirror row_mask:0xf bank_mask:0xc
	v_add_f32_dpp v234, v234, v234 row_mirror row_mask:0xf bank_mask:0x3
	v_add_f32_dpp v234, v238, v238 row_mirror row_mask:0xf bank_mask:0xc
	v_add_f32_dpp v235, v235, v235 row_mirror row_mask:0xf bank_mask:0x3
	v_add_f32_dpp v235, v239, v239 row_mirror row_mask:0xf bank_mask:0xc
	v_add_f32_dpp v232, v232, v232 row_half_mirror row_mask:0xf bank_mask:0x5
	v_add_f32_dpp v232, v234, v234 row_half_mirror row_mask:0xf bank_mask:0xa
	v_add_f32_dpp v233, v233, v233 row_half_mirror row_mask:0xf bank_mask:0x5
	v_add_f32_dpp v233, v235, v235 row_half_mirror row_mask:0xf bank_mask:0xa
	v_add_f32_dpp v248, v232, v232 quad_perm:[2,3,0,1] row_mask:0xf bank_mask:0xf
	s_nop 0
	v_add_f32_dpp v249, v233, v233 quad_perm:[2,3,0,1] row_mask:0xf bank_mask:0xf
	v_cndmask_b32_e64 v232, v248, v249, s[68:69]
	s_nop 1
	v_add_f32_dpp v233, v232, v232 quad_perm:[1,0,3,2] row_mask:0xf bank_mask:0xf
	v_cvt_pk_bf16_f32 v214, v233, v233
	s_mov_b64 exec, s[38:39]
	global_store_short v213, v214, s[8:9] offset:64
	s_mov_b64 exec, -1
	v_lshlrev_b32_e32 v224, 16, v196
	v_and_b32_e32 v225, 0xffff0000, v196
	v_lshlrev_b32_e32 v226, 16, v197
	v_and_b32_e32 v227, 0xffff0000, v197
	v_lshlrev_b32_e32 v228, 16, v198
	v_and_b32_e32 v229, 0xffff0000, v198
	v_lshlrev_b32_e32 v230, 16, v199
	v_and_b32_e32 v231, 0xffff0000, v199
	v_lshlrev_b32_e32 v200, 16, v148
	v_and_b32_e32 v201, 0xffff0000, v148
	v_lshlrev_b32_e32 v202, 16, v149
	v_and_b32_e32 v203, 0xffff0000, v149
	v_lshlrev_b32_e32 v204, 16, v150
	v_and_b32_e32 v205, 0xffff0000, v150
	v_lshlrev_b32_e32 v206, 16, v151
	v_and_b32_e32 v207, 0xffff0000, v151
	v_lshlrev_b32_e32 v216, 16, v164
	v_and_b32_e32 v217, 0xffff0000, v164
	v_lshlrev_b32_e32 v218, 16, v165
	v_and_b32_e32 v219, 0xffff0000, v165
	v_lshlrev_b32_e32 v220, 16, v166
	v_and_b32_e32 v221, 0xffff0000, v166
	v_lshlrev_b32_e32 v222, 16, v167
	v_and_b32_e32 v223, 0xffff0000, v167
	v_pk_mul_f32 v[200:201], v[200:201], v[210:211] op_sel:[0,1] op_sel_hi:[1,1]
	v_pk_mul_f32 v[202:203], v[202:203], v[210:211] op_sel:[0,1] op_sel_hi:[1,1]
	v_pk_mul_f32 v[204:205], v[204:205], v[210:211] op_sel:[0,1] op_sel_hi:[1,1]
	v_pk_mul_f32 v[206:207], v[206:207], v[210:211] op_sel:[0,1] op_sel_hi:[1,1]
	v_pk_mul_f32 v[64:65], v[64:65], v[130:131] op_sel:[0,1] op_sel_hi:[1,1]
	v_pk_mul_f32 v[66:67], v[66:67], v[130:131] op_sel:[0,1] op_sel_hi:[1,1]
	v_pk_fma_f32 v[64:65], v[200:201], v[224:225], v[64:65] op_sel:[0,0,0] op_sel_hi:[1,0,1]
	v_pk_fma_f32 v[66:67], v[202:203], v[224:225], v[66:67] op_sel:[0,0,0] op_sel_hi:[1,0,1]
	v_pk_mul_f32 v[68:69], v[68:69], v[130:131] op_sel:[0,1] op_sel_hi:[1,1]
	v_pk_mul_f32 v[70:71], v[70:71], v[130:131] op_sel:[0,1] op_sel_hi:[1,1]
	v_pk_fma_f32 v[68:69], v[204:205], v[224:225], v[68:69] op_sel:[0,0,0] op_sel_hi:[1,0,1]
	v_pk_fma_f32 v[70:71], v[206:207], v[224:225], v[70:71] op_sel:[0,0,0] op_sel_hi:[1,0,1]
	v_pk_mul_f32 v[240:241], v[216:217], v[64:65]
	v_pk_fma_f32 v[240:241], v[218:219], v[66:67], v[240:241]
	v_pk_fma_f32 v[240:241], v[220:221], v[68:69], v[240:241]
	v_pk_fma_f32 v[240:241], v[222:223], v[70:71], v[240:241]
	v_add_f32_e32 v232, v240, v241
	v_pk_mul_f32 v[72:73], v[72:73], v[130:131] op_sel:[0,1] op_sel_hi:[1,1]
	v_pk_mul_f32 v[74:75], v[74:75], v[130:131] op_sel:[0,1] op_sel_hi:[1,1]
	v_pk_fma_f32 v[72:73], v[200:201], v[224:225], v[72:73] op_sel:[0,1,0] op_sel_hi:[1,1,1]
	v_pk_fma_f32 v[74:75], v[202:203], v[224:225], v[74:75] op_sel:[0,1,0] op_sel_hi:[1,1,1]
	v_pk_mul_f32 v[76:77], v[76:77], v[130:131] op_sel:[0,1] op_sel_hi:[1,1]
	v_pk_mul_f32 v[78:79], v[78:79], v[130:131] op_sel:[0,1] op_sel_hi:[1,1]
	v_pk_fma_f32 v[76:77], v[204:205], v[224:225], v[76:77] op_sel:[0,1,0] op_sel_hi:[1,1,1]
	v_pk_fma_f32 v[78:79], v[206:207], v[224:225], v[78:79] op_sel:[0,1,0] op_sel_hi:[1,1,1]
	v_pk_mul_f32 v[242:243], v[216:217], v[72:73]
	v_pk_fma_f32 v[242:243], v[218:219], v[74:75], v[242:243]
	v_pk_fma_f32 v[242:243], v[220:221], v[76:77], v[242:243]
	v_pk_fma_f32 v[242:243], v[222:223], v[78:79], v[242:243]
; __device__ __forceinline__ float bf2f(unsigned h) { return __uint_as_float(h << 16); }
; __device__ __forceinline__ void ssd_sample_items(LAS unsigned char* lds, int it0, int itstride, int nitems, const bf16_t* XBC, const float* DT, const float* a_log,
;                                                  const float* state_in, bf16_t* MIX, float* s_ssm) {
;     ...
;             for (int t = 0; t < 4; ++t) {
;                 const float dt = dtv[t]; const float da = __expf(dt * A);
;                 const f32x4 Bt = (f32x4){bf2f(Bp[t].x & 0xffffu), bf2f(Bp[t].x >> 16), bf2f(Bp[t].y & 0xffffu), bf2f(Bp[t].y >> 16)} * dt;
;                 const f32x4 Ct = (f32x4){bf2f(Cp[t].x & 0xffffu), bf2f(Cp[t].x >> 16), bf2f(Cp[t].y & 0xffffu), bf2f(Cp[t].y >> 16)};
;                 float part[8];
;                 { const bool up8 = (nl & 8) != 0;
; #pragma unroll
;                   for (int i = 0; i < 8; ++i) {
;                     const float x0 = Xs[t * 512 + w * 64 + 32 * hh + 2 * i + half], x1 = Xs[t * 512 + w * 64 + 32 * hh + 2 * (i + 8) + half];
;                     st[i] = st[i] * da + Bt * x0; st[i + 8] = st[i + 8] * da + Bt * x1;
;                     const f32x4 q0 = Ct * st[i], q1 = Ct * st[i + 8];
;                     const float p0 = (q0.x + q0.y) + (q0.z + q0.w), p1 = (q1.x + q1.y) + (q1.z + q1.w);
;                     const float send = up8 ? p0 : p1, keep = up8 ? p1 : p0; part[i] = keep + __shfl_xor(send, 8); } }
	v_add_f32_e32 v233, v242, v243
	v_pk_mul_f32 v[80:81], v[80:81], v[130:131] op_sel:[0,1] op_sel_hi:[1,1]
	v_pk_mul_f32 v[82:83], v[82:83], v[130:131] op_sel:[0,1] op_sel_hi:[1,1]
	v_pk_fma_f32 v[80:81], v[200:201], v[226:227], v[80:81] op_sel:[0,0,0] op_sel_hi:[1,0,1]
	v_pk_fma_f32 v[82:83], v[202:203], v[226:227], v[82:83] op_sel:[0,0,0] op_sel_hi:[1,0,1]
	v_pk_mul_f32 v[84:85], v[84:85], v[130:131] op_sel:[0,1] op_sel_hi:[1,1]
	v_pk_mul_f32 v[86:87], v[86:87], v[130:131] op_sel:[0,1] op_sel_hi:[1,1]
	v_pk_fma_f32 v[84:85], v[204:205], v[226:227], v[84:85] op_sel:[0,0,0] op_sel_hi:[1,0,1]
	v_pk_fma_f32 v[86:87], v[206:207], v[226:227], v[86:87] op_sel:[0,0,0] op_sel_hi:[1,0,1]
	v_pk_mul_f32 v[244:245], v[216:217], v[80:81]
	v_pk_fma_f32 v[244:245], v[218:219], v[82:83], v[244:245]
	v_pk_fma_f32 v[244:245], v[220:221], v[84:85], v[244:245]
	v_pk_fma_f32 v[244:245], v[222:223], v[86:87], v[244:245]
	v_add_f32_e32 v234, v244, v245
	v_pk_mul_f32 v[88:89], v[88:89], v[130:131] op_sel:[0,1] op_sel_hi:[1,1]
	v_pk_mul_f32 v[90:91], v[90:91], v[130:131] op_sel:[0,1] op_sel_hi:[1,1]
	v_pk_fma_f32 v[88:89], v[200:201], v[226:227], v[88:89] op_sel:[0,1,0] op_sel_hi:[1,1,1]
	v_pk_fma_f32 v[90:91], v[202:203], v[226:227], v[90:91] op_sel:[0,1,0] op_sel_hi:[1,1,1]
	v_pk_mul_f32 v[92:93], v[92:93], v[130:131] op_sel:[0,1] op_sel_hi:[1,1]
	v_pk_mul_f32 v[94:95], v[94:95], v[130:131] op_sel:[0,1] op_sel_hi:[1,1]
	v_pk_fma_f32 v[92:93], v[204:205], v[226:227], v[92:93] op_sel:[0,1,0] op_sel_hi:[1,1,1]
	v_pk_fma_f32 v[94:95], v[206:207], v[226:227], v[94:95] op_sel:[0,1,0] op_sel_hi:[1,1,1]
	v_pk_mul_f32 v[246:247], v[216:217], v[88:89]
	v_pk_fma_f32 v[246:247], v[218:219], v[90:91], v[246:247]
	v_pk_fma_f32 v[246:247], v[220:221], v[92:93], v[246:247]
	v_pk_fma_f32 v[246:247], v[222:223], v[94:95], v[246:247]
	v_add_f32_e32 v235, v246, v247
	v_pk_mul_f32 v[96:97], v[96:97], v[130:131] op_sel:[0,1] op_sel_hi:[1,1]
	v_pk_mul_f32 v[98:99], v[98:99], v[130:131] op_sel:[0,1] op_sel_hi:[1,1]
	v_pk_fma_f32 v[96:97], v[200:201], v[228:229], v[96:97] op_sel:[0,0,0] op_sel_hi:[1,0,1]
	v_pk_fma_f32 v[98:99], v[202:203], v[228:229], v[98:99] op_sel:[0,0,0] op_sel_hi:[1,0,1]
	v_pk_mul_f32 v[100:101], v[100:101], v[130:131] op_sel:[0,1] op_sel_hi:[1,1]
	v_pk_mul_f32 v[102:103], v[102:103], v[130:131] op_sel:[0,1] op_sel_hi:[1,1]
	v_pk_fma_f32 v[100:101], v[204:205], v[228:229], v[100:101] op_sel:[0,0,0] op_sel_hi:[1,0,1]
	v_pk_fma_f32 v[102:103], v[206:207], v[228:229], v[102:103] op_sel:[0,0,0] op_sel_hi:[1,0,1]
	v_pk_mul_f32 v[240:241], v[216:217], v[96:97]
	v_pk_fma_f32 v[240:241], v[218:219], v[98:99], v[240:241]
	v_pk_fma_f32 v[240:241], v[220:221], v[100:101], v[240:241]
	v_pk_fma_f32 v[240:241], v[222:223], v[102:103], v[240:241]
	v_add_f32_e32 v236, v240, v241
	v_pk_mul_f32 v[104:105], v[104:105], v[130:131] op_sel:[0,1] op_sel_hi:[1,1]
	v_pk_mul_f32 v[106:107], v[106:107], v[130:131] op_sel:[0,1] op_sel_hi:[1,1]
	v_pk_fma_f32 v[104:105], v[200:201], v[228:229], v[104:105] op_sel:[0,1,0] op_sel_hi:[1,1,1]
	v_pk_fma_f32 v[106:107], v[202:203], v[228:229], v[106:107] op_sel:[0,1,0] op_sel_hi:[1,1,1]
	v_pk_mul_f32 v[108:109], v[108:109], v[130:131] op_sel:[0,1] op_sel_hi:[1,1]
	v_pk_mul_f32 v[110:111], v[110:111], v[130:131] op_sel:[0,1] op_sel_hi:[1,1]
	v_pk_fma_f32 v[108:109], v[204:205], v[228:229], v[108:109] op_sel:[0,1,0] op_sel_hi:[1,1,1]
	v_pk_fma_f32 v[110:111], v[206:207], v[228:229], v[110:111] op_sel:[0,1,0] op_sel_hi:[1,1,1]
	v_pk_mul_f32 v[242:243], v[216:217], v[104:105]
	v_pk_fma_f32 v[242:243], v[218:219], v[106:107], v[242:243]
	v_pk_fma_f32 v[242:243], v[220:221], v[108:109], v[242:243]
	v_pk_fma_f32 v[242:243], v[222:223], v[110:111], v[242:243]
	v_add_f32_e32 v237, v242, v243
	v_pk_mul_f32 v[112:113], v[112:113], v[130:131] op_sel:[0,1] op_sel_hi:[1,1]
	v_pk_mul_f32 v[114:115], v[114:115], v[130:131] op_sel:[0,1] op_sel_hi:[1,1]
	v_pk_fma_f32 v[112:113], v[200:201], v[230:231], v[112:113] op_sel:[0,0,0] op_sel_hi:[1,0,1]
	v_pk_fma_f32 v[114:115], v[202:203], v[230:231], v[114:115] op_sel:[0,0,0] op_sel_hi:[1,0,1]
	v_pk_mul_f32 v[116:117], v[116:117], v[130:131] op_sel:[0,1] op_sel_hi:[1,1]
	v_pk_mul_f32 v[118:119], v[118:119], v[130:131] op_sel:[0,1] op_sel_hi:[1,1]
	v_pk_fma_f32 v[116:117], v[204:205], v[230:231], v[116:117] op_sel:[0,0,0] op_sel_hi:[1,0,1]
	v_pk_fma_f32 v[118:119], v[206:207], v[230:231], v[118:119] op_sel:[0,0,0] op_sel_hi:[1,0,1]
	v_pk_mul_f32 v[244:245], v[216:217], v[112:113]
	v_pk_fma_f32 v[244:245], v[218:219], v[114:115], v[244:245]
	v_pk_fma_f32 v[244:245], v[220:221], v[116:117], v[244:245]
	v_pk_fma_f32 v[244:245], v[222:223], v[118:119], v[244:245]
	v_add_f32_e32 v238, v244, v245
	v_pk_mul_f32 v[120:121], v[120:121], v[130:131] op_sel:[0,1] op_sel_hi:[1,1]
	v_pk_mul_f32 v[122:123], v[122:123], v[130:131] op_sel:[0,1] op_sel_hi:[1,1]
	v_pk_fma_f32 v[120:121], v[200:201], v[230:231], v[120:121] op_sel:[0,1,0] op_sel_hi:[1,1,1]
	v_pk_fma_f32 v[122:123], v[202:203], v[230:231], v[122:123] op_sel:[0,1,0] op_sel_hi:[1,1,1]
	v_pk_mul_f32 v[124:125], v[124:125], v[130:131] op_sel:[0,1] op_sel_hi:[1,1]
	v_pk_mul_f32 v[126:127], v[126:127], v[130:131] op_sel:[0,1] op_sel_hi:[1,1]
	v_pk_fma_f32 v[124:125], v[204:205], v[230:231], v[124:125] op_sel:[0,1,0] op_sel_hi:[1,1,1]
	v_pk_fma_f32 v[126:127], v[206:207], v[230:231], v[126:127] op_sel:[0,1,0] op_sel_hi:[1,1,1]
	v_pk_mul_f32 v[246:247], v[216:217], v[120:121]
	v_pk_fma_f32 v[246:247], v[218:219], v[122:123], v[246:247]
	v_pk_fma_f32 v[246:247], v[220:221], v[124:125], v[246:247]
	v_pk_fma_f32 v[246:247], v[222:223], v[126:127], v[246:247]
	v_add_f32_e32 v239, v246, v247
; __device__ __forceinline__ void ssd_sample_items(LAS unsigned char* lds, int it0, int itstride, int nitems, const bf16_t* XBC, const float* DT, const float* a_log,
;                                                  const float* state_in, bf16_t* MIX, float* s_ssm) {
;     ...
;     for (int it = it0; it < nitems; it += itstride) {
;         const int b = it >> 2, g = it & 3, h = g * 8 + w;
;         u32x2 Bp[4], Cp[4]; float dtv[4];
; #pragma unroll
;         for (int t = 0; t < 4; ++t) { const size_t row = (size_t)(MP + 4 * b + t);
;             Xs[t * 512 + tid] = bf2f(XBC[row * XBCW + g * 512 + tid]);
;             Bp[t] = *(const u32x2*)(XBC + row * XBCW + 2048 + g * 128 + 4 * nl); Cp[t] = *(const u32x2*)(XBC + row * XBCW + 2560 + g * 128 + 4 * nl);
;             dtv[t] = DT[row * NH + h]; }
;         const float A = -__expf(a_log[h]);
;         LDS_BARRIER();
; #pragma unroll
;         for (int hh = 0; hh < 2; ++hh) {
;             f32x4 st[16];
; #pragma unroll
;             for (int k = 0; k < 16; ++k) st[k] = nx[k];
;             {
;                 const int itn = it + itstride;
;                 if (hh == 0) { const float* sp = state_in + (size_t)(b * NH + h) * HP * NS + 4096;
; #pragma unroll
;                     for (int k = 0; k < 16; ++k) nx[k] = *(const f32x4*)(sp + k * 256 + lane * 4); }
;                 else if (itn < nitems) { const int bn = itn >> 2, gn = itn & 3; const float* sp = state_in + (size_t)(bn * NH + gn * 8 + w) * HP * NS;
; #pragma unroll
;                     for (int k = 0; k < 16; ++k) nx[k] = *(const f32x4*)(sp + k * 256 + lane * 4); }
;             }
;             float yv[4];
; #pragma unroll
;             for (int t = 0; t < 4; ++t) {
;                 const float dt = dtv[t]; const float da = __expf(dt * A);
;                 const f32x4 Bt = (f32x4){bf2f(Bp[t].x & 0xffffu), bf2f(Bp[t].x >> 16), bf2f(Bp[t].y & 0xffffu), bf2f(Bp[t].y >> 16)} * dt;
;                 const f32x4 Ct = (f32x4){bf2f(Cp[t].x & 0xffffu), bf2f(Cp[t].x >> 16), bf2f(Cp[t].y & 0xffffu), bf2f(Cp[t].y >> 16)};
;                 float part[8];
;                 { const bool up8 = (nl & 8) != 0;
; #pragma unroll
;                   for (int i = 0; i < 8; ++i) {
;                     const float x0 = Xs[t * 512 + w * 64 + 32 * hh + 2 * i + half], x1 = Xs[t * 512 + w * 64 + 32 * hh + 2 * (i + 8) + half];
	v_add_f32_dpp v232, v232, v232 row_mirror row_mask:0xf bank_mask:0x3
	v_add_f32_dpp v232, v236, v236 row_mirror row_mask:0xf bank_mask:0xc
	v_add_f32_dpp v233, v233, v233 row_mirror row_mask:0xf bank_mask:0x3
	v_add_f32_dpp v233, v237, v237 row_mirror row_mask:0xf bank_mask:0xc
	v_add_f32_dpp v234, v234, v234 row_mirror row_mask:0xf bank_mask:0x3
	v_add_f32_dpp v234, v238, v238 row_mirror row_mask:0xf bank_mask:0xc
	v_add_f32_dpp v235, v235, v235 row_mirror row_mask:0xf bank_mask:0x3
	v_add_f32_dpp v235, v239, v239 row_mirror row_mask:0xf bank_mask:0xc
	v_add_f32_dpp v232, v232, v232 row_half_mirror row_mask:0xf bank_mask:0x5
	v_add_f32_dpp v232, v234, v234 row_half_mirror row_mask:0xf bank_mask:0xa
	v_add_f32_dpp v233, v233, v233 row_half_mirror row_mask:0xf bank_mask:0x5
	v_add_f32_dpp v233, v235, v235 row_half_mirror row_mask:0xf bank_mask:0xa
	v_add_f32_dpp v248, v232, v232 quad_perm:[2,3,0,1] row_mask:0xf bank_mask:0xf
	s_nop 0
	v_add_f32_dpp v249, v233, v233 quad_perm:[2,3,0,1] row_mask:0xf bank_mask:0xf
	v_cndmask_b32_e64 v232, v248, v249, s[68:69]
	s_nop 1
	v_add_f32_dpp v233, v232, v232 quad_perm:[1,0,3,2] row_mask:0xf bank_mask:0xf
	v_cvt_pk_bf16_f32 v214, v233, v233
	s_mov_b64 exec, s[38:39]
	global_store_short v213, v214, s[10:11] offset:64
	s_mov_b64 exec, -1
	s_mov_b32 s12, s56
	s_mov_b32 s13, s57
	s_add_u32 s47, s47, s33
	s_cmpk_lt_u32 s47, 512
	s_cbranch_scc0 .Lssds_last
	s_lshr_b32 s20, s47, 2
	s_and_b32 s21, s47, 3
	s_lshl_b32 s22, s21, 3
	s_add_u32 s22, s22, s46
	s_lshl_b32 s23, s20, 5
	s_add_u32 s23, s23, s22
	s_lshr_b32 s51, s23, 17
	s_lshl_b32 s50, s23, 15
	s_add_u32 s52, s18, s50
	s_addc_u32 s53, s19, s51
	s_add_u32 s50, s14, s50
	s_addc_u32 s51, s15, s51
	s_add_u32 s54, s50, 0x4000
	s_addc_u32 s55, s51, 0
	s_add_u32 s56, s52, 0x4000
	s_addc_u32 s57, s53, 0
	s_lshl_b32 s20, s20, 2
	s_add_u32 s20, s20, 0x2000
	s_lshl_b32 s23, s22, 7
	s_mul_hi_u32 s59, s20, 0x1800
	s_mul_i32 s58, s20, 0x1800
	s_add_u32 s58, s58, s40
	s_addc_u32 s59, s59, s41
	s_add_u32 s58, s58, s23
	s_addc_u32 s59, s59, 0
	s_add_u32 s60, s58, 0x1800
	s_addc_u32 s61, s59, 0
	s_add_u32 s62, s60, 0x1800
	s_addc_u32 s63, s61, 0
	s_add_u32 s64, s62, 0x1800
	s_addc_u32 s65, s63, 0
	s_lshr_b32 s5, s20, 19
	s_lshl_b32 s4, s20, 13
	s_add_u32 s4, s4, s44
	s_addc_u32 s5, s5, s45
	s_add_u32 s4, s4, s23
	s_addc_u32 s5, s5, 0
	s_add_u32 s6, s4, 0x2000
	s_addc_u32 s7, s5, 0
	s_add_u32 s8, s6, 0x2000
	s_addc_u32 s9, s7, 0
	s_add_u32 s10, s8, 0x2000
	s_addc_u32 s11, s9, 0
	s_lshl_b32 s23, s22, 2
	s_lshr_b32 s21, s20, 25
	s_lshl_b32 s20, s20, 7
	s_add_u32 s20, s20, s42
	s_addc_u32 s21, s21, s43
	s_add_u32 s20, s20, s23
	s_addc_u32 s21, s21, 0
	s_load_dword s28, s[20:21], 0x0
	s_load_dword s29, s[20:21], 0x80
	s_load_dword s30, s[20:21], 0x100
	s_load_dword s31, s[20:21], 0x180
	s_add_u32 s20, s16, s23
	s_addc_u32 s21, s17, 0
	s_load_dword s36, s[20:21], 0x0
	s_and_b32 s20, s47, 3
	s_lshl_b32 s20, s20, 8
	s_lshl_b32 s21, s22, 7
	s_sub_u32 s20, s20, s21
	s_add_u32 s20, s20, 0x1000
	s_add_u32 s22, s58, s20
	s_addc_u32 s23, s59, 0
	global_load_dwordx2 v[136:137], v134, s[22:23]
	global_load_dwordx2 v[138:139], v134, s[22:23] offset:128
	global_load_dwordx2 v[152:153], v134, s[22:23] offset:1024
	global_load_dwordx2 v[154:155], v134, s[22:23] offset:1152
	s_add_u32 s22, s60, s20
	s_addc_u32 s23, s61, 0
	global_load_dwordx2 v[140:141], v134, s[22:23]
	global_load_dwordx2 v[142:143], v134, s[22:23] offset:128
	global_load_dwordx2 v[156:157], v134, s[22:23] offset:1024
	global_load_dwordx2 v[158:159], v134, s[22:23] offset:1152
	s_add_u32 s22, s62, s20
	s_addc_u32 s23, s63, 0
	global_load_dwordx2 v[144:145], v134, s[22:23]
	global_load_dwordx2 v[146:147], v134, s[22:23] offset:128
	global_load_dwordx2 v[160:161], v134, s[22:23] offset:1024
	global_load_dwordx2 v[162:163], v134, s[22:23] offset:1152
	s_add_u32 s22, s64, s20
	s_addc_u32 s23, s65, 0
	global_load_dwordx2 v[148:149], v134, s[22:23]
	global_load_dwordx2 v[150:151], v134, s[22:23] offset:128
	global_load_dwordx2 v[164:165], v134, s[22:23] offset:1024
	global_load_dwordx2 v[166:167], v134, s[22:23] offset:1152
	global_load_dwordx4 v[168:171], v133, s[58:59] offset:0
	global_load_dwordx4 v[184:187], v133, s[58:59] offset:64
	global_load_dwordx4 v[172:175], v133, s[60:61] offset:0
	global_load_dwordx4 v[188:191], v133, s[60:61] offset:64
	global_load_dwordx4 v[176:179], v133, s[62:63] offset:0
	global_load_dwordx4 v[192:195], v133, s[62:63] offset:64
	global_load_dwordx4 v[180:183], v133, s[64:65] offset:0
	global_load_dwordx4 v[196:199], v133, s[64:65] offset:64
	global_store_dwordx4 v132, v[64:67], s[12:13] offset:0
	global_store_dwordx4 v132, v[68:71], s[12:13] offset:256
	global_store_dwordx4 v132, v[72:75], s[12:13] offset:512
	global_store_dwordx4 v132, v[76:79], s[12:13] offset:768
	global_store_dwordx4 v132, v[80:83], s[12:13] offset:1024
	global_store_dwordx4 v132, v[84:87], s[12:13] offset:1280
	global_store_dwordx4 v132, v[88:91], s[12:13] offset:1536
	global_store_dwordx4 v132, v[92:95], s[12:13] offset:1792
	global_store_dwordx4 v132, v[96:99], s[12:13] offset:2048
	global_store_dwordx4 v132, v[100:103], s[12:13] offset:2304
	global_store_dwordx4 v132, v[104:107], s[12:13] offset:2560
	global_store_dwordx4 v132, v[108:111], s[12:13] offset:2816
	global_store_dwordx4 v132, v[112:115], s[12:13] offset:3072
	global_store_dwordx4 v132, v[116:119], s[12:13] offset:3328
	global_store_dwordx4 v132, v[120:123], s[12:13] offset:3584
	global_store_dwordx4 v132, v[124:127], s[12:13] offset:3840
	s_branch .Lssds_unit
; __device__ __forceinline__ float bf2f(unsigned h) { return __uint_as_float(h << 16); }
; __device__ __forceinline__ void ssd_sample_items(LAS unsigned char* lds, int it0, int itstride, int nitems, const bf16_t* XBC, const float* DT, const float* a_log,
;                                                  const float* state_in, bf16_t* MIX, float* s_ssm) {
;     ...
;             float* op = s_ssm + (size_t)(b * NH + h) * HP * NS + hh * 4096;
; #pragma unroll
;             for (int k = 0; k < 16; ++k) *(f32x4*)(op + k * 256 + lane * 4) = st[k];
; __device__ __forceinline__ void mix_finalize_conformer(size_t row, bf16_t* MIX, const bf16_t* CONVOUT, const float* ln_w, const float* ln_b, int lane) {
;     bf16_t* mp = MIX + row * DMIX;
;     {
;         const bf16_t* cp = CONVOUT + row * DM;
;         f32x4 v[8], ww[8], bb[8];
; #pragma unroll
;         for (int k = 0; k < 8; ++k) { const u32x2 cv = *(const u32x2*)(cp + (k * 64 + lane) * 4); v[k] = (f32x4){bf2f(cv.x & 0xffffu), bf2f(cv.x >> 16), bf2f(cv.y & 0xffffu), bf2f(cv.y >> 16)};
;             ww[k] = *(const f32x4*)(ln_w + (k * 64 + lane) * 4); bb[k] = *(const f32x4*)(ln_b + (k * 64 + lane) * 4); }
;         float s = 0.f;
; #pragma unroll
;         for (int k = 0; k < 8; ++k) s += (v[k].x + v[k].y) + (v[k].z + v[k].w);
;         const float mean = wave_sum(s) * (1.f / DM); float q = 0.f;
; #pragma unroll
;         for (int k = 0; k < 8; ++k) { v[k] = v[k] - mean; q += (v[k].x * v[k].x + v[k].y * v[k].y) + (v[k].z * v[k].z + v[k].w * v[k].w); }
;         const float rstd = rsqrtf(wave_sum(q) * (1.f / DM) + EPS);
.Lssds_last:
	global_store_dwordx4 v132, v[64:67], s[12:13] offset:0
	global_store_dwordx4 v132, v[68:71], s[12:13] offset:256
	global_store_dwordx4 v132, v[72:75], s[12:13] offset:512
	global_store_dwordx4 v132, v[76:79], s[12:13] offset:768
	global_store_dwordx4 v132, v[80:83], s[12:13] offset:1024
	global_store_dwordx4 v132, v[84:87], s[12:13] offset:1280
	global_store_dwordx4 v132, v[88:91], s[12:13] offset:1536
	global_store_dwordx4 v132, v[92:95], s[12:13] offset:1792
	global_store_dwordx4 v132, v[96:99], s[12:13] offset:2048
	global_store_dwordx4 v132, v[100:103], s[12:13] offset:2304
	global_store_dwordx4 v132, v[104:107], s[12:13] offset:2560
	global_store_dwordx4 v132, v[108:111], s[12:13] offset:2816
	global_store_dwordx4 v132, v[112:115], s[12:13] offset:3072
	global_store_dwordx4 v132, v[116:119], s[12:13] offset:3328
	global_store_dwordx4 v132, v[120:123], s[12:13] offset:3584
	global_store_dwordx4 v132, v[124:127], s[12:13] offset:3840
.Lssds_end:
.LBB0_435:
	s_cmpk_gt_u32 s90, 0xff
	s_cbranch_scc1 .LBB0_439
	v_readlane_b32 s4, v253, 20
	s_sub_i32 s4, s2, s4
	s_ashr_i32 s3, s3, 6
	s_lshl_b32 s4, s4, 3
	s_add_i32 s6, s4, s3
	s_cmpk_gt_i32 s6, 0x21ff
	s_cbranch_scc1 .LBB0_439
	s_load_dwordx4 s[8:11], s[0:1], 0x80
	s_waitcnt vmcnt(0)
	v_lshlrev_b32_e32 v0, 4, v135
	v_mov_b32_e32 v65, 0
	v_and_b32_e32 v64, 0x3f0, v0
	v_or_b32_e32 v0, 0x1000, v64
	v_mov_b32_e32 v1, v65
	s_waitcnt lgkmcnt(0)
	v_lshl_add_u64 v[70:71], s[8:9], 0, v[0:1]
	v_lshl_add_u64 v[72:73], s[10:11], 0, v[0:1]
	v_or_b32_e32 v0, 0x1400, v64
	v_lshl_add_u64 v[74:75], s[8:9], 0, v[0:1]
	v_lshl_add_u64 v[76:77], s[10:11], 0, v[0:1]
	v_or_b32_e32 v0, 0x1800, v64
	v_lshl_add_u64 v[78:79], s[8:9], 0, v[0:1]
	v_lshl_add_u64 v[80:81], s[10:11], 0, v[0:1]
	v_mbcnt_lo_u32_b32 v0, -1, 0
	v_mbcnt_hi_u32_b32 v0, -1, v0
	v_and_b32_e32 v1, 64, v0
	v_add_u32_e32 v1, 64, v1
	v_xor_b32_e32 v2, 1, v0
	v_cmp_lt_i32_e32 vcc, v2, v1
	v_readlane_b32 s0, v253, 20
	s_sub_i32 s0, s94, s0
	v_cndmask_b32_e32 v2, v0, v2, vcc
	v_lshlrev_b32_e32 v90, 2, v2
	v_xor_b32_e32 v2, 2, v0
	v_cmp_lt_i32_e32 vcc, v2, v1
	s_ashr_i32 s7, s6, 31
	v_readlane_b32 s12, v253, 16
	v_cndmask_b32_e32 v2, v0, v2, vcc
	v_lshlrev_b32_e32 v91, 2, v2
	v_xor_b32_e32 v2, 4, v0
	v_cmp_lt_i32_e32 vcc, v2, v1
	v_lshl_add_u64 v[66:67], s[8:9], 0, v[64:65]
	v_lshl_add_u64 v[68:69], s[10:11], 0, v[64:65]
	v_cndmask_b32_e32 v2, v0, v2, vcc
	v_lshlrev_b32_e32 v92, 2, v2
	v_xor_b32_e32 v2, 8, v0
	v_cmp_lt_i32_e32 vcc, v2, v1
	v_or_b32_e32 v64, 0x1c00, v64
	s_lshl_b32 s0, s0, 3
	v_cndmask_b32_e32 v2, v0, v2, vcc
	v_lshlrev_b32_e32 v93, 2, v2
	v_xor_b32_e32 v2, 16, v0
	v_cmp_lt_i32_e32 vcc, v2, v1
	s_lshl_b64 s[4:5], s[6:7], 12
	v_readlane_b32 s14, v253, 18
	v_cndmask_b32_e32 v2, v0, v2, vcc
	v_lshl_add_u64 v[82:83], s[8:9], 0, v[64:65]
	v_lshlrev_b32_e32 v94, 2, v2
	v_xor_b32_e32 v2, 32, v0
	v_readlane_b32 s15, v253, 19
	s_add_u32 s8, s14, s4
	v_cmp_lt_i32_e32 vcc, v2, v1
	s_addc_u32 s9, s15, s5
	s_ashr_i32 s1, s0, 31
	v_lshl_add_u64 v[84:85], s[10:11], 0, v[64:65]
	v_cndmask_b32_e32 v0, v0, v2, vcc
	s_lshl_b64 s[10:11], s[0:1], 12
	s_lshl_b64 s[4:5], s[6:7], 13
	v_lshlrev_b32_e32 v95, 2, v0
	v_and_b32_e32 v0, 63, v135
	v_readlane_b32 s13, v253, 17
	s_add_u32 s12, s14, s4
	v_lshlrev_b32_e32 v64, 3, v0
	s_addc_u32 s13, s15, s5
	s_lshl_b64 s[14:15], s[0:1], 13
	v_mov_b32_e32 v96, 0x3727c5ac
	s_mov_b32 s1, 0x800000
	s_mov_b32 s3, 0x1acd1000

; #define LAS __attribute__((address_space(3)))
; __device__ __forceinline__ unsigned pk2(float lo, float hi) { unsigned r; asm("v_cvt_pk_bf16_f32 %0, %1, %2" : "=v"(r) : "v"(lo), "v"(hi)); return r; }
; __device__ __forceinline__ void p0_transpose_item(const float* W, int K, int N, bf16_t* WT, int k0, int n0, int drow0, LAS float* scr, int lane, const float* kscale = nullptr) {
;     const float ks = kscale ? kscale[k0 + lane] : 1.f;
; #pragma unroll 8
;     for (int i = 0; i < 32; ++i) { const int kk = 2 * i + (lane >> 5); scr[kk * 33 + (lane & 31)] = W[(size_t)(k0 + kk) * N + n0 + (lane & 31)] * __shfl(ks, kk); }
;     asm volatile("s_waitcnt lgkmcnt(0)" ::: "memory");
;     const int c = lane & 7;
; #pragma unroll
;     for (int j = 0; j < 4; ++j) { const int n = (lane >> 3) + 8 * j; const LAS float* s = scr + (8 * c) * 33 + n;
;         u32x4 o; o.x = pk2(s[0 * 33], s[1 * 33]); o.y = pk2(s[2 * 33], s[3 * 33]); o.z = pk2(s[4 * 33], s[5 * 33]); o.w = pk2(s[6 * 33], s[7 * 33]);
;         *(u32x4*)(WT + (size_t)(drow0 + n) * K + k0 + 8 * c) = o; }
; __global__ void __launch_bounds__(512, 2) mk_fwd(Args args) {
;     ...
;         constexpr int I_IN = (DM / 64) * (9248 / 32), I_OUT = (DMIX / 64) * (DM / 32), I_UP = (DM / 64) * (FF2 / 32), I_DN = (FF / 64) * (DM / 32);
;         constexpr int n_items0 = I_IN + I_OUT + I_UP + I_DN;
;         for (int it = gw; it < n_items0; it += NGW) {
;             int r = it;
;             if (r < I_IN) { const int nblk = 9248 / 32, kb = r / nblk, nb = r % nblk; p0_transpose_item(w_in, DM, 9248, WinT, 64 * kb, 32 * nb, win_dest_row(32 * nb), scr, lane); continue; } r -= I_IN;
;             if (r < I_OUT) { const int nblk = DM / 32, kb = r / nblk, nb = r % nblk; p0_transpose_item(w_out, DMIX, DM, WoutT, 64 * kb, 32 * nb, 32 * nb, scr, lane); continue; } r -= I_OUT;
;             if (r < I_UP) { const int nblk = FF2 / 32, kb = r / nblk, nb = r % nblk; p0_transpose_item(w_up, DM, FF2, WupT, 64 * kb, 32 * nb, 32 * nb, scr, lane, norm_ffn_w); continue; } r -= I_UP;
;             { const int nblk = DM / 32, kb = r / nblk, nb = r % nblk; p0_transpose_item(w_down, FF, DM, WdnT, 64 * kb, 32 * nb, 32 * nb, scr, lane); }
;         }
.LBB0_491:
	v_writelane_b32 v254, s3, 0
	v_writelane_b32 v254, s4, 1
	v_writelane_b32 v254, s8, 2
	v_writelane_b32 v254, s9, 3
	v_writelane_b32 v254, s10, 4
	v_writelane_b32 v254, s11, 5
	v_writelane_b32 v254, s12, 6
	v_writelane_b32 v254, s13, 7
	v_writelane_b32 v254, s14, 8
	v_writelane_b32 v254, s15, 9
	v_writelane_b32 v254, s16, 10
	v_writelane_b32 v254, s17, 11
	v_writelane_b32 v254, s18, 12
	v_writelane_b32 v254, s19, 13
	v_writelane_b32 v254, s20, 14
	v_writelane_b32 v254, s21, 15
	v_writelane_b32 v254, s22, 16
	v_writelane_b32 v254, s23, 17
	v_writelane_b32 v254, s24, 18
	v_writelane_b32 v254, s25, 19
	v_writelane_b32 v254, s26, 20
	v_writelane_b32 v254, s27, 21
	v_writelane_b32 v254, s28, 22
	v_writelane_b32 v254, s29, 23
	v_writelane_b32 v254, s30, 24
	v_writelane_b32 v254, s31, 25
	v_writelane_b32 v254, s32, 26
	v_writelane_b32 v254, s33, 27
	v_writelane_b32 v254, s34, 28
	v_writelane_b32 v254, s35, 29
	v_writelane_b32 v254, s36, 30
	v_writelane_b32 v254, s37, 31
	v_writelane_b32 v254, s38, 32
	v_writelane_b32 v254, s39, 33
	v_writelane_b32 v254, s40, 34
	v_writelane_b32 v254, s41, 35
	v_writelane_b32 v254, s42, 36
	v_writelane_b32 v254, s43, 37
	v_writelane_b32 v254, s44, 38
	v_writelane_b32 v254, s45, 39
	v_writelane_b32 v254, s46, 40
	v_writelane_b32 v254, s47, 41
	v_writelane_b32 v254, s48, 42
	v_writelane_b32 v254, s49, 43
	v_writelane_b32 v254, s50, 44
	v_writelane_b32 v254, s51, 45
	v_writelane_b32 v254, s52, 46
	v_writelane_b32 v254, s53, 47
	v_writelane_b32 v254, s54, 48
	v_writelane_b32 v254, s55, 49
	s_cmpk_lt_u32 s2, 128
	s_cbranch_scc1 .Ltup3_skip
	s_mov_b64 s[8:9], s[96:97]
	v_and_b32_e32 v3, 63, v212
	v_readfirstlane_b32 s4, v212
	s_sub_u32 s3, s2, 128
	s_lshl_b32 s3, s3, 3
	s_lshr_b32 s4, s4, 6
	s_add_u32 s3, s3, s4
	s_add_u32 s11, s3, 10288
	s_sub_u32 s10, s94, 128
	s_lshl_b32 s10, s10, 3
	s_cmpk_lt_u32 s11, 17456
	s_cbranch_scc0 .Ltup3_skip
	s_load_dwordx2 s[12:13], s[8:9], 0x38
	s_load_dwordx2 s[14:15], s[8:9], 0x90
	s_load_dwordx2 s[16:17], s[8:9], 0xa0
	s_load_dwordx2 s[18:19], s[8:9], 0xb8
	s_load_dwordx2 s[20:21], s[8:9], 0x98
	s_load_dwordx2 s[22:23], s[8:9], 0xd0
	v_lshrrev_b32_e32 v4, 3, v3
	v_and_b32_e32 v7, 7, v3
	v_lshlrev_b32_e32 v5, 4, v7
	v_lshlrev_b32_e32 v6, 5, v7
	s_lshl_b32 s24, s4, 14
	v_lshl_add_u32 v16, v4, 7, s24
	v_xor_b32_e32 v8, 0, v7
	v_lshl_add_u32 v8, v8, 4, v16
	v_xor_b32_e32 v9, 1, v7
	v_lshl_add_u32 v9, v9, 4, v16
	v_xor_b32_e32 v10, 2, v7
	v_lshl_add_u32 v10, v10, 4, v16
	v_xor_b32_e32 v11, 3, v7
	v_lshl_add_u32 v11, v11, 4, v16
	v_xor_b32_e32 v12, 4, v7
	v_lshl_add_u32 v12, v12, 4, v16
	v_xor_b32_e32 v13, 5, v7
	v_lshl_add_u32 v13, v13, 4, v16
	v_xor_b32_e32 v14, 6, v7
	v_lshl_add_u32 v14, v14, 4, v16
	v_xor_b32_e32 v15, 7, v7
	v_lshl_add_u32 v15, v15, 4, v16
	v_lshlrev_b32_e32 v20, 2, v7
	v_lshl_add_u32 v21, v7, 10, s24
	v_add_u32_e32 v16, 0, v4
	v_xor_b32_e32 v16, v16, v20
	v_lshl_add_u32 v16, v16, 2, v21
	v_add_u32_e32 v17, 8, v4
	v_xor_b32_e32 v17, v17, v20
	v_lshl_add_u32 v17, v17, 2, v21
	v_add_u32_e32 v18, 16, v4
	v_xor_b32_e32 v18, v18, v20
	v_lshl_add_u32 v18, v18, 2, v21
	v_add_u32_e32 v19, 24, v4
	v_xor_b32_e32 v19, v19, v20
	v_lshl_add_u32 v19, v19, 2, v21
	s_waitcnt lgkmcnt(0)
	s_cmpk_lt_u32 s11, 9248
	s_cbranch_scc0 .Ltup3_pro_notin
	s_mul_hi_u32 s40, s11, 14861479
	s_mul_i32 s42, s40, 289
	s_sub_u32 s41, s11, s42
	s_mul_i32 s42, s40, 2367488
	s_lshl_b32 s43, s41, 7
	s_add_u32 s42, s42, s43
	s_add_u32 s26, s12, s42
	s_addc_u32 s27, s13, 0
	s_mov_b32 s28, 36992
	s_lshl_b32 s45, s41, 5
	s_mov_b32 s46, s45
	s_cmpk_lt_u32 s45, 5120
	s_cbranch_scc1 .Ltup3_pro_drow_done
	s_movk_i32 s46, 9216
	s_cmpk_lt_u32 s45, 5152
	s_cbranch_scc1 .Ltup3_pro_drow_done
	s_sub_u32 s47, s45, 5152
	s_movk_i32 s43, 5120
	s_cmpk_lt_u32 s45, 7200
	s_cbranch_scc1 .Ltup3_pro_drow_cf
	s_sub_u32 s47, s45, 7200
	s_movk_i32 s43, 5248
